# GEMM K-loop LDS-DMA loads: 60 of the per-load 64-bit VALU address adds replaced by SGPR-base + 32-bit VGPR-offset addressing (s_nop kept after m0 writes)
# speedup vs baseline: 1.0002x; 1.0002x over previous
; DI bf16_t* slot(const Params& p, int i) { return (bf16_t*)(p.ws + OFF_SLOT + (size_t)i * SLOT); }
; #define STAGE(bufoff, gbase) STAGE_(bufoff, gbase, voffA)
; #define STAGEB(bufoff, gbase) STAGE_(bufoff, gbase, voffB)
; #define WAIT_V(n) asm volatile("s_waitcnt vmcnt(" #n ")" ::: "memory")
; #define BAR __builtin_amdgcn_s_barrier()
; #define WAIT_V(n) asm volatile("s_waitcnt vmcnt(" #n ")" ::: "memory")
; #define BAR do { __builtin_amdgcn_sched_barrier(0); __builtin_amdgcn_s_barrier(); asm volatile("" ::: "memory"); __builtin_amdgcn_sched_barrier(0); } while (0)
; template <bool SP2, bool ALIGN_EPI, bool DUAL, class Epi> DI void gemm_phase2(const bf16_t* A, const bf16_t* Bt, const bf16_t* A2, const bf16_t* Bt2, int M, int N, int K, const Epi& E, lds_t* lds) {
;     ...
;     STAGEB(SB(0, 0), cB); STAGEB(SB(0, 1), cB + bstep); STAGE(SA(0, 0), cA); STAGE(SA(0, 1), cA + hstep);
;     if (wr == 1) BAR;
;     WAIT_V(2); BAR;
;     STAGEB(SB(1, 0), cB + kstep); STAGE(SA(1, 0), cA + kstep); STAGEB(SB(1, 1), cB + bstep + kstep);
;     WAIT_V(6); BAR;
;   DI void operator()(g8::Acc& acc, int pm, int pn, int wr, int wc, int fr, int fq) const {
;     ...
;     const int seg = pn >> 2;
;     const float* rope = (const float*)(p.ws + OFF_ROPE);
;     bf16_t* dst; unsigned ld; int cofs;
;     if (seg < 5) { dst = slot(p, seg + 1); ld = 1024; cofs = seg * 1024; } else { dst = (bf16_t*)p.out; ld = 2048; cofs = 5 * 1024; }
;     const float qs = (seg == 0) ? 0.125f * LOG2E : 1.0f;
;     const float sgn = (fq == 0) ? -1.0f : 1.0f; const bool use = fq < 2;
;     const unsigned col0 = (unsigned)(pn * BM + wc * 64 - cofs);
.LBB0_151:
	s_mov_b64 s[58:59], 0x80
	s_and_b32 s6, s0, 3
	s_add_i32 m0, s3, 0x18000
	v_lshl_add_u64 v[6:7], v[6:7], 0, s[58:59]
	s_lshl_b32 s93, s1, 6
	s_lshl_b32 s5, s1, 13
	s_lshl_b32 s7, s6, 12
	s_waitcnt vmcnt(2)
	s_barrier
	global_load_lds_dwordx4 v[6:7], off
	v_lshl_add_u64 v[4:5], v[4:5], 0, s[58:59]
	s_add_i32 m0, s3, 0x1a000
	s_add_i32 s52, s3, 0x8000
	s_add_i32 s53, s3, 0xa000
	global_load_lds_dwordx4 v[4:5], off
	v_lshl_add_u64 v[0:1], v[0:1], 0, s[58:59]
	s_mov_b32 m0, s52
	s_add_u32 s0, s88, 0x10080
	global_load_lds_dwordx4 v[0:1], off
	v_lshl_add_u64 v[0:1], v[2:3], 0, s[58:59]
	s_mov_b32 m0, s53
	s_addc_u32 s1, s89, 0
	global_load_lds_dwordx4 v[0:1], off
	s_add_i32 m0, s3, 0x1c000
	s_nop 0
	global_load_lds_dwordx4 v130, s[0:1]
	v_lshl_add_u64 v[0:1], s[0:1], 0, v[134:135]
	s_add_i32 m0, s3, 0x1e000
	v_and_b32_e32 v155, 15, v8
	global_load_lds_dwordx4 v[0:1], off
	v_bfe_u32 v0, v8, 4, 2
	v_lshlrev_b32_e32 v1, 4, v0
	v_lshlrev_b32_e32 v2, 2, v8
	v_lshl_or_b32 v1, v155, 6, v1
	v_and_b32_e32 v2, 32, v2
	v_lshlrev_b32_e32 v156, 3, v0
	v_bitop3_b32 v3, v1, s5, v2 bitop3:0xde
	s_cmpk_lt_u32 s4, 0x100
	v_cmp_eq_u32_e32 vcc, 0, v0
	v_cmp_gt_u32_e64 s[4:5], 2, v0
	v_lshlrev_b32_e32 v0, 14, v9
	v_and_b32_e32 v0, 0xffff8000, v0
	v_bitop3_b32 v157, v1, s7, v2 bitop3:0xde
	v_lshl_add_u32 v0, v10, 11, v0
	v_and_b32_e32 v1, 1, v9
	v_lshl_or_b32 v0, v1, 6, v0
	v_lshl_add_u32 v140, v11, 1, v0
	v_lshlrev_b32_e32 v0, 14, v12
	v_and_b32_e32 v0, 0xffff8000, v0
	s_waitcnt vmcnt(6)
	v_lshl_add_u32 v0, v13, 11, v0
	v_and_b32_e32 v1, 1, v12
	s_cselect_b64 s[60:61], -1, 0
	v_cndmask_b32_e64 v136, 1.0, -1.0, vcc
	s_lshl_b32 s77, s6, 6
	v_cmp_lt_u32_e64 s[6:7], 7, v155
	v_lshl_or_b32 v0, v1, 6, v0
	s_add_i32 s12, 0, 0x10000
	s_add_i32 s13, 0, 0x14000
	v_and_b32_e32 v158, 7, v8
	v_cndmask_b32_e64 v159, 0, 32, s[6:7]
	v_cndmask_b32_e64 v160, 32, 0, s[6:7]
	v_mov_b32_e32 v137, v136
	v_mov_b32_e32 v138, v136
	v_mov_b32_e32 v139, v136
	v_mov_b32_e32 v141, v131
	v_lshl_add_u32 v142, v14, 1, v0
	v_mov_b32_e32 v143, v131
	v_add_u32_e32 v161, s12, v157
	v_add_u32_e32 v162, s13, v157
	v_add_u32_e32 v163, 0, v3
	v_mov_b32_e32 v164, 0x3e38aa3b
	v_mbcnt_hi_u32_b32 v165, -1, v154
	s_mov_b32 s62, 0
	s_mov_b32 s76, 0
	s_barrier
	s_branch .LBB0_154

; #define STAGE(bufoff, gbase) STAGE_(bufoff, gbase, voffA)
; #define STAGEB(bufoff, gbase) STAGE_(bufoff, gbase, voffB)
; #define LDA(dst, b, h) do { _Pragma("unroll") for (int m = 0; m < 4; ++m) _Pragma("unroll") for (int k = 0; k < 2; ++k) dst[m][k] = *LDSP(const bf16x8, lds + SA(b, h) + aoff + m * 2048 + k * 1024); } while (0)
; #define LDB(dst, b, h) do { _Pragma("unroll") for (int n = 0; n < 2; ++n) _Pragma("unroll") for (int k = 0; k < 2; ++k) dst[n][k] = *LDSP(const bf16x8, lds + SB(b, h) + boff + n * 2048 + k * 1024); } while (0)
; #define MMA(ai, bj, AT, BT) do { __builtin_amdgcn_s_setprio(1); \
;     _Pragma("unroll") for (int m = 0; m < 4; ++m) _Pragma("unroll") for (int n = 0; n < 2; ++n) _Pragma("unroll") for (int k = 0; k < 2; ++k) \
;       acc[ai][bj][m][n] = __builtin_amdgcn_mfma_f32_16x16x32_bf16(BT[n][k], AT[m][k], acc[ai][bj][m][n], 0, 0, 0); \
;     __builtin_amdgcn_s_setprio(0); } while (0)
; #define WAIT_V(n) asm volatile("s_waitcnt vmcnt(" #n ")" ::: "memory")
; #define WAIT_L(n) asm volatile("s_waitcnt lgkmcnt(" #n ")" ::: "memory")
; #define BAR __builtin_amdgcn_s_barrier()
; #define SCHED __builtin_amdgcn_sched_barrier(0)
; #define WAIT_V(n) asm volatile("s_waitcnt vmcnt(" #n ")" ::: "memory")
; #define BAR do { __builtin_amdgcn_sched_barrier(0); __builtin_amdgcn_s_barrier(); asm volatile("" ::: "memory"); __builtin_amdgcn_sched_barrier(0); } while (0)
; template <bool SP2, bool ALIGN_EPI, bool DUAL, class Epi> DI void gemm_phase2(const bf16_t* A, const bf16_t* Bt, const bf16_t* A2, const bf16_t* Bt2, int M, int N, int K, const Epi& E, lds_t* lds) {
;     ...
;       const char* a1 = cA + (size_t)(t + 1) * kstep;
;       const char* a2 = last ? nA : cA + (size_t)(t + 2) * kstep; const char* b2 = last ? nB : cB + (size_t)(t + 2) * kstep;
;       const char* a3 = a2 + kstep; const char* b3 = b2 + kstep;
;       if constexpr (SP2) {
;         LDB(B0, 0, 0); LDB(B1, 0, 1); SCHED; LDA(At, 0, 0); STAGE(SA(1, 1), a1 + hstep);
;         WAIT_V(8); WAIT_L(0); BAR; MMA(0, 0, At, B0); MMA(0, 1, At, B1); BAR; SCHED;
;         LDA(At, 0, 1); STAGEB(SB(0, 0), b2); STAGEB(SB(0, 1), b2 + bstep); STAGE(SA(0, 0), a2);
;         WAIT_V(8); WAIT_L(0); BAR; MMA(1, 0, At, B0); MMA(1, 1, At, B1); BAR; SCHED;
.LBB0_157:
	ds_read_b128 v[144:147], v161
	ds_read_b128 v[148:151], v161 offset:1024
	ds_read_b128 v[166:169], v161 offset:2048
	ds_read_b128 v[170:173], v161 offset:3072
	ds_read_b128 v[174:177], v162
	ds_read_b128 v[178:181], v162 offset:1024
	ds_read_b128 v[182:185], v162 offset:2048
	ds_read_b128 v[186:189], v162 offset:3072
	s_add_u32 s22, s8, 0xfffc0080
	s_addc_u32 s23, s9, -1
	s_cmp_eq_u32 s21, 12
	s_cselect_b32 s91, s0, s23
	s_cselect_b32 s90, s1, s22
	s_cselect_b32 s89, s11, s20
	s_cselect_b32 s88, s18, s19
	s_add_i32 m0, s3, 0xc000
	ds_read_b128 v[190:193], v163
	ds_read_b128 v[194:197], v163 offset:1024
	ds_read_b128 v[198:201], v163 offset:2048
	ds_read_b128 v[202:205], v163 offset:3072
	ds_read_b128 v[206:209], v163 offset:4096
	ds_read_b128 v[214:217], v163 offset:5120
	ds_read_b128 v[218:221], v163 offset:6144
	ds_read_b128 v[222:225], v163 offset:7168
	global_load_lds_dwordx4 v140, s[8:9]
	s_add_i32 m0, s3, 0xe000
	s_nop 0
	global_load_lds_dwordx4 v142, s[8:9]
	s_waitcnt vmcnt(8)
	s_waitcnt lgkmcnt(0)
	s_barrier
	s_setprio 1
	s_waitcnt lgkmcnt(0)
	v_mfma_f32_16x16x32_bf16 v[124:127], v[144:147], v[190:193], v[124:127]
	v_mfma_f32_16x16x32_bf16 v[120:123], v[166:169], v[190:193], v[120:123]
	v_mfma_f32_16x16x32_bf16 v[108:111], v[144:147], v[198:201], v[108:111]
	v_mfma_f32_16x16x32_bf16 v[104:107], v[166:169], v[198:201], v[104:107]
	v_mfma_f32_16x16x32_bf16 v[92:95], v[144:147], v[206:209], v[92:95]
	v_mfma_f32_16x16x32_bf16 v[88:91], v[166:169], v[206:209], v[88:91]
	v_mfma_f32_16x16x32_bf16 v[76:79], v[144:147], v[218:221], v[76:79]
	v_mfma_f32_16x16x32_bf16 v[72:75], v[166:169], v[218:221], v[72:75]
	v_mfma_f32_16x16x32_bf16 v[124:127], v[148:151], v[194:197], v[124:127]
	v_mfma_f32_16x16x32_bf16 v[120:123], v[170:173], v[194:197], v[120:123]
	v_mfma_f32_16x16x32_bf16 v[108:111], v[148:151], v[202:205], v[108:111]
	v_mfma_f32_16x16x32_bf16 v[104:107], v[170:173], v[202:205], v[104:107]
	v_mfma_f32_16x16x32_bf16 v[92:95], v[148:151], v[214:217], v[92:95]
	v_mfma_f32_16x16x32_bf16 v[88:91], v[170:173], v[214:217], v[88:91]
	v_mfma_f32_16x16x32_bf16 v[76:79], v[148:151], v[222:225], v[76:79]
	v_mfma_f32_16x16x32_bf16 v[72:75], v[170:173], v[222:225], v[72:75]
	s_setprio 0
	s_setprio 1
	v_mfma_f32_16x16x32_bf16 v[116:119], v[174:177], v[190:193], v[116:119]
	v_mfma_f32_16x16x32_bf16 v[112:115], v[182:185], v[190:193], v[112:115]
	v_mfma_f32_16x16x32_bf16 v[100:103], v[174:177], v[198:201], v[100:103]
	v_mfma_f32_16x16x32_bf16 v[96:99], v[182:185], v[198:201], v[96:99]
	v_mfma_f32_16x16x32_bf16 v[84:87], v[174:177], v[206:209], v[84:87]
	v_mfma_f32_16x16x32_bf16 v[80:83], v[182:185], v[206:209], v[80:83]
	v_mfma_f32_16x16x32_bf16 v[68:71], v[174:177], v[218:221], v[68:71]
	v_mfma_f32_16x16x32_bf16 v[64:67], v[182:185], v[218:221], v[64:67]
	v_mfma_f32_16x16x32_bf16 v[116:119], v[178:181], v[194:197], v[116:119]
	v_mfma_f32_16x16x32_bf16 v[112:115], v[186:189], v[194:197], v[112:115]
	v_mfma_f32_16x16x32_bf16 v[100:103], v[178:181], v[202:205], v[100:103]
	v_mfma_f32_16x16x32_bf16 v[96:99], v[186:189], v[202:205], v[96:99]
	v_mfma_f32_16x16x32_bf16 v[84:87], v[178:181], v[214:217], v[84:87]
	v_mfma_f32_16x16x32_bf16 v[80:83], v[186:189], v[214:217], v[80:83]
	v_mfma_f32_16x16x32_bf16 v[68:71], v[178:181], v[222:225], v[68:71]
	v_mfma_f32_16x16x32_bf16 v[64:67], v[186:189], v[222:225], v[64:67]
	s_setprio 0
	s_barrier
	s_add_i32 s22, s12, s2
	v_lshl_add_u64 v[152:153], s[88:89], 0, v[130:131]
	s_mov_b32 m0, s22
	ds_read_b128 v[190:193], v163 offset:16384
	ds_read_b128 v[194:197], v163 offset:17408
	ds_read_b128 v[198:201], v163 offset:18432
	ds_read_b128 v[202:205], v163 offset:19456
	ds_read_b128 v[206:209], v163 offset:20480
	ds_read_b128 v[214:217], v163 offset:21504
	ds_read_b128 v[218:221], v163 offset:22528
	ds_read_b128 v[222:225], v163 offset:23552
	global_load_lds_dwordx4 v[152:153], off
	s_add_i32 m0, s22, 0x2000
	s_add_u32 s22, s88, 0x10000
	v_lshl_add_u64 v[210:211], s[88:89], 0, v[134:135]
	s_addc_u32 s23, s89, 0
	s_add_i32 s33, s13, s2
	global_load_lds_dwordx4 v[210:211], off
	s_mov_b32 m0, s33
	v_lshl_add_u64 v[228:229], s[90:91], 0, v[132:133]
	global_load_lds_dwordx4 v130, s[22:23]
	s_add_i32 m0, s33, 0x2000
	s_nop 0
	global_load_lds_dwordx4 v134, s[22:23]
	v_lshl_add_u64 v[226:227], s[90:91], 0, v[128:129]
	s_mov_b32 m0, s3
	s_nop 0
	global_load_lds_dwordx4 v[226:227], off
	s_mov_b32 m0, s14
	s_nop 0
	global_load_lds_dwordx4 v[228:229], off
	s_waitcnt vmcnt(8)
	s_waitcnt lgkmcnt(0)
	s_barrier
; #define STAGE(bufoff, gbase) STAGE_(bufoff, gbase, voffA)
; #define LDA(dst, b, h) do { _Pragma("unroll") for (int m = 0; m < 4; ++m) _Pragma("unroll") for (int k = 0; k < 2; ++k) dst[m][k] = *LDSP(const bf16x8, lds + SA(b, h) + aoff + m * 2048 + k * 1024); } while (0)
; #define LDB(dst, b, h) do { _Pragma("unroll") for (int n = 0; n < 2; ++n) _Pragma("unroll") for (int k = 0; k < 2; ++k) dst[n][k] = *LDSP(const bf16x8, lds + SB(b, h) + boff + n * 2048 + k * 1024); } while (0)
; #define MMA(ai, bj, AT, BT) do { __builtin_amdgcn_s_setprio(1); \
;     _Pragma("unroll") for (int m = 0; m < 4; ++m) _Pragma("unroll") for (int n = 0; n < 2; ++n) _Pragma("unroll") for (int k = 0; k < 2; ++k) \
;       acc[ai][bj][m][n] = __builtin_amdgcn_mfma_f32_16x16x32_bf16(BT[n][k], AT[m][k], acc[ai][bj][m][n], 0, 0, 0); \
;     __builtin_amdgcn_s_setprio(0); } while (0)
; #define WAIT_V(n) asm volatile("s_waitcnt vmcnt(" #n ")" ::: "memory")
; #define WAIT_L(n) asm volatile("s_waitcnt lgkmcnt(" #n ")" ::: "memory")
; #define BAR __builtin_amdgcn_s_barrier()
; #define SCHED __builtin_amdgcn_sched_barrier(0)
; #define WAIT_V(n) asm volatile("s_waitcnt vmcnt(" #n ")" ::: "memory")
; #define BAR do { __builtin_amdgcn_sched_barrier(0); __builtin_amdgcn_s_barrier(); asm volatile("" ::: "memory"); __builtin_amdgcn_sched_barrier(0); } while (0)
; template <bool SP2, bool ALIGN_EPI, bool DUAL, class Epi> DI void gemm_phase2(const bf16_t* A, const bf16_t* Bt, const bf16_t* A2, const bf16_t* Bt2, int M, int N, int K, const Epi& E, lds_t* lds) {
;     ...
;         WAIT_V(8); WAIT_L(0); BAR; MMA(1, 0, At, B0); MMA(1, 1, At, B1); BAR; SCHED;
;         LDB(B0, 1, 0); LDB(B1, 1, 1); SCHED; LDA(At, 1, 0); STAGE(SA(0, 1), a2 + hstep);
;         WAIT_V(8); WAIT_L(0); BAR; MMA(0, 0, At, B0); MMA(0, 1, At, B1); BAR; SCHED;
	s_setprio 1
	s_waitcnt lgkmcnt(0)
	v_mfma_f32_16x16x32_bf16 v[60:63], v[144:147], v[190:193], v[60:63]
	v_mfma_f32_16x16x32_bf16 v[56:59], v[166:169], v[190:193], v[56:59]
	v_mfma_f32_16x16x32_bf16 v[44:47], v[144:147], v[198:201], v[44:47]
	v_mfma_f32_16x16x32_bf16 v[40:43], v[166:169], v[198:201], v[40:43]
	v_mfma_f32_16x16x32_bf16 v[28:31], v[144:147], v[206:209], v[28:31]
	v_mfma_f32_16x16x32_bf16 v[24:27], v[166:169], v[206:209], v[24:27]
	v_mfma_f32_16x16x32_bf16 v[12:15], v[144:147], v[218:221], v[12:15]
	v_mfma_f32_16x16x32_bf16 v[8:11], v[166:169], v[218:221], v[8:11]
	v_mfma_f32_16x16x32_bf16 v[60:63], v[148:151], v[194:197], v[60:63]
	v_mfma_f32_16x16x32_bf16 v[56:59], v[170:173], v[194:197], v[56:59]
	v_mfma_f32_16x16x32_bf16 v[44:47], v[148:151], v[202:205], v[44:47]
	v_mfma_f32_16x16x32_bf16 v[40:43], v[170:173], v[202:205], v[40:43]
	v_mfma_f32_16x16x32_bf16 v[28:31], v[148:151], v[214:217], v[28:31]
	v_mfma_f32_16x16x32_bf16 v[24:27], v[170:173], v[214:217], v[24:27]
	v_mfma_f32_16x16x32_bf16 v[12:15], v[148:151], v[222:225], v[12:15]
	v_mfma_f32_16x16x32_bf16 v[8:11], v[170:173], v[222:225], v[8:11]
	s_setprio 0
	s_setprio 1
	v_mfma_f32_16x16x32_bf16 v[52:55], v[174:177], v[190:193], v[52:55]
	v_mfma_f32_16x16x32_bf16 v[48:51], v[182:185], v[190:193], v[48:51]
	v_mfma_f32_16x16x32_bf16 v[36:39], v[174:177], v[198:201], v[36:39]
	v_mfma_f32_16x16x32_bf16 v[32:35], v[182:185], v[198:201], v[32:35]
	v_mfma_f32_16x16x32_bf16 v[20:23], v[174:177], v[206:209], v[20:23]
	v_mfma_f32_16x16x32_bf16 v[16:19], v[182:185], v[206:209], v[16:19]
	v_mfma_f32_16x16x32_bf16 v[4:7], v[174:177], v[218:221], v[4:7]
	v_mfma_f32_16x16x32_bf16 v[0:3], v[182:185], v[218:221], v[0:3]
	v_mfma_f32_16x16x32_bf16 v[52:55], v[178:181], v[194:197], v[52:55]
	v_mfma_f32_16x16x32_bf16 v[48:51], v[186:189], v[194:197], v[48:51]
	v_mfma_f32_16x16x32_bf16 v[36:39], v[178:181], v[202:205], v[36:39]
	v_mfma_f32_16x16x32_bf16 v[32:35], v[186:189], v[202:205], v[32:35]
	v_mfma_f32_16x16x32_bf16 v[20:23], v[178:181], v[214:217], v[20:23]
	v_mfma_f32_16x16x32_bf16 v[16:19], v[186:189], v[214:217], v[16:19]
	v_mfma_f32_16x16x32_bf16 v[4:7], v[178:181], v[222:225], v[4:7]
	v_mfma_f32_16x16x32_bf16 v[0:3], v[186:189], v[222:225], v[0:3]
	s_setprio 0
	s_barrier
	s_add_i32 s33, 0, 0x18000
	s_add_i32 s34, 0, 0x1c000
	v_add_u32_e32 v170, s33, v157
	v_add_u32_e32 v186, s34, v157
	ds_read_b128 v[144:147], v170
	ds_read_b128 v[148:151], v170 offset:1024
	ds_read_b128 v[166:169], v170 offset:2048
	ds_read_b128 v[170:173], v170 offset:3072
	ds_read_b128 v[174:177], v186
	ds_read_b128 v[178:181], v186 offset:1024
	ds_read_b128 v[182:185], v186 offset:2048
	ds_read_b128 v[186:189], v186 offset:3072
	s_add_u32 s22, s90, 0x40000
	s_addc_u32 s23, s91, 0
	s_mov_b32 m0, s15
	ds_read_b128 v[190:193], v163 offset:32768
	ds_read_b128 v[194:197], v163 offset:33792
	ds_read_b128 v[198:201], v163 offset:34816
	ds_read_b128 v[202:205], v163 offset:35840
	ds_read_b128 v[206:209], v163 offset:36864
	ds_read_b128 v[214:217], v163 offset:37888
	ds_read_b128 v[218:221], v163 offset:38912
	ds_read_b128 v[222:225], v163 offset:39936
	global_load_lds_dwordx4 v128, s[22:23]
	v_lshl_add_u64 v[230:231], s[22:23], 0, v[132:133]
	s_mov_b32 m0, s35
	s_nop 0
	global_load_lds_dwordx4 v[230:231], off
	s_waitcnt vmcnt(8)
	s_waitcnt lgkmcnt(0)
	s_barrier
	s_setprio 1
	s_waitcnt lgkmcnt(0)
	v_mfma_f32_16x16x32_bf16 v[124:127], v[144:147], v[190:193], v[124:127]
	v_mfma_f32_16x16x32_bf16 v[120:123], v[166:169], v[190:193], v[120:123]
	v_mfma_f32_16x16x32_bf16 v[108:111], v[144:147], v[198:201], v[108:111]
	v_mfma_f32_16x16x32_bf16 v[104:107], v[166:169], v[198:201], v[104:107]
	v_mfma_f32_16x16x32_bf16 v[92:95], v[144:147], v[206:209], v[92:95]
	v_mfma_f32_16x16x32_bf16 v[88:91], v[166:169], v[206:209], v[88:91]
	v_mfma_f32_16x16x32_bf16 v[76:79], v[144:147], v[218:221], v[76:79]
	v_mfma_f32_16x16x32_bf16 v[72:75], v[166:169], v[218:221], v[72:75]
	v_mfma_f32_16x16x32_bf16 v[124:127], v[148:151], v[194:197], v[124:127]
	v_mfma_f32_16x16x32_bf16 v[120:123], v[170:173], v[194:197], v[120:123]
	v_mfma_f32_16x16x32_bf16 v[108:111], v[148:151], v[202:205], v[108:111]
	v_mfma_f32_16x16x32_bf16 v[104:107], v[170:173], v[202:205], v[104:107]
	v_mfma_f32_16x16x32_bf16 v[92:95], v[148:151], v[214:217], v[92:95]
	v_mfma_f32_16x16x32_bf16 v[88:91], v[170:173], v[214:217], v[88:91]
	v_mfma_f32_16x16x32_bf16 v[76:79], v[148:151], v[222:225], v[76:79]
	v_mfma_f32_16x16x32_bf16 v[72:75], v[170:173], v[222:225], v[72:75]
	s_setprio 0
	s_setprio 1
	v_mfma_f32_16x16x32_bf16 v[116:119], v[174:177], v[190:193], v[116:119]
	v_mfma_f32_16x16x32_bf16 v[112:115], v[182:185], v[190:193], v[112:115]
	v_mfma_f32_16x16x32_bf16 v[100:103], v[174:177], v[198:201], v[100:103]
	v_mfma_f32_16x16x32_bf16 v[96:99], v[182:185], v[198:201], v[96:99]
	v_mfma_f32_16x16x32_bf16 v[84:87], v[174:177], v[206:209], v[84:87]
	v_mfma_f32_16x16x32_bf16 v[80:83], v[182:185], v[206:209], v[80:83]
	v_mfma_f32_16x16x32_bf16 v[68:71], v[174:177], v[218:221], v[68:71]
	v_mfma_f32_16x16x32_bf16 v[64:67], v[182:185], v[218:221], v[64:67]
	v_mfma_f32_16x16x32_bf16 v[116:119], v[178:181], v[194:197], v[116:119]
	v_mfma_f32_16x16x32_bf16 v[112:115], v[186:189], v[194:197], v[112:115]
	v_mfma_f32_16x16x32_bf16 v[100:103], v[178:181], v[202:205], v[100:103]
	v_mfma_f32_16x16x32_bf16 v[96:99], v[186:189], v[202:205], v[96:99]
	v_mfma_f32_16x16x32_bf16 v[84:87], v[178:181], v[214:217], v[84:87]
	v_mfma_f32_16x16x32_bf16 v[80:83], v[186:189], v[214:217], v[80:83]
	v_mfma_f32_16x16x32_bf16 v[68:71], v[178:181], v[222:225], v[68:71]
	v_mfma_f32_16x16x32_bf16 v[64:67], v[186:189], v[222:225], v[64:67]
	s_setprio 0
	s_barrier
; #define STAGE(bufoff, gbase) STAGE_(bufoff, gbase, voffA)
; #define STAGEB(bufoff, gbase) STAGE_(bufoff, gbase, voffB)
; #define LDA(dst, b, h) do { _Pragma("unroll") for (int m = 0; m < 4; ++m) _Pragma("unroll") for (int k = 0; k < 2; ++k) dst[m][k] = *LDSP(const bf16x8, lds + SA(b, h) + aoff + m * 2048 + k * 1024); } while (0)
; #define MMA(ai, bj, AT, BT) do { __builtin_amdgcn_s_setprio(1); \
;     _Pragma("unroll") for (int m = 0; m < 4; ++m) _Pragma("unroll") for (int n = 0; n < 2; ++n) _Pragma("unroll") for (int k = 0; k < 2; ++k) \
;       acc[ai][bj][m][n] = __builtin_amdgcn_mfma_f32_16x16x32_bf16(BT[n][k], AT[m][k], acc[ai][bj][m][n], 0, 0, 0); \
;     __builtin_amdgcn_s_setprio(0); } while (0)
; #define WAIT_V(n) asm volatile("s_waitcnt vmcnt(" #n ")" ::: "memory")
; #define WAIT_L(n) asm volatile("s_waitcnt lgkmcnt(" #n ")" ::: "memory")
; #define BAR __builtin_amdgcn_s_barrier()
; #define SCHED __builtin_amdgcn_sched_barrier(0)
; #define WAIT_V(n) asm volatile("s_waitcnt vmcnt(" #n ")" ::: "memory")
; #define BAR do { __builtin_amdgcn_sched_barrier(0); __builtin_amdgcn_s_barrier(); asm volatile("" ::: "memory"); __builtin_amdgcn_sched_barrier(0); } while (0)
; template <bool SP2, bool ALIGN_EPI, bool DUAL, class Epi> DI void gemm_phase2(const bf16_t* A, const bf16_t* Bt, const bf16_t* A2, const bf16_t* Bt2, int M, int N, int K, const Epi& E, lds_t* lds) {
;     ...
;         LDA(At, 1, 1); STAGEB(SB(1, 0), b3); STAGEB(SB(1, 1), b3 + bstep); STAGE(SA(1, 0), a3);
;         WAIT_V(8); WAIT_L(0); BAR; MMA(1, 0, At, B0); MMA(1, 1, At, B1); BAR; SCHED;
	s_add_i32 s22, s33, s2
	v_lshl_add_u64 v[152:153], v[152:153], 0, s[58:59]
	s_mov_b32 m0, s22
	ds_read_b128 v[190:193], v163 offset:49152
	ds_read_b128 v[194:197], v163 offset:50176
	ds_read_b128 v[198:201], v163 offset:51200
	ds_read_b128 v[202:205], v163 offset:52224
	ds_read_b128 v[206:209], v163 offset:53248
	ds_read_b128 v[214:217], v163 offset:54272
	ds_read_b128 v[218:221], v163 offset:55296
	ds_read_b128 v[222:225], v163 offset:56320
	global_load_lds_dwordx4 v[152:153], off
	s_add_i32 m0, s22, 0x2000
	s_add_u32 s22, s88, 0x10080
	v_lshl_add_u64 v[152:153], v[210:211], 0, s[58:59]
	s_addc_u32 s23, s89, 0
	s_add_i32 s33, s34, s2
	global_load_lds_dwordx4 v[152:153], off
	s_mov_b32 m0, s33
	s_nop 0
	global_load_lds_dwordx4 v130, s[22:23]
	s_add_i32 m0, s33, 0x2000
	s_nop 0
	global_load_lds_dwordx4 v134, s[22:23]
	v_lshl_add_u64 v[152:153], v[226:227], 0, s[58:59]
	s_mov_b32 m0, s52
	s_nop 0
	global_load_lds_dwordx4 v[152:153], off
	v_lshl_add_u64 v[152:153], v[228:229], 0, s[58:59]
	s_mov_b32 m0, s53
	s_nop 0
	global_load_lds_dwordx4 v[152:153], off
	s_waitcnt vmcnt(8)
	s_waitcnt lgkmcnt(0)
	s_barrier
	s_setprio 1
	s_waitcnt lgkmcnt(0)
	v_mfma_f32_16x16x32_bf16 v[60:63], v[144:147], v[190:193], v[60:63]
	v_mfma_f32_16x16x32_bf16 v[56:59], v[166:169], v[190:193], v[56:59]
	v_mfma_f32_16x16x32_bf16 v[44:47], v[144:147], v[198:201], v[44:47]
	v_mfma_f32_16x16x32_bf16 v[40:43], v[166:169], v[198:201], v[40:43]
	v_mfma_f32_16x16x32_bf16 v[28:31], v[144:147], v[206:209], v[28:31]
	v_mfma_f32_16x16x32_bf16 v[24:27], v[166:169], v[206:209], v[24:27]
	v_mfma_f32_16x16x32_bf16 v[12:15], v[144:147], v[218:221], v[12:15]
	v_mfma_f32_16x16x32_bf16 v[8:11], v[166:169], v[218:221], v[8:11]
	v_mfma_f32_16x16x32_bf16 v[60:63], v[148:151], v[194:197], v[60:63]
	v_mfma_f32_16x16x32_bf16 v[56:59], v[170:173], v[194:197], v[56:59]
	v_mfma_f32_16x16x32_bf16 v[44:47], v[148:151], v[202:205], v[44:47]
	v_mfma_f32_16x16x32_bf16 v[40:43], v[170:173], v[202:205], v[40:43]
	v_mfma_f32_16x16x32_bf16 v[28:31], v[148:151], v[214:217], v[28:31]
	v_mfma_f32_16x16x32_bf16 v[24:27], v[170:173], v[214:217], v[24:27]
	v_mfma_f32_16x16x32_bf16 v[12:15], v[148:151], v[222:225], v[12:15]
	v_mfma_f32_16x16x32_bf16 v[8:11], v[170:173], v[222:225], v[8:11]
	s_setprio 0
	s_setprio 1
	v_mfma_f32_16x16x32_bf16 v[52:55], v[174:177], v[190:193], v[52:55]
	v_mfma_f32_16x16x32_bf16 v[48:51], v[182:185], v[190:193], v[48:51]
	v_mfma_f32_16x16x32_bf16 v[36:39], v[174:177], v[198:201], v[36:39]
	v_mfma_f32_16x16x32_bf16 v[32:35], v[182:185], v[198:201], v[32:35]
	v_mfma_f32_16x16x32_bf16 v[20:23], v[174:177], v[206:209], v[20:23]
	v_mfma_f32_16x16x32_bf16 v[16:19], v[182:185], v[206:209], v[16:19]
	v_mfma_f32_16x16x32_bf16 v[4:7], v[174:177], v[218:221], v[4:7]
	v_mfma_f32_16x16x32_bf16 v[0:3], v[182:185], v[218:221], v[0:3]
	v_mfma_f32_16x16x32_bf16 v[52:55], v[178:181], v[194:197], v[52:55]
	v_mfma_f32_16x16x32_bf16 v[48:51], v[186:189], v[194:197], v[48:51]
	v_mfma_f32_16x16x32_bf16 v[36:39], v[178:181], v[202:205], v[36:39]
	v_mfma_f32_16x16x32_bf16 v[32:35], v[186:189], v[202:205], v[32:35]
	v_mfma_f32_16x16x32_bf16 v[20:23], v[178:181], v[214:217], v[20:23]
	v_mfma_f32_16x16x32_bf16 v[16:19], v[186:189], v[214:217], v[16:19]
	v_mfma_f32_16x16x32_bf16 v[4:7], v[178:181], v[222:225], v[4:7]
	v_mfma_f32_16x16x32_bf16 v[0:3], v[186:189], v[222:225], v[0:3]
	s_setprio 0
	s_barrier
	s_add_i32 s21, s21, 2
	s_add_u32 s8, s8, 0x100
	s_addc_u32 s9, s9, 0
	s_add_u32 s19, s19, 0x100
	s_addc_u32 s20, s20, 0
	s_cmp_gt_u32 s21, 13
	s_cbranch_scc0 .LBB0_157
	s_and_b64 vcc, exec, s[60:61]
	s_cbranch_vccz .LBB0_160
	s_barrier

; #define STAGE(bufoff, gbase) STAGE_(bufoff, gbase, voffA)
; #define STAGEB(bufoff, gbase) STAGE_(bufoff, gbase, voffB)
; #define WAIT_V(n) asm volatile("s_waitcnt vmcnt(" #n ")" ::: "memory")
; #define BAR __builtin_amdgcn_s_barrier()
; #define WAIT_V(n) asm volatile("s_waitcnt vmcnt(" #n ")" ::: "memory")
; #define BAR do { __builtin_amdgcn_sched_barrier(0); __builtin_amdgcn_s_barrier(); asm volatile("" ::: "memory"); __builtin_amdgcn_sched_barrier(0); } while (0)
; template <bool SP2, bool ALIGN_EPI, bool DUAL, class Epi> DI void gemm_phase2(const bf16_t* A, const bf16_t* Bt, const bf16_t* A2, const bf16_t* Bt2, int M, int N, int K, const Epi& E, lds_t* lds) {
;     ...
;   for (int i = 0; i < 2; ++i) { int R, C; stage_rc(tid * 16 + i * 8192, R, C); const int Rb = (R >> 5) * 64 + perm32(R & 31);
;     voffA[i] = (unsigned)(R * K + C) * 2u; voffB[i] = (unsigned)(Rb * K + C) * 2u; }
;   const size_t kstep = (size_t)(BK * 2), hstep = (size_t)HALF * K * 2, tstep = 2 * hstep, bstep = (size_t)32 * K * 2;
;   const unsigned ldsw = (unsigned)wid * 1024u;
;   const int aoff = lds_byte(wr * 64 + fr, fq * 8), boff = lds_byte(wc * 32 + fr, fq * 8);
;     ...
;     STAGEB(SB(0, 0), cB); STAGEB(SB(0, 1), cB + bstep); STAGE(SA(0, 0), cA); STAGE(SA(0, 1), cA + hstep);
;     if (wr == 1) BAR;
;     WAIT_V(2); BAR;
;     STAGEB(SB(1, 0), cB + kstep); STAGE(SA(1, 0), cA + kstep); STAGEB(SB(1, 1), cB + bstep + kstep);
;     WAIT_V(6); BAR;
.LBB0_331:
	s_mov_b64 s[8:9], 0x80
	s_and_b32 s0, s0, 3
	s_add_i32 m0, s3, 0x18000
	v_lshl_add_u64 v[6:7], v[6:7], 0, s[8:9]
	s_lshl_b32 s11, s1, 13
	s_lshl_b32 s19, s0, 12
	s_waitcnt vmcnt(2)
	s_barrier
	global_load_lds_dwordx4 v[6:7], off
	v_lshl_add_u64 v[4:5], v[4:5], 0, s[8:9]
	s_add_i32 m0, s3, 0x1a000
	s_add_i32 s15, s3, 0x8000
	s_add_i32 s18, s3, 0xa000
	global_load_lds_dwordx4 v[4:5], off
	v_lshl_add_u64 v[0:1], v[0:1], 0, s[8:9]
	s_mov_b32 m0, s15
	s_add_u32 s20, s86, 0x10080
	global_load_lds_dwordx4 v[0:1], off
	v_lshl_add_u64 v[0:1], v[2:3], 0, s[8:9]
	s_mov_b32 m0, s18
	s_addc_u32 s21, s87, 0
	global_load_lds_dwordx4 v[0:1], off
	s_add_i32 m0, s3, 0x1c000
	s_nop 0
	global_load_lds_dwordx4 v130, s[20:21]
	v_lshl_add_u64 v[0:1], s[20:21], 0, v[134:135]
	s_add_i32 m0, s3, 0x1e000
	v_lshlrev_b32_e32 v3, 2, v8
	global_load_lds_dwordx4 v[0:1], off
	v_lshrrev_b32_e32 v1, 1, v8
	v_and_b32_e32 v1, 24, v1
	v_and_b32_e32 v0, 15, v8
	v_lshlrev_b32_e32 v2, 1, v1
	v_lshl_or_b32 v2, v0, 6, v2
	v_and_b32_e32 v3, 32, v3
	v_bitop3_b32 v4, v2, s11, v3 bitop3:0xde
	v_bitop3_b32 v140, v2, s19, v3 bitop3:0xde
	v_and_b32_e32 v2, 7, v8
	s_sext_i32_i8 s22, s4
	s_cmpk_lt_u32 s5, 0x100
	v_cmp_lt_u32_e64 s[4:5], 7, v0
	v_lshlrev_b32_e32 v0, 12, v2
	v_lshl_or_b32 v143, s1, 18, v0
	v_lshlrev_b32_e32 v0, 14, v9
	v_and_b32_e32 v0, 0xffff8000, v0
	v_lshl_or_b32 v144, s0, 6, v1
	v_lshl_add_u32 v0, v10, 11, v0
	v_and_b32_e32 v1, 1, v9
	v_lshl_or_b32 v0, v1, 6, v0
	v_lshl_add_u32 v136, v11, 1, v0
	v_lshlrev_b32_e32 v0, 14, v12
	v_and_b32_e32 v0, 0xffff8000, v0
	s_waitcnt vmcnt(6)
	v_lshl_add_u32 v0, v13, 11, v0
	v_and_b32_e32 v1, 1, v12
	s_cselect_b64 s[54:55], -1, 0
	v_lshl_or_b32 v0, v1, 6, v0
	s_add_i32 s19, 0, 0x10000
	s_add_i32 s20, 0, 0x14000
	v_cndmask_b32_e64 v141, 0, 32, s[4:5]
	v_cndmask_b32_e64 v142, 32, 0, s[4:5]
	v_mov_b32_e32 v137, v131
	v_lshl_add_u32 v138, v14, 1, v0
	v_mov_b32_e32 v139, v131
	v_add_u32_e32 v145, s19, v140
	v_add_u32_e32 v146, s20, v140
	v_add_u32_e32 v147, 0, v4
	s_mov_b32 s60, 0
	s_mov_b32 s21, 0
	s_barrier
	s_branch .LBB0_334

; #define STAGE(bufoff, gbase) STAGE_(bufoff, gbase, voffA)
; #define STAGEB(bufoff, gbase) STAGE_(bufoff, gbase, voffB)
; #define LDA(dst, b, h) do { _Pragma("unroll") for (int m = 0; m < 4; ++m) _Pragma("unroll") for (int k = 0; k < 2; ++k) dst[m][k] = *LDSP(const bf16x8, lds + SA(b, h) + aoff + m * 2048 + k * 1024); } while (0)
; #define LDB(dst, b, h) do { _Pragma("unroll") for (int n = 0; n < 2; ++n) _Pragma("unroll") for (int k = 0; k < 2; ++k) dst[n][k] = *LDSP(const bf16x8, lds + SB(b, h) + boff + n * 2048 + k * 1024); } while (0)
; #define MMA(ai, bj, AT, BT) do { __builtin_amdgcn_s_setprio(1); \
;     _Pragma("unroll") for (int m = 0; m < 4; ++m) _Pragma("unroll") for (int n = 0; n < 2; ++n) _Pragma("unroll") for (int k = 0; k < 2; ++k) \
;       acc[ai][bj][m][n] = __builtin_amdgcn_mfma_f32_16x16x32_bf16(BT[n][k], AT[m][k], acc[ai][bj][m][n], 0, 0, 0); \
;     __builtin_amdgcn_s_setprio(0); } while (0)
; #define WAIT_V(n) asm volatile("s_waitcnt vmcnt(" #n ")" ::: "memory")
; #define WAIT_L(n) asm volatile("s_waitcnt lgkmcnt(" #n ")" ::: "memory")
; #define BAR __builtin_amdgcn_s_barrier()
; #define SCHED __builtin_amdgcn_sched_barrier(0)
; #define WAIT_V(n) asm volatile("s_waitcnt vmcnt(" #n ")" ::: "memory")
; #define BAR do { __builtin_amdgcn_sched_barrier(0); __builtin_amdgcn_s_barrier(); asm volatile("" ::: "memory"); __builtin_amdgcn_sched_barrier(0); } while (0)
; template <bool SP2, bool ALIGN_EPI, bool DUAL, class Epi> DI void gemm_phase2(const bf16_t* A, const bf16_t* Bt, const bf16_t* A2, const bf16_t* Bt2, int M, int N, int K, const Epi& E, lds_t* lds) {
;     ...
;       const char* a1 = cA + (size_t)(t + 1) * kstep;
;       const char* a2 = last ? nA : cA + (size_t)(t + 2) * kstep; const char* b2 = last ? nB : cB + (size_t)(t + 2) * kstep;
;       const char* a3 = a2 + kstep; const char* b3 = b2 + kstep;
;       if constexpr (SP2) {
;         LDB(B0, 0, 0); LDB(B1, 0, 1); SCHED; LDA(At, 0, 0); STAGE(SA(1, 1), a1 + hstep);
;         WAIT_V(8); WAIT_L(0); BAR; MMA(0, 0, At, B0); MMA(0, 1, At, B1); BAR; SCHED;
;         LDA(At, 0, 1); STAGEB(SB(0, 0), b2); STAGEB(SB(0, 1), b2 + bstep); STAGE(SA(0, 0), a2);
;         WAIT_V(8); WAIT_L(0); BAR; MMA(1, 0, At, B0); MMA(1, 1, At, B1); BAR; SCHED;
.LBB0_341:
	ds_read_b128 v[148:151], v145
	ds_read_b128 v[156:159], v145 offset:1024
	ds_read_b128 v[160:163], v145 offset:2048
	ds_read_b128 v[164:167], v145 offset:3072
	ds_read_b128 v[168:171], v146
	ds_read_b128 v[172:175], v146 offset:1024
	ds_read_b128 v[176:179], v146 offset:2048
	ds_read_b128 v[180:183], v146 offset:3072
	s_add_u32 s52, s68, 0xfffc0080
	s_addc_u32 s53, s69, -1
	s_cmp_eq_u32 s35, 12
	s_cselect_b32 s89, s0, s53
	s_cselect_b32 s88, s1, s52
	s_cselect_b32 s87, s11, s34
	s_cselect_b32 s86, s23, s33
	s_add_i32 m0, s3, 0xc000
	ds_read_b128 v[184:187], v147
	ds_read_b128 v[188:191], v147 offset:1024
	ds_read_b128 v[192:195], v147 offset:2048
	ds_read_b128 v[196:199], v147 offset:3072
	ds_read_b128 v[200:203], v147 offset:4096
	ds_read_b128 v[204:207], v147 offset:5120
	ds_read_b128 v[208:211], v147 offset:6144
	ds_read_b128 v[214:217], v147 offset:7168
	global_load_lds_dwordx4 v136, s[68:69]
	s_add_i32 m0, s3, 0xe000
	s_nop 0
	global_load_lds_dwordx4 v138, s[68:69]
	s_waitcnt vmcnt(8)
	s_waitcnt lgkmcnt(0)
	s_barrier
	s_setprio 1
	s_waitcnt lgkmcnt(0)
	v_mfma_f32_16x16x32_bf16 v[124:127], v[148:151], v[184:187], v[124:127]
	v_mfma_f32_16x16x32_bf16 v[120:123], v[160:163], v[184:187], v[120:123]
	v_mfma_f32_16x16x32_bf16 v[108:111], v[148:151], v[192:195], v[108:111]
	v_mfma_f32_16x16x32_bf16 v[104:107], v[160:163], v[192:195], v[104:107]
	v_mfma_f32_16x16x32_bf16 v[92:95], v[148:151], v[200:203], v[92:95]
	v_mfma_f32_16x16x32_bf16 v[88:91], v[160:163], v[200:203], v[88:91]
	v_mfma_f32_16x16x32_bf16 v[76:79], v[148:151], v[208:211], v[76:79]
	v_mfma_f32_16x16x32_bf16 v[72:75], v[160:163], v[208:211], v[72:75]
	v_mfma_f32_16x16x32_bf16 v[124:127], v[156:159], v[188:191], v[124:127]
	v_mfma_f32_16x16x32_bf16 v[120:123], v[164:167], v[188:191], v[120:123]
	v_mfma_f32_16x16x32_bf16 v[108:111], v[156:159], v[196:199], v[108:111]
	v_mfma_f32_16x16x32_bf16 v[104:107], v[164:167], v[196:199], v[104:107]
	v_mfma_f32_16x16x32_bf16 v[92:95], v[156:159], v[204:207], v[92:95]
	v_mfma_f32_16x16x32_bf16 v[88:91], v[164:167], v[204:207], v[88:91]
	v_mfma_f32_16x16x32_bf16 v[76:79], v[156:159], v[214:217], v[76:79]
	v_mfma_f32_16x16x32_bf16 v[72:75], v[164:167], v[214:217], v[72:75]
	s_setprio 0
	s_setprio 1
	v_mfma_f32_16x16x32_bf16 v[116:119], v[168:171], v[184:187], v[116:119]
	v_mfma_f32_16x16x32_bf16 v[112:115], v[176:179], v[184:187], v[112:115]
	v_mfma_f32_16x16x32_bf16 v[100:103], v[168:171], v[192:195], v[100:103]
	v_mfma_f32_16x16x32_bf16 v[96:99], v[176:179], v[192:195], v[96:99]
	v_mfma_f32_16x16x32_bf16 v[84:87], v[168:171], v[200:203], v[84:87]
	v_mfma_f32_16x16x32_bf16 v[80:83], v[176:179], v[200:203], v[80:83]
	v_mfma_f32_16x16x32_bf16 v[68:71], v[168:171], v[208:211], v[68:71]
	v_mfma_f32_16x16x32_bf16 v[64:67], v[176:179], v[208:211], v[64:67]
	v_mfma_f32_16x16x32_bf16 v[116:119], v[172:175], v[188:191], v[116:119]
	v_mfma_f32_16x16x32_bf16 v[112:115], v[180:183], v[188:191], v[112:115]
	v_mfma_f32_16x16x32_bf16 v[100:103], v[172:175], v[196:199], v[100:103]
	v_mfma_f32_16x16x32_bf16 v[96:99], v[180:183], v[196:199], v[96:99]
	v_mfma_f32_16x16x32_bf16 v[84:87], v[172:175], v[204:207], v[84:87]
	v_mfma_f32_16x16x32_bf16 v[80:83], v[180:183], v[204:207], v[80:83]
	v_mfma_f32_16x16x32_bf16 v[68:71], v[172:175], v[214:217], v[68:71]
	v_mfma_f32_16x16x32_bf16 v[64:67], v[180:183], v[214:217], v[64:67]
	s_setprio 0
	s_barrier
	s_add_i32 s52, s19, s2
	v_lshl_add_u64 v[152:153], s[86:87], 0, v[130:131]
	s_mov_b32 m0, s52
	ds_read_b128 v[184:187], v147 offset:16384
	ds_read_b128 v[188:191], v147 offset:17408
	ds_read_b128 v[192:195], v147 offset:18432
	ds_read_b128 v[196:199], v147 offset:19456
	ds_read_b128 v[200:203], v147 offset:20480
	ds_read_b128 v[204:207], v147 offset:21504
	ds_read_b128 v[208:211], v147 offset:22528
	ds_read_b128 v[214:217], v147 offset:23552
	global_load_lds_dwordx4 v[152:153], off
	s_add_i32 m0, s52, 0x2000
	s_add_u32 s52, s86, 0x10000
	v_lshl_add_u64 v[218:219], s[86:87], 0, v[134:135]
	s_addc_u32 s53, s87, 0
	s_add_i32 s61, s20, s2
	global_load_lds_dwordx4 v[218:219], off
	s_mov_b32 m0, s61
	v_lshl_add_u64 v[222:223], s[88:89], 0, v[132:133]
	global_load_lds_dwordx4 v130, s[52:53]
	s_add_i32 m0, s61, 0x2000
	s_nop 0
	global_load_lds_dwordx4 v134, s[52:53]
	v_lshl_add_u64 v[220:221], s[88:89], 0, v[128:129]
	s_mov_b32 m0, s3
	s_nop 0
	global_load_lds_dwordx4 v[220:221], off
	s_mov_b32 m0, s12
	s_nop 0
	global_load_lds_dwordx4 v[222:223], off
	s_waitcnt vmcnt(8)
	s_waitcnt lgkmcnt(0)
	s_barrier
; #define STAGE(bufoff, gbase) STAGE_(bufoff, gbase, voffA)
; #define LDA(dst, b, h) do { _Pragma("unroll") for (int m = 0; m < 4; ++m) _Pragma("unroll") for (int k = 0; k < 2; ++k) dst[m][k] = *LDSP(const bf16x8, lds + SA(b, h) + aoff + m * 2048 + k * 1024); } while (0)
; #define LDB(dst, b, h) do { _Pragma("unroll") for (int n = 0; n < 2; ++n) _Pragma("unroll") for (int k = 0; k < 2; ++k) dst[n][k] = *LDSP(const bf16x8, lds + SB(b, h) + boff + n * 2048 + k * 1024); } while (0)
; #define MMA(ai, bj, AT, BT) do { __builtin_amdgcn_s_setprio(1); \
;     _Pragma("unroll") for (int m = 0; m < 4; ++m) _Pragma("unroll") for (int n = 0; n < 2; ++n) _Pragma("unroll") for (int k = 0; k < 2; ++k) \
;       acc[ai][bj][m][n] = __builtin_amdgcn_mfma_f32_16x16x32_bf16(BT[n][k], AT[m][k], acc[ai][bj][m][n], 0, 0, 0); \
;     __builtin_amdgcn_s_setprio(0); } while (0)
; #define WAIT_V(n) asm volatile("s_waitcnt vmcnt(" #n ")" ::: "memory")
; #define WAIT_L(n) asm volatile("s_waitcnt lgkmcnt(" #n ")" ::: "memory")
; #define BAR __builtin_amdgcn_s_barrier()
; #define SCHED __builtin_amdgcn_sched_barrier(0)
; #define WAIT_V(n) asm volatile("s_waitcnt vmcnt(" #n ")" ::: "memory")
; #define BAR do { __builtin_amdgcn_sched_barrier(0); __builtin_amdgcn_s_barrier(); asm volatile("" ::: "memory"); __builtin_amdgcn_sched_barrier(0); } while (0)
; template <bool SP2, bool ALIGN_EPI, bool DUAL, class Epi> DI void gemm_phase2(const bf16_t* A, const bf16_t* Bt, const bf16_t* A2, const bf16_t* Bt2, int M, int N, int K, const Epi& E, lds_t* lds) {
;     ...
;         WAIT_V(8); WAIT_L(0); BAR; MMA(1, 0, At, B0); MMA(1, 1, At, B1); BAR; SCHED;
;         LDB(B0, 1, 0); LDB(B1, 1, 1); SCHED; LDA(At, 1, 0); STAGE(SA(0, 1), a2 + hstep);
;         WAIT_V(8); WAIT_L(0); BAR; MMA(0, 0, At, B0); MMA(0, 1, At, B1); BAR; SCHED;
	s_setprio 1
	s_waitcnt lgkmcnt(0)
	v_mfma_f32_16x16x32_bf16 v[60:63], v[148:151], v[184:187], v[60:63]
	v_mfma_f32_16x16x32_bf16 v[56:59], v[160:163], v[184:187], v[56:59]
	v_mfma_f32_16x16x32_bf16 v[44:47], v[148:151], v[192:195], v[44:47]
	v_mfma_f32_16x16x32_bf16 v[40:43], v[160:163], v[192:195], v[40:43]
	v_mfma_f32_16x16x32_bf16 v[28:31], v[148:151], v[200:203], v[28:31]
	v_mfma_f32_16x16x32_bf16 v[24:27], v[160:163], v[200:203], v[24:27]
	v_mfma_f32_16x16x32_bf16 v[12:15], v[148:151], v[208:211], v[12:15]
	v_mfma_f32_16x16x32_bf16 v[8:11], v[160:163], v[208:211], v[8:11]
	v_mfma_f32_16x16x32_bf16 v[60:63], v[156:159], v[188:191], v[60:63]
	v_mfma_f32_16x16x32_bf16 v[56:59], v[164:167], v[188:191], v[56:59]
	v_mfma_f32_16x16x32_bf16 v[44:47], v[156:159], v[196:199], v[44:47]
	v_mfma_f32_16x16x32_bf16 v[40:43], v[164:167], v[196:199], v[40:43]
	v_mfma_f32_16x16x32_bf16 v[28:31], v[156:159], v[204:207], v[28:31]
	v_mfma_f32_16x16x32_bf16 v[24:27], v[164:167], v[204:207], v[24:27]
	v_mfma_f32_16x16x32_bf16 v[12:15], v[156:159], v[214:217], v[12:15]
	v_mfma_f32_16x16x32_bf16 v[8:11], v[164:167], v[214:217], v[8:11]
	s_setprio 0
	s_setprio 1
	v_mfma_f32_16x16x32_bf16 v[52:55], v[168:171], v[184:187], v[52:55]
	v_mfma_f32_16x16x32_bf16 v[48:51], v[176:179], v[184:187], v[48:51]
	v_mfma_f32_16x16x32_bf16 v[36:39], v[168:171], v[192:195], v[36:39]
	v_mfma_f32_16x16x32_bf16 v[32:35], v[176:179], v[192:195], v[32:35]
	v_mfma_f32_16x16x32_bf16 v[20:23], v[168:171], v[200:203], v[20:23]
	v_mfma_f32_16x16x32_bf16 v[16:19], v[176:179], v[200:203], v[16:19]
	v_mfma_f32_16x16x32_bf16 v[4:7], v[168:171], v[208:211], v[4:7]
	v_mfma_f32_16x16x32_bf16 v[0:3], v[176:179], v[208:211], v[0:3]
	v_mfma_f32_16x16x32_bf16 v[52:55], v[172:175], v[188:191], v[52:55]
	v_mfma_f32_16x16x32_bf16 v[48:51], v[180:183], v[188:191], v[48:51]
	v_mfma_f32_16x16x32_bf16 v[36:39], v[172:175], v[196:199], v[36:39]
	v_mfma_f32_16x16x32_bf16 v[32:35], v[180:183], v[196:199], v[32:35]
	v_mfma_f32_16x16x32_bf16 v[20:23], v[172:175], v[204:207], v[20:23]
	v_mfma_f32_16x16x32_bf16 v[16:19], v[180:183], v[204:207], v[16:19]
	v_mfma_f32_16x16x32_bf16 v[4:7], v[172:175], v[214:217], v[4:7]
	v_mfma_f32_16x16x32_bf16 v[0:3], v[180:183], v[214:217], v[0:3]
	s_setprio 0
	s_barrier
	s_add_i32 s61, 0, 0x18000
	v_add_u32_e32 v155, s61, v140
	s_add_i32 s65, 0, 0x1c000
	ds_read_b128 v[148:151], v155
	ds_read_b128 v[156:159], v155 offset:1024
	ds_read_b128 v[160:163], v155 offset:2048
	ds_read_b128 v[164:167], v155 offset:3072
	v_add_u32_e32 v155, s65, v140
	ds_read_b128 v[168:171], v155
	ds_read_b128 v[172:175], v155 offset:1024
	ds_read_b128 v[176:179], v155 offset:2048
	ds_read_b128 v[180:183], v155 offset:3072
	s_add_u32 s52, s88, 0x40000
	s_addc_u32 s53, s89, 0
	s_mov_b32 m0, s13
	ds_read_b128 v[184:187], v147 offset:32768
	ds_read_b128 v[188:191], v147 offset:33792
	ds_read_b128 v[192:195], v147 offset:34816
	ds_read_b128 v[196:199], v147 offset:35840
	ds_read_b128 v[200:203], v147 offset:36864
	ds_read_b128 v[204:207], v147 offset:37888
	ds_read_b128 v[208:211], v147 offset:38912
	ds_read_b128 v[214:217], v147 offset:39936
	global_load_lds_dwordx4 v128, s[52:53]
	v_lshl_add_u64 v[224:225], s[52:53], 0, v[132:133]
	s_mov_b32 m0, s14
	s_nop 0
	global_load_lds_dwordx4 v[224:225], off
	s_waitcnt vmcnt(8)
	s_waitcnt lgkmcnt(0)
	s_barrier
	s_setprio 1
	s_waitcnt lgkmcnt(0)
	v_mfma_f32_16x16x32_bf16 v[124:127], v[148:151], v[184:187], v[124:127]
	v_mfma_f32_16x16x32_bf16 v[120:123], v[160:163], v[184:187], v[120:123]
	v_mfma_f32_16x16x32_bf16 v[108:111], v[148:151], v[192:195], v[108:111]
	v_mfma_f32_16x16x32_bf16 v[104:107], v[160:163], v[192:195], v[104:107]
	v_mfma_f32_16x16x32_bf16 v[92:95], v[148:151], v[200:203], v[92:95]
	v_mfma_f32_16x16x32_bf16 v[88:91], v[160:163], v[200:203], v[88:91]
	v_mfma_f32_16x16x32_bf16 v[76:79], v[148:151], v[208:211], v[76:79]
	v_mfma_f32_16x16x32_bf16 v[72:75], v[160:163], v[208:211], v[72:75]
	v_mfma_f32_16x16x32_bf16 v[124:127], v[156:159], v[188:191], v[124:127]
	v_mfma_f32_16x16x32_bf16 v[120:123], v[164:167], v[188:191], v[120:123]
	v_mfma_f32_16x16x32_bf16 v[108:111], v[156:159], v[196:199], v[108:111]
	v_mfma_f32_16x16x32_bf16 v[104:107], v[164:167], v[196:199], v[104:107]
	v_mfma_f32_16x16x32_bf16 v[92:95], v[156:159], v[204:207], v[92:95]
	v_mfma_f32_16x16x32_bf16 v[88:91], v[164:167], v[204:207], v[88:91]
	v_mfma_f32_16x16x32_bf16 v[76:79], v[156:159], v[214:217], v[76:79]
	v_mfma_f32_16x16x32_bf16 v[72:75], v[164:167], v[214:217], v[72:75]
	s_setprio 0
	s_setprio 1
	v_mfma_f32_16x16x32_bf16 v[116:119], v[168:171], v[184:187], v[116:119]
	v_mfma_f32_16x16x32_bf16 v[112:115], v[176:179], v[184:187], v[112:115]
	v_mfma_f32_16x16x32_bf16 v[100:103], v[168:171], v[192:195], v[100:103]
	v_mfma_f32_16x16x32_bf16 v[96:99], v[176:179], v[192:195], v[96:99]
	v_mfma_f32_16x16x32_bf16 v[84:87], v[168:171], v[200:203], v[84:87]
	v_mfma_f32_16x16x32_bf16 v[80:83], v[176:179], v[200:203], v[80:83]
	v_mfma_f32_16x16x32_bf16 v[68:71], v[168:171], v[208:211], v[68:71]
	v_mfma_f32_16x16x32_bf16 v[64:67], v[176:179], v[208:211], v[64:67]
	v_mfma_f32_16x16x32_bf16 v[116:119], v[172:175], v[188:191], v[116:119]
	v_mfma_f32_16x16x32_bf16 v[112:115], v[180:183], v[188:191], v[112:115]
	v_mfma_f32_16x16x32_bf16 v[100:103], v[172:175], v[196:199], v[100:103]
	v_mfma_f32_16x16x32_bf16 v[96:99], v[180:183], v[196:199], v[96:99]
	v_mfma_f32_16x16x32_bf16 v[84:87], v[172:175], v[204:207], v[84:87]
	v_mfma_f32_16x16x32_bf16 v[80:83], v[180:183], v[204:207], v[80:83]
	v_mfma_f32_16x16x32_bf16 v[68:71], v[172:175], v[214:217], v[68:71]
	v_mfma_f32_16x16x32_bf16 v[64:67], v[180:183], v[214:217], v[64:67]
	s_setprio 0
	s_barrier
; #define STAGE(bufoff, gbase) STAGE_(bufoff, gbase, voffA)
; #define STAGEB(bufoff, gbase) STAGE_(bufoff, gbase, voffB)
; #define LDA(dst, b, h) do { _Pragma("unroll") for (int m = 0; m < 4; ++m) _Pragma("unroll") for (int k = 0; k < 2; ++k) dst[m][k] = *LDSP(const bf16x8, lds + SA(b, h) + aoff + m * 2048 + k * 1024); } while (0)
; #define MMA(ai, bj, AT, BT) do { __builtin_amdgcn_s_setprio(1); \
;     _Pragma("unroll") for (int m = 0; m < 4; ++m) _Pragma("unroll") for (int n = 0; n < 2; ++n) _Pragma("unroll") for (int k = 0; k < 2; ++k) \
;       acc[ai][bj][m][n] = __builtin_amdgcn_mfma_f32_16x16x32_bf16(BT[n][k], AT[m][k], acc[ai][bj][m][n], 0, 0, 0); \
;     __builtin_amdgcn_s_setprio(0); } while (0)
; #define WAIT_V(n) asm volatile("s_waitcnt vmcnt(" #n ")" ::: "memory")
; #define WAIT_L(n) asm volatile("s_waitcnt lgkmcnt(" #n ")" ::: "memory")
; #define BAR __builtin_amdgcn_s_barrier()
; #define SCHED __builtin_amdgcn_sched_barrier(0)
; #define WAIT_V(n) asm volatile("s_waitcnt vmcnt(" #n ")" ::: "memory")
; #define BAR do { __builtin_amdgcn_sched_barrier(0); __builtin_amdgcn_s_barrier(); asm volatile("" ::: "memory"); __builtin_amdgcn_sched_barrier(0); } while (0)
; template <bool SP2, bool ALIGN_EPI, bool DUAL, class Epi> DI void gemm_phase2(const bf16_t* A, const bf16_t* Bt, const bf16_t* A2, const bf16_t* Bt2, int M, int N, int K, const Epi& E, lds_t* lds) {
;     ...
;         LDA(At, 1, 1); STAGEB(SB(1, 0), b3); STAGEB(SB(1, 1), b3 + bstep); STAGE(SA(1, 0), a3);
;         WAIT_V(8); WAIT_L(0); BAR; MMA(1, 0, At, B0); MMA(1, 1, At, B1); BAR; SCHED;
	s_add_i32 s52, s61, s2
	v_lshl_add_u64 v[152:153], v[152:153], 0, s[8:9]
	s_mov_b32 m0, s52
	ds_read_b128 v[184:187], v147 offset:49152
	ds_read_b128 v[188:191], v147 offset:50176
	ds_read_b128 v[192:195], v147 offset:51200
	ds_read_b128 v[196:199], v147 offset:52224
	ds_read_b128 v[200:203], v147 offset:53248
	ds_read_b128 v[204:207], v147 offset:54272
	ds_read_b128 v[208:211], v147 offset:55296
	ds_read_b128 v[214:217], v147 offset:56320
	global_load_lds_dwordx4 v[152:153], off
	s_add_i32 m0, s52, 0x2000
	s_add_u32 s52, s86, 0x10080
	v_lshl_add_u64 v[152:153], v[218:219], 0, s[8:9]
	s_addc_u32 s53, s87, 0
	s_add_i32 s61, s65, s2
	global_load_lds_dwordx4 v[152:153], off
	s_mov_b32 m0, s61
	s_nop 0
	global_load_lds_dwordx4 v130, s[52:53]
	s_add_i32 m0, s61, 0x2000
	s_nop 0
	global_load_lds_dwordx4 v134, s[52:53]
	v_lshl_add_u64 v[152:153], v[220:221], 0, s[8:9]
	s_mov_b32 m0, s15
	s_nop 0
	global_load_lds_dwordx4 v[152:153], off
	v_lshl_add_u64 v[152:153], v[222:223], 0, s[8:9]
	s_mov_b32 m0, s18
	s_nop 0
	global_load_lds_dwordx4 v[152:153], off
	s_waitcnt vmcnt(8)
	s_waitcnt lgkmcnt(0)
	s_barrier
	s_setprio 1
	s_waitcnt lgkmcnt(0)
	v_mfma_f32_16x16x32_bf16 v[60:63], v[148:151], v[184:187], v[60:63]
	v_mfma_f32_16x16x32_bf16 v[56:59], v[160:163], v[184:187], v[56:59]
	v_mfma_f32_16x16x32_bf16 v[44:47], v[148:151], v[192:195], v[44:47]
	v_mfma_f32_16x16x32_bf16 v[40:43], v[160:163], v[192:195], v[40:43]
	v_mfma_f32_16x16x32_bf16 v[28:31], v[148:151], v[200:203], v[28:31]
	v_mfma_f32_16x16x32_bf16 v[24:27], v[160:163], v[200:203], v[24:27]
	v_mfma_f32_16x16x32_bf16 v[12:15], v[148:151], v[208:211], v[12:15]
	v_mfma_f32_16x16x32_bf16 v[8:11], v[160:163], v[208:211], v[8:11]
	v_mfma_f32_16x16x32_bf16 v[60:63], v[156:159], v[188:191], v[60:63]
	v_mfma_f32_16x16x32_bf16 v[56:59], v[164:167], v[188:191], v[56:59]
	v_mfma_f32_16x16x32_bf16 v[44:47], v[156:159], v[196:199], v[44:47]
	v_mfma_f32_16x16x32_bf16 v[40:43], v[164:167], v[196:199], v[40:43]
	v_mfma_f32_16x16x32_bf16 v[28:31], v[156:159], v[204:207], v[28:31]
	v_mfma_f32_16x16x32_bf16 v[24:27], v[164:167], v[204:207], v[24:27]
	v_mfma_f32_16x16x32_bf16 v[12:15], v[156:159], v[214:217], v[12:15]
	v_mfma_f32_16x16x32_bf16 v[8:11], v[164:167], v[214:217], v[8:11]
	s_setprio 0
	s_setprio 1
	v_mfma_f32_16x16x32_bf16 v[52:55], v[168:171], v[184:187], v[52:55]
	v_mfma_f32_16x16x32_bf16 v[48:51], v[176:179], v[184:187], v[48:51]
	v_mfma_f32_16x16x32_bf16 v[36:39], v[168:171], v[192:195], v[36:39]
	v_mfma_f32_16x16x32_bf16 v[32:35], v[176:179], v[192:195], v[32:35]
	v_mfma_f32_16x16x32_bf16 v[20:23], v[168:171], v[200:203], v[20:23]
	v_mfma_f32_16x16x32_bf16 v[16:19], v[176:179], v[200:203], v[16:19]
	v_mfma_f32_16x16x32_bf16 v[4:7], v[168:171], v[208:211], v[4:7]
	v_mfma_f32_16x16x32_bf16 v[0:3], v[176:179], v[208:211], v[0:3]
	v_mfma_f32_16x16x32_bf16 v[52:55], v[172:175], v[188:191], v[52:55]
	v_mfma_f32_16x16x32_bf16 v[48:51], v[180:183], v[188:191], v[48:51]
	v_mfma_f32_16x16x32_bf16 v[36:39], v[172:175], v[196:199], v[36:39]
	v_mfma_f32_16x16x32_bf16 v[32:35], v[180:183], v[196:199], v[32:35]
	v_mfma_f32_16x16x32_bf16 v[20:23], v[172:175], v[204:207], v[20:23]
	v_mfma_f32_16x16x32_bf16 v[16:19], v[180:183], v[204:207], v[16:19]
	v_mfma_f32_16x16x32_bf16 v[4:7], v[172:175], v[214:217], v[4:7]
	v_mfma_f32_16x16x32_bf16 v[0:3], v[180:183], v[214:217], v[0:3]
	s_setprio 0
	s_barrier
	s_add_i32 s35, s35, 2
	s_add_u32 s68, s68, 0x100
	s_addc_u32 s69, s69, 0
	s_add_u32 s33, s33, 0x100
	s_addc_u32 s34, s34, 0
	s_cmp_gt_u32 s35, 13
	s_cbranch_scc0 .LBB0_341
	s_and_b64 vcc, exec, s[54:55]
	s_cbranch_vccz .LBB0_344
	s_barrier

; #define STAGE(bufoff, gbase) STAGE_(bufoff, gbase, voffA)
; #define STAGEB(bufoff, gbase) STAGE_(bufoff, gbase, voffB)
; #define WAIT_V(n) asm volatile("s_waitcnt vmcnt(" #n ")" ::: "memory")
; #define BAR __builtin_amdgcn_s_barrier()
; #define WAIT_V(n) asm volatile("s_waitcnt vmcnt(" #n ")" ::: "memory")
; #define BAR do { __builtin_amdgcn_sched_barrier(0); __builtin_amdgcn_s_barrier(); asm volatile("" ::: "memory"); __builtin_amdgcn_sched_barrier(0); } while (0)
; DI void zero_acc(Acc& acc) {
; #pragma unroll
;   for (int a = 0; a < 2; ++a)
; #pragma unroll
;     for (int b = 0; b < 2; ++b)
; #pragma unroll
;       for (int m = 0; m < 4; ++m)
; #pragma unroll
;         for (int n = 0; n < 2; ++n) acc[a][b][m][n] = (f32x4){0.f, 0.f, 0.f, 0.f};
; }
; template <bool SP2, bool ALIGN_EPI, bool DUAL, class Epi> DI void gemm_phase2(const bf16_t* A, const bf16_t* Bt, const bf16_t* A2, const bf16_t* Bt2, int M, int N, int K, const Epi& E, lds_t* lds) {
;     ...
;     STAGEB(SB(0, 0), cB); STAGEB(SB(0, 1), cB + bstep); STAGE(SA(0, 0), cA); STAGE(SA(0, 1), cA + hstep);
;     if (wr == 1) BAR;
;     WAIT_V(2); BAR;
;     STAGEB(SB(1, 0), cB + kstep); STAGE(SA(1, 0), cA + kstep); STAGEB(SB(1, 1), cB + bstep + kstep);
;     WAIT_V(6); BAR;
.LBB0_469:
	v_bfe_u32 v15, v8, 4, 2
	s_add_u32 s28, s74, 0x14000000
	v_and_b32_e32 v140, 15, v8
	v_lshlrev_b32_e32 v17, 3, v15
	v_lshlrev_b32_e32 v15, 4, v15
	v_lshlrev_b32_e32 v19, 2, v8
	s_mov_b64 s[30:31], 0x80
	s_sext_i32_i8 s33, s0
	s_addc_u32 s29, s75, 0
	s_and_b32 s4, s1, 3
	v_lshl_or_b32 v18, v140, 6, v15
	s_lshl_b32 s0, s3, 13
	v_and_b32_e32 v19, 32, v19
	s_add_i32 m0, s9, 0x18000
	v_lshl_add_u64 v[6:7], v[6:7], 0, s[30:31]
	s_lshl_b32 s15, s3, 6
	v_bitop3_b32 v20, v18, s0, v19 bitop3:0xde
	s_lshl_b32 s0, s4, 12
	s_waitcnt vmcnt(2)
	s_barrier
	global_load_lds_dwordx4 v[6:7], off
	v_lshl_add_u64 v[4:5], v[4:5], 0, s[30:31]
	s_add_i32 m0, s9, 0x1a000
	s_add_i32 s18, s9, 0x8000
	s_add_i32 s19, s9, 0xa000
	v_bitop3_b32 v141, v18, s0, v19 bitop3:0xde
	global_load_lds_dwordx4 v[4:5], off
	v_lshl_add_u64 v[0:1], v[0:1], 0, s[30:31]
	s_mov_b32 m0, s18
	s_add_u32 s0, s62, 0x10080
	global_load_lds_dwordx4 v[0:1], off
	v_lshl_add_u64 v[0:1], v[2:3], 0, s[30:31]
	s_mov_b32 m0, s19
	s_addc_u32 s1, s63, 0
	global_load_lds_dwordx4 v[0:1], off
	s_add_i32 m0, s9, 0x1c000
	s_nop 0
	global_load_lds_dwordx4 v130, s[0:1]
	v_lshl_add_u64 v[0:1], s[0:1], 0, v[134:135]
	s_add_i32 m0, s9, 0x1e000
	v_or_b32_e32 v16, s15, v140
	global_load_lds_dwordx4 v[0:1], off
	v_lshlrev_b32_e32 v0, 14, v9
	v_and_b32_e32 v0, 0xffff8000, v0
	v_lshl_add_u32 v0, v10, 11, v0
	v_and_b32_e32 v1, 1, v9
	v_lshl_or_b32 v0, v1, 6, v0
	v_lshl_add_u32 v136, v11, 1, v0
	v_lshlrev_b32_e32 v0, 14, v12
	v_and_b32_e32 v0, 0xffff8000, v0
	s_waitcnt vmcnt(6)
	v_lshl_add_u32 v0, v13, 11, v0
	v_and_b32_e32 v1, 1, v12
	s_cmpk_lt_u32 s2, 0x100
	v_lshl_or_b32 v142, s4, 7, v15
	v_lshl_or_b32 v145, s4, 6, v17
	v_cmp_lt_u32_e64 s[4:5], 7, v140
	v_lshl_or_b32 v0, v1, 6, v0
	s_cselect_b64 s[38:39], -1, 0
	v_or_b32_e32 v143, 0x800, v142
	v_and_b32_e32 v144, 7, v8
	v_cndmask_b32_e64 v146, 0, 32, s[4:5]
	v_cndmask_b32_e64 v147, 32, 0, s[4:5]
	v_lshlrev_b32_e32 v148, 12, v16
	v_mov_b32_e32 v137, v131
	v_lshl_add_u32 v138, v14, 1, v0
	v_mov_b32_e32 v139, v131
	s_add_i32 s20, 0, 0x10000
	s_add_i32 s21, 0, 0x14000
	v_add_u32_e32 v149, 0, v20
	v_mov_b32_e32 v150, 0x4000
	s_mov_b32 s40, 0
	s_mov_b32 s23, 0
	s_mov_b32 s22, 0
	v_mov_b32_e32 v0, v131
	v_mov_b32_e32 v1, v131
	v_mov_b32_e32 v2, v131
	v_mov_b32_e32 v3, v131
	v_mov_b32_e32 v4, v131
	v_mov_b32_e32 v5, v131
	v_mov_b32_e32 v6, v131
	v_mov_b32_e32 v7, v131
	v_mov_b32_e32 v8, v131
	v_mov_b32_e32 v9, v131
	v_mov_b32_e32 v10, v131
	v_mov_b32_e32 v11, v131
	v_mov_b32_e32 v12, v131
	v_mov_b32_e32 v13, v131
	v_mov_b32_e32 v14, v131
	v_mov_b32_e32 v15, v131
	v_mov_b32_e32 v16, v131
	v_mov_b32_e32 v17, v131
	v_mov_b32_e32 v18, v131
	v_mov_b32_e32 v19, v131
	v_mov_b32_e32 v20, v131
	v_mov_b32_e32 v21, v131
	v_mov_b32_e32 v22, v131
	v_mov_b32_e32 v23, v131
	v_mov_b32_e32 v24, v131
	v_mov_b32_e32 v25, v131
	v_mov_b32_e32 v26, v131
	v_mov_b32_e32 v27, v131
	v_mov_b32_e32 v28, v131
	v_mov_b32_e32 v29, v131
	v_mov_b32_e32 v30, v131
	v_mov_b32_e32 v31, v131
	v_mov_b32_e32 v32, v131
	v_mov_b32_e32 v33, v131
	v_mov_b32_e32 v34, v131
	v_mov_b32_e32 v35, v131
	v_mov_b32_e32 v36, v131
	v_mov_b32_e32 v37, v131
	v_mov_b32_e32 v38, v131
	v_mov_b32_e32 v39, v131
	v_mov_b32_e32 v40, v131
	v_mov_b32_e32 v41, v131
	v_mov_b32_e32 v42, v131
	v_mov_b32_e32 v43, v131
	v_mov_b32_e32 v44, v131
	v_mov_b32_e32 v45, v131
	v_mov_b32_e32 v46, v131
	v_mov_b32_e32 v47, v131
	v_mov_b32_e32 v48, v131
	v_mov_b32_e32 v49, v131
	v_mov_b32_e32 v50, v131
	v_mov_b32_e32 v51, v131
	v_mov_b32_e32 v52, v131
	v_mov_b32_e32 v53, v131
	v_mov_b32_e32 v54, v131
	v_mov_b32_e32 v55, v131
	v_mov_b32_e32 v56, v131
	v_mov_b32_e32 v57, v131
	v_mov_b32_e32 v58, v131
	v_mov_b32_e32 v59, v131
	v_mov_b32_e32 v60, v131
	v_mov_b32_e32 v61, v131
	v_mov_b32_e32 v62, v131
	v_mov_b32_e32 v63, v131
	v_mov_b32_e32 v64, v131
	v_mov_b32_e32 v65, v131
	v_mov_b32_e32 v66, v131
	v_mov_b32_e32 v67, v131
	v_mov_b32_e32 v68, v131
	v_mov_b32_e32 v69, v131
	v_mov_b32_e32 v70, v131
	v_mov_b32_e32 v71, v131
	v_mov_b32_e32 v72, v131
	v_mov_b32_e32 v73, v131
	v_mov_b32_e32 v74, v131
	v_mov_b32_e32 v75, v131
	v_mov_b32_e32 v76, v131
	v_mov_b32_e32 v77, v131
	v_mov_b32_e32 v78, v131
	v_mov_b32_e32 v79, v131
	v_mov_b32_e32 v80, v131
	v_mov_b32_e32 v81, v131
	v_mov_b32_e32 v82, v131
	v_mov_b32_e32 v83, v131
	v_mov_b32_e32 v84, v131
	v_mov_b32_e32 v85, v131
	v_mov_b32_e32 v86, v131
	v_mov_b32_e32 v87, v131
	v_mov_b32_e32 v88, v131
	v_mov_b32_e32 v89, v131
	v_mov_b32_e32 v90, v131
	v_mov_b32_e32 v91, v131
	v_mov_b32_e32 v92, v131
	v_mov_b32_e32 v93, v131
	v_mov_b32_e32 v94, v131
	v_mov_b32_e32 v95, v131
	v_mov_b32_e32 v96, v131
	v_mov_b32_e32 v97, v131
	v_mov_b32_e32 v98, v131
	v_mov_b32_e32 v99, v131
	v_mov_b32_e32 v100, v131
	v_mov_b32_e32 v101, v131
	v_mov_b32_e32 v102, v131
	v_mov_b32_e32 v103, v131
	v_mov_b32_e32 v104, v131
	v_mov_b32_e32 v105, v131
	v_mov_b32_e32 v106, v131
	v_mov_b32_e32 v107, v131
	v_mov_b32_e32 v108, v131
	v_mov_b32_e32 v109, v131
	v_mov_b32_e32 v110, v131
	v_mov_b32_e32 v111, v131
	v_mov_b32_e32 v112, v131
	v_mov_b32_e32 v113, v131
	v_mov_b32_e32 v114, v131
	v_mov_b32_e32 v115, v131
	v_mov_b32_e32 v116, v131
	v_mov_b32_e32 v117, v131
	v_mov_b32_e32 v118, v131
	v_mov_b32_e32 v119, v131
	v_mov_b32_e32 v120, v131
	v_mov_b32_e32 v121, v131
	v_mov_b32_e32 v122, v131
	v_mov_b32_e32 v123, v131
	v_mov_b32_e32 v124, v131
	v_mov_b32_e32 v125, v131
	v_mov_b32_e32 v126, v131
	v_mov_b32_e32 v127, v131
	s_barrier
	s_branch .LBB0_472

; #define STAGE(bufoff, gbase) STAGE_(bufoff, gbase, voffA)
; #define STAGEB(bufoff, gbase) STAGE_(bufoff, gbase, voffB)
; #define LDA(dst, b, h) do { _Pragma("unroll") for (int m = 0; m < 4; ++m) _Pragma("unroll") for (int k = 0; k < 2; ++k) dst[m][k] = *LDSP(const bf16x8, lds + SA(b, h) + aoff + m * 2048 + k * 1024); } while (0)
; #define LDB(dst, b, h) do { _Pragma("unroll") for (int n = 0; n < 2; ++n) _Pragma("unroll") for (int k = 0; k < 2; ++k) dst[n][k] = *LDSP(const bf16x8, lds + SB(b, h) + boff + n * 2048 + k * 1024); } while (0)
; #define MMA(ai, bj, AT, BT) do { __builtin_amdgcn_s_setprio(1); \
;     _Pragma("unroll") for (int m = 0; m < 4; ++m) _Pragma("unroll") for (int n = 0; n < 2; ++n) _Pragma("unroll") for (int k = 0; k < 2; ++k) \
;       acc[ai][bj][m][n] = __builtin_amdgcn_mfma_f32_16x16x32_bf16(BT[n][k], AT[m][k], acc[ai][bj][m][n], 0, 0, 0); \
;     __builtin_amdgcn_s_setprio(0); } while (0)
; #define WAIT_V(n) asm volatile("s_waitcnt vmcnt(" #n ")" ::: "memory")
; #define WAIT_L(n) asm volatile("s_waitcnt lgkmcnt(" #n ")" ::: "memory")
; #define BAR __builtin_amdgcn_s_barrier()
; #define SCHED __builtin_amdgcn_sched_barrier(0)
; #define WAIT_V(n) asm volatile("s_waitcnt vmcnt(" #n ")" ::: "memory")
; #define BAR do { __builtin_amdgcn_sched_barrier(0); __builtin_amdgcn_s_barrier(); asm volatile("" ::: "memory"); __builtin_amdgcn_sched_barrier(0); } while (0)
; template <bool SP2, bool ALIGN_EPI, bool DUAL, class Epi> DI void gemm_phase2(const bf16_t* A, const bf16_t* Bt, const bf16_t* A2, const bf16_t* Bt2, int M, int N, int K, const Epi& E, lds_t* lds) {
;     ...
;       const char* a1 = cA + (size_t)(t + 1) * kstep;
;       const char* a2 = last ? nA : cA + (size_t)(t + 2) * kstep; const char* b2 = last ? nB : cB + (size_t)(t + 2) * kstep;
;       const char* a3 = a2 + kstep; const char* b3 = b2 + kstep;
;       if constexpr (SP2) {
;         LDB(B0, 0, 0); LDB(B1, 0, 1); SCHED; LDA(At, 0, 0); STAGE(SA(1, 1), a1 + hstep);
;         WAIT_V(8); WAIT_L(0); BAR; MMA(0, 0, At, B0); MMA(0, 1, At, B1); BAR; SCHED;
;         LDA(At, 0, 1); STAGEB(SB(0, 0), b2); STAGEB(SB(0, 1), b2 + bstep); STAGE(SA(0, 0), a2);
;         WAIT_V(8); WAIT_L(0); BAR; MMA(1, 0, At, B0); MMA(1, 1, At, B1); BAR; SCHED;
.LBB0_482:
	v_add_u32_e32 v151, s20, v141
	ds_read_b128 v[152:155], v151
	ds_read_b128 v[156:159], v151 offset:1024
	ds_read_b128 v[160:163], v151 offset:2048
	ds_read_b128 v[164:167], v151 offset:3072
	v_add_u32_e32 v151, s21, v141
	ds_read_b128 v[168:171], v151
	ds_read_b128 v[172:175], v151 offset:1024
	ds_read_b128 v[176:179], v151 offset:2048
	ds_read_b128 v[180:183], v151 offset:3072
	s_add_u32 s41, s60, 0xfffc0080
	s_addc_u32 s59, s61, -1
	s_cmp_eq_u32 s37, 12
	s_cselect_b32 s65, s2, s59
	s_cselect_b32 s64, s3, s41
	s_cselect_b32 s63, s0, s35
	s_cselect_b32 s62, s1, s34
	s_add_i32 m0, s9, 0xc000
	ds_read_b128 v[184:187], v149
	ds_read_b128 v[188:191], v149 offset:1024
	ds_read_b128 v[192:195], v149 offset:2048
	ds_read_b128 v[196:199], v149 offset:3072
	ds_read_b128 v[200:203], v149 offset:4096
	ds_read_b128 v[204:207], v149 offset:5120
	ds_read_b128 v[208:211], v149 offset:6144
	ds_read_b128 v[216:219], v149 offset:7168
	global_load_lds_dwordx4 v136, s[60:61]
	s_add_i32 m0, s9, 0xe000
	s_nop 0
	global_load_lds_dwordx4 v138, s[60:61]
	s_waitcnt vmcnt(8)
	s_waitcnt lgkmcnt(0)
	s_barrier
	s_setprio 1
	s_waitcnt lgkmcnt(0)
	v_mfma_f32_16x16x32_bf16 v[124:127], v[152:155], v[184:187], v[124:127]
	v_mfma_f32_16x16x32_bf16 v[120:123], v[160:163], v[184:187], v[120:123]
	v_mfma_f32_16x16x32_bf16 v[116:119], v[152:155], v[192:195], v[116:119]
	v_mfma_f32_16x16x32_bf16 v[112:115], v[160:163], v[192:195], v[112:115]
	v_mfma_f32_16x16x32_bf16 v[108:111], v[152:155], v[200:203], v[108:111]
	v_mfma_f32_16x16x32_bf16 v[104:107], v[160:163], v[200:203], v[104:107]
	v_mfma_f32_16x16x32_bf16 v[100:103], v[152:155], v[208:211], v[100:103]
	v_mfma_f32_16x16x32_bf16 v[96:99], v[160:163], v[208:211], v[96:99]
	v_mfma_f32_16x16x32_bf16 v[124:127], v[156:159], v[188:191], v[124:127]
	v_mfma_f32_16x16x32_bf16 v[120:123], v[164:167], v[188:191], v[120:123]
	v_mfma_f32_16x16x32_bf16 v[116:119], v[156:159], v[196:199], v[116:119]
	v_mfma_f32_16x16x32_bf16 v[112:115], v[164:167], v[196:199], v[112:115]
	v_mfma_f32_16x16x32_bf16 v[108:111], v[156:159], v[204:207], v[108:111]
	v_mfma_f32_16x16x32_bf16 v[104:107], v[164:167], v[204:207], v[104:107]
	v_mfma_f32_16x16x32_bf16 v[100:103], v[156:159], v[216:219], v[100:103]
	v_mfma_f32_16x16x32_bf16 v[96:99], v[164:167], v[216:219], v[96:99]
	s_setprio 0
	s_setprio 1
	v_mfma_f32_16x16x32_bf16 v[92:95], v[168:171], v[184:187], v[92:95]
	v_mfma_f32_16x16x32_bf16 v[88:91], v[176:179], v[184:187], v[88:91]
	v_mfma_f32_16x16x32_bf16 v[84:87], v[168:171], v[192:195], v[84:87]
	v_mfma_f32_16x16x32_bf16 v[80:83], v[176:179], v[192:195], v[80:83]
	v_mfma_f32_16x16x32_bf16 v[76:79], v[168:171], v[200:203], v[76:79]
	v_mfma_f32_16x16x32_bf16 v[72:75], v[176:179], v[200:203], v[72:75]
	v_mfma_f32_16x16x32_bf16 v[68:71], v[168:171], v[208:211], v[68:71]
	v_mfma_f32_16x16x32_bf16 v[64:67], v[176:179], v[208:211], v[64:67]
	v_mfma_f32_16x16x32_bf16 v[92:95], v[172:175], v[188:191], v[92:95]
	v_mfma_f32_16x16x32_bf16 v[88:91], v[180:183], v[188:191], v[88:91]
	v_mfma_f32_16x16x32_bf16 v[84:87], v[172:175], v[196:199], v[84:87]
	v_mfma_f32_16x16x32_bf16 v[80:83], v[180:183], v[196:199], v[80:83]
	v_mfma_f32_16x16x32_bf16 v[76:79], v[172:175], v[204:207], v[76:79]
	v_mfma_f32_16x16x32_bf16 v[72:75], v[180:183], v[204:207], v[72:75]
	v_mfma_f32_16x16x32_bf16 v[68:71], v[172:175], v[216:219], v[68:71]
	v_mfma_f32_16x16x32_bf16 v[64:67], v[180:183], v[216:219], v[64:67]
	s_setprio 0
	s_barrier
	s_add_i32 s41, s20, s8
	v_lshl_add_u64 v[220:221], s[62:63], 0, v[130:131]
	s_mov_b32 m0, s41
	ds_read_b128 v[184:187], v149 offset:16384
	ds_read_b128 v[188:191], v149 offset:17408
	ds_read_b128 v[192:195], v149 offset:18432
	ds_read_b128 v[196:199], v149 offset:19456
	ds_read_b128 v[200:203], v149 offset:20480
	ds_read_b128 v[204:207], v149 offset:21504
	ds_read_b128 v[208:211], v149 offset:22528
	ds_read_b128 v[216:219], v149 offset:23552
	global_load_lds_dwordx4 v[220:221], off
	s_add_i32 m0, s41, 0x2000
	s_add_u32 s66, s62, 0x10000
	v_lshl_add_u64 v[222:223], s[62:63], 0, v[134:135]
	s_addc_u32 s67, s63, 0
	s_add_i32 s41, s21, s8
	global_load_lds_dwordx4 v[222:223], off
	s_mov_b32 m0, s41
	v_lshl_add_u64 v[226:227], s[64:65], 0, v[132:133]
	global_load_lds_dwordx4 v130, s[66:67]
	s_add_i32 m0, s41, 0x2000
	s_nop 0
	global_load_lds_dwordx4 v134, s[66:67]
	v_lshl_add_u64 v[224:225], s[64:65], 0, v[128:129]
	s_mov_b32 m0, s9
	s_nop 0
	global_load_lds_dwordx4 v[224:225], off
	s_mov_b32 m0, s10
	s_nop 0
	global_load_lds_dwordx4 v[226:227], off
	s_waitcnt vmcnt(8)
	s_waitcnt lgkmcnt(0)
	s_barrier
; #define STAGE(bufoff, gbase) STAGE_(bufoff, gbase, voffA)
; #define LDA(dst, b, h) do { _Pragma("unroll") for (int m = 0; m < 4; ++m) _Pragma("unroll") for (int k = 0; k < 2; ++k) dst[m][k] = *LDSP(const bf16x8, lds + SA(b, h) + aoff + m * 2048 + k * 1024); } while (0)
; #define LDB(dst, b, h) do { _Pragma("unroll") for (int n = 0; n < 2; ++n) _Pragma("unroll") for (int k = 0; k < 2; ++k) dst[n][k] = *LDSP(const bf16x8, lds + SB(b, h) + boff + n * 2048 + k * 1024); } while (0)
; #define MMA(ai, bj, AT, BT) do { __builtin_amdgcn_s_setprio(1); \
;     _Pragma("unroll") for (int m = 0; m < 4; ++m) _Pragma("unroll") for (int n = 0; n < 2; ++n) _Pragma("unroll") for (int k = 0; k < 2; ++k) \
;       acc[ai][bj][m][n] = __builtin_amdgcn_mfma_f32_16x16x32_bf16(BT[n][k], AT[m][k], acc[ai][bj][m][n], 0, 0, 0); \
;     __builtin_amdgcn_s_setprio(0); } while (0)
; #define WAIT_V(n) asm volatile("s_waitcnt vmcnt(" #n ")" ::: "memory")
; #define WAIT_L(n) asm volatile("s_waitcnt lgkmcnt(" #n ")" ::: "memory")
; #define BAR __builtin_amdgcn_s_barrier()
; #define SCHED __builtin_amdgcn_sched_barrier(0)
; #define WAIT_V(n) asm volatile("s_waitcnt vmcnt(" #n ")" ::: "memory")
; #define BAR do { __builtin_amdgcn_sched_barrier(0); __builtin_amdgcn_s_barrier(); asm volatile("" ::: "memory"); __builtin_amdgcn_sched_barrier(0); } while (0)
; template <bool SP2, bool ALIGN_EPI, bool DUAL, class Epi> DI void gemm_phase2(const bf16_t* A, const bf16_t* Bt, const bf16_t* A2, const bf16_t* Bt2, int M, int N, int K, const Epi& E, lds_t* lds) {
;     ...
;         WAIT_V(8); WAIT_L(0); BAR; MMA(1, 0, At, B0); MMA(1, 1, At, B1); BAR; SCHED;
;         LDB(B0, 1, 0); LDB(B1, 1, 1); SCHED; LDA(At, 1, 0); STAGE(SA(0, 1), a2 + hstep);
;         WAIT_V(8); WAIT_L(0); BAR; MMA(0, 0, At, B0); MMA(0, 1, At, B1); BAR; SCHED;
	s_setprio 1
	s_waitcnt lgkmcnt(0)
	v_mfma_f32_16x16x32_bf16 v[60:63], v[152:155], v[184:187], v[60:63]
	v_mfma_f32_16x16x32_bf16 v[56:59], v[160:163], v[184:187], v[56:59]
	v_mfma_f32_16x16x32_bf16 v[52:55], v[152:155], v[192:195], v[52:55]
	v_mfma_f32_16x16x32_bf16 v[48:51], v[160:163], v[192:195], v[48:51]
	v_mfma_f32_16x16x32_bf16 v[44:47], v[152:155], v[200:203], v[44:47]
	v_mfma_f32_16x16x32_bf16 v[40:43], v[160:163], v[200:203], v[40:43]
	v_mfma_f32_16x16x32_bf16 v[36:39], v[152:155], v[208:211], v[36:39]
	v_mfma_f32_16x16x32_bf16 v[32:35], v[160:163], v[208:211], v[32:35]
	v_mfma_f32_16x16x32_bf16 v[60:63], v[156:159], v[188:191], v[60:63]
	v_mfma_f32_16x16x32_bf16 v[56:59], v[164:167], v[188:191], v[56:59]
	v_mfma_f32_16x16x32_bf16 v[52:55], v[156:159], v[196:199], v[52:55]
	v_mfma_f32_16x16x32_bf16 v[48:51], v[164:167], v[196:199], v[48:51]
	v_mfma_f32_16x16x32_bf16 v[44:47], v[156:159], v[204:207], v[44:47]
	v_mfma_f32_16x16x32_bf16 v[40:43], v[164:167], v[204:207], v[40:43]
	v_mfma_f32_16x16x32_bf16 v[36:39], v[156:159], v[216:219], v[36:39]
	v_mfma_f32_16x16x32_bf16 v[32:35], v[164:167], v[216:219], v[32:35]
	s_setprio 0
	s_setprio 1
	v_mfma_f32_16x16x32_bf16 v[28:31], v[168:171], v[184:187], v[28:31]
	v_mfma_f32_16x16x32_bf16 v[24:27], v[176:179], v[184:187], v[24:27]
	v_mfma_f32_16x16x32_bf16 v[20:23], v[168:171], v[192:195], v[20:23]
	v_mfma_f32_16x16x32_bf16 v[16:19], v[176:179], v[192:195], v[16:19]
	v_mfma_f32_16x16x32_bf16 v[12:15], v[168:171], v[200:203], v[12:15]
	v_mfma_f32_16x16x32_bf16 v[8:11], v[176:179], v[200:203], v[8:11]
	v_mfma_f32_16x16x32_bf16 v[4:7], v[168:171], v[208:211], v[4:7]
	v_mfma_f32_16x16x32_bf16 v[0:3], v[176:179], v[208:211], v[0:3]
	v_mfma_f32_16x16x32_bf16 v[28:31], v[172:175], v[188:191], v[28:31]
	v_mfma_f32_16x16x32_bf16 v[24:27], v[180:183], v[188:191], v[24:27]
	v_mfma_f32_16x16x32_bf16 v[20:23], v[172:175], v[196:199], v[20:23]
	v_mfma_f32_16x16x32_bf16 v[16:19], v[180:183], v[196:199], v[16:19]
	v_mfma_f32_16x16x32_bf16 v[12:15], v[172:175], v[204:207], v[12:15]
	v_mfma_f32_16x16x32_bf16 v[8:11], v[180:183], v[204:207], v[8:11]
	v_mfma_f32_16x16x32_bf16 v[4:7], v[172:175], v[216:219], v[4:7]
	v_mfma_f32_16x16x32_bf16 v[0:3], v[180:183], v[216:219], v[0:3]
	s_setprio 0
	s_barrier
	s_add_i32 s41, 0, 0x18000
	v_add_u32_e32 v151, s41, v141
	s_add_i32 s59, 0, 0x1c000
	ds_read_b128 v[152:155], v151
	ds_read_b128 v[156:159], v151 offset:1024
	ds_read_b128 v[160:163], v151 offset:2048
	ds_read_b128 v[164:167], v151 offset:3072
	v_add_u32_e32 v151, s59, v141
	ds_read_b128 v[168:171], v151
	ds_read_b128 v[172:175], v151 offset:1024
	ds_read_b128 v[176:179], v151 offset:2048
	ds_read_b128 v[180:183], v151 offset:3072
	s_add_u32 s64, s64, 0x40000
	s_addc_u32 s65, s65, 0
	s_mov_b32 m0, s11
	ds_read_b128 v[184:187], v149 offset:32768
	ds_read_b128 v[188:191], v149 offset:33792
	ds_read_b128 v[192:195], v149 offset:34816
	ds_read_b128 v[196:199], v149 offset:35840
	ds_read_b128 v[200:203], v149 offset:36864
	ds_read_b128 v[204:207], v149 offset:37888
	ds_read_b128 v[208:211], v149 offset:38912
	ds_read_b128 v[216:219], v149 offset:39936
	global_load_lds_dwordx4 v128, s[64:65]
	v_lshl_add_u64 v[228:229], s[64:65], 0, v[132:133]
	s_mov_b32 m0, s14
	s_nop 0
	global_load_lds_dwordx4 v[228:229], off
	s_waitcnt vmcnt(8)
	s_waitcnt lgkmcnt(0)
	s_barrier
	s_setprio 1
	s_waitcnt lgkmcnt(0)
	v_mfma_f32_16x16x32_bf16 v[124:127], v[152:155], v[184:187], v[124:127]
	v_mfma_f32_16x16x32_bf16 v[120:123], v[160:163], v[184:187], v[120:123]
	v_mfma_f32_16x16x32_bf16 v[116:119], v[152:155], v[192:195], v[116:119]
	v_mfma_f32_16x16x32_bf16 v[112:115], v[160:163], v[192:195], v[112:115]
	v_mfma_f32_16x16x32_bf16 v[108:111], v[152:155], v[200:203], v[108:111]
	v_mfma_f32_16x16x32_bf16 v[104:107], v[160:163], v[200:203], v[104:107]
	v_mfma_f32_16x16x32_bf16 v[100:103], v[152:155], v[208:211], v[100:103]
	v_mfma_f32_16x16x32_bf16 v[96:99], v[160:163], v[208:211], v[96:99]
	v_mfma_f32_16x16x32_bf16 v[124:127], v[156:159], v[188:191], v[124:127]
	v_mfma_f32_16x16x32_bf16 v[120:123], v[164:167], v[188:191], v[120:123]
	v_mfma_f32_16x16x32_bf16 v[116:119], v[156:159], v[196:199], v[116:119]
	v_mfma_f32_16x16x32_bf16 v[112:115], v[164:167], v[196:199], v[112:115]
	v_mfma_f32_16x16x32_bf16 v[108:111], v[156:159], v[204:207], v[108:111]
	v_mfma_f32_16x16x32_bf16 v[104:107], v[164:167], v[204:207], v[104:107]
	v_mfma_f32_16x16x32_bf16 v[100:103], v[156:159], v[216:219], v[100:103]
	v_mfma_f32_16x16x32_bf16 v[96:99], v[164:167], v[216:219], v[96:99]
	s_setprio 0
	s_setprio 1
	v_mfma_f32_16x16x32_bf16 v[92:95], v[168:171], v[184:187], v[92:95]
	v_mfma_f32_16x16x32_bf16 v[88:91], v[176:179], v[184:187], v[88:91]
	v_mfma_f32_16x16x32_bf16 v[84:87], v[168:171], v[192:195], v[84:87]
	v_mfma_f32_16x16x32_bf16 v[80:83], v[176:179], v[192:195], v[80:83]
	v_mfma_f32_16x16x32_bf16 v[76:79], v[168:171], v[200:203], v[76:79]
	v_mfma_f32_16x16x32_bf16 v[72:75], v[176:179], v[200:203], v[72:75]
	v_mfma_f32_16x16x32_bf16 v[68:71], v[168:171], v[208:211], v[68:71]
	v_mfma_f32_16x16x32_bf16 v[64:67], v[176:179], v[208:211], v[64:67]
	v_mfma_f32_16x16x32_bf16 v[92:95], v[172:175], v[188:191], v[92:95]
	v_mfma_f32_16x16x32_bf16 v[88:91], v[180:183], v[188:191], v[88:91]
	v_mfma_f32_16x16x32_bf16 v[84:87], v[172:175], v[196:199], v[84:87]
	v_mfma_f32_16x16x32_bf16 v[80:83], v[180:183], v[196:199], v[80:83]
	v_mfma_f32_16x16x32_bf16 v[76:79], v[172:175], v[204:207], v[76:79]
	v_mfma_f32_16x16x32_bf16 v[72:75], v[180:183], v[204:207], v[72:75]
	v_mfma_f32_16x16x32_bf16 v[68:71], v[172:175], v[216:219], v[68:71]
	v_mfma_f32_16x16x32_bf16 v[64:67], v[180:183], v[216:219], v[64:67]
	s_setprio 0
	s_barrier
; #define STAGE(bufoff, gbase) STAGE_(bufoff, gbase, voffA)
; #define STAGEB(bufoff, gbase) STAGE_(bufoff, gbase, voffB)
; #define LDA(dst, b, h) do { _Pragma("unroll") for (int m = 0; m < 4; ++m) _Pragma("unroll") for (int k = 0; k < 2; ++k) dst[m][k] = *LDSP(const bf16x8, lds + SA(b, h) + aoff + m * 2048 + k * 1024); } while (0)
; #define MMA(ai, bj, AT, BT) do { __builtin_amdgcn_s_setprio(1); \
;     _Pragma("unroll") for (int m = 0; m < 4; ++m) _Pragma("unroll") for (int n = 0; n < 2; ++n) _Pragma("unroll") for (int k = 0; k < 2; ++k) \
;       acc[ai][bj][m][n] = __builtin_amdgcn_mfma_f32_16x16x32_bf16(BT[n][k], AT[m][k], acc[ai][bj][m][n], 0, 0, 0); \
;     __builtin_amdgcn_s_setprio(0); } while (0)
; #define WAIT_V(n) asm volatile("s_waitcnt vmcnt(" #n ")" ::: "memory")
; #define WAIT_L(n) asm volatile("s_waitcnt lgkmcnt(" #n ")" ::: "memory")
; #define BAR __builtin_amdgcn_s_barrier()
; #define SCHED __builtin_amdgcn_sched_barrier(0)
; #define WAIT_V(n) asm volatile("s_waitcnt vmcnt(" #n ")" ::: "memory")
; #define BAR do { __builtin_amdgcn_sched_barrier(0); __builtin_amdgcn_s_barrier(); asm volatile("" ::: "memory"); __builtin_amdgcn_sched_barrier(0); } while (0)
; template <bool SP2, bool ALIGN_EPI, bool DUAL, class Epi> DI void gemm_phase2(const bf16_t* A, const bf16_t* Bt, const bf16_t* A2, const bf16_t* Bt2, int M, int N, int K, const Epi& E, lds_t* lds) {
;     ...
;         LDA(At, 1, 1); STAGEB(SB(1, 0), b3); STAGEB(SB(1, 1), b3 + bstep); STAGE(SA(1, 0), a3);
;         WAIT_V(8); WAIT_L(0); BAR; MMA(1, 0, At, B0); MMA(1, 1, At, B1); BAR; SCHED;
	s_add_i32 s41, s41, s8
	v_lshl_add_u64 v[220:221], v[220:221], 0, s[30:31]
	s_mov_b32 m0, s41
	ds_read_b128 v[184:187], v149 offset:49152
	ds_read_b128 v[188:191], v149 offset:50176
	ds_read_b128 v[192:195], v149 offset:51200
	ds_read_b128 v[196:199], v149 offset:52224
	ds_read_b128 v[200:203], v149 offset:53248
	ds_read_b128 v[204:207], v149 offset:54272
	ds_read_b128 v[208:211], v149 offset:55296
	ds_read_b128 v[216:219], v149 offset:56320
	global_load_lds_dwordx4 v[220:221], off
	s_add_i32 m0, s41, 0x2000
	s_add_u32 s62, s62, 0x10080
	v_lshl_add_u64 v[220:221], v[222:223], 0, s[30:31]
	s_addc_u32 s63, s63, 0
	s_add_i32 s41, s59, s8
	global_load_lds_dwordx4 v[220:221], off
	s_mov_b32 m0, s41
	s_nop 0
	global_load_lds_dwordx4 v130, s[62:63]
	s_add_i32 m0, s41, 0x2000
	s_nop 0
	global_load_lds_dwordx4 v134, s[62:63]
	v_lshl_add_u64 v[220:221], v[224:225], 0, s[30:31]
	s_mov_b32 m0, s18
	s_nop 0
	global_load_lds_dwordx4 v[220:221], off
	v_lshl_add_u64 v[220:221], v[226:227], 0, s[30:31]
	s_mov_b32 m0, s19
	s_nop 0
	global_load_lds_dwordx4 v[220:221], off
	s_waitcnt vmcnt(8)
	s_waitcnt lgkmcnt(0)
	s_barrier
	s_setprio 1
	s_waitcnt lgkmcnt(0)
	v_mfma_f32_16x16x32_bf16 v[60:63], v[152:155], v[184:187], v[60:63]
	v_mfma_f32_16x16x32_bf16 v[56:59], v[160:163], v[184:187], v[56:59]
	v_mfma_f32_16x16x32_bf16 v[52:55], v[152:155], v[192:195], v[52:55]
	v_mfma_f32_16x16x32_bf16 v[48:51], v[160:163], v[192:195], v[48:51]
	v_mfma_f32_16x16x32_bf16 v[44:47], v[152:155], v[200:203], v[44:47]
	v_mfma_f32_16x16x32_bf16 v[40:43], v[160:163], v[200:203], v[40:43]
	v_mfma_f32_16x16x32_bf16 v[36:39], v[152:155], v[208:211], v[36:39]
	v_mfma_f32_16x16x32_bf16 v[32:35], v[160:163], v[208:211], v[32:35]
	v_mfma_f32_16x16x32_bf16 v[60:63], v[156:159], v[188:191], v[60:63]
	v_mfma_f32_16x16x32_bf16 v[56:59], v[164:167], v[188:191], v[56:59]
	v_mfma_f32_16x16x32_bf16 v[52:55], v[156:159], v[196:199], v[52:55]
	v_mfma_f32_16x16x32_bf16 v[48:51], v[164:167], v[196:199], v[48:51]
	v_mfma_f32_16x16x32_bf16 v[44:47], v[156:159], v[204:207], v[44:47]
	v_mfma_f32_16x16x32_bf16 v[40:43], v[164:167], v[204:207], v[40:43]
	v_mfma_f32_16x16x32_bf16 v[36:39], v[156:159], v[216:219], v[36:39]
	v_mfma_f32_16x16x32_bf16 v[32:35], v[164:167], v[216:219], v[32:35]
	s_setprio 0
	s_setprio 1
	v_mfma_f32_16x16x32_bf16 v[28:31], v[168:171], v[184:187], v[28:31]
	v_mfma_f32_16x16x32_bf16 v[24:27], v[176:179], v[184:187], v[24:27]
	v_mfma_f32_16x16x32_bf16 v[20:23], v[168:171], v[192:195], v[20:23]
	v_mfma_f32_16x16x32_bf16 v[16:19], v[176:179], v[192:195], v[16:19]
	v_mfma_f32_16x16x32_bf16 v[12:15], v[168:171], v[200:203], v[12:15]
	v_mfma_f32_16x16x32_bf16 v[8:11], v[176:179], v[200:203], v[8:11]
	v_mfma_f32_16x16x32_bf16 v[4:7], v[168:171], v[208:211], v[4:7]
	v_mfma_f32_16x16x32_bf16 v[0:3], v[176:179], v[208:211], v[0:3]
	v_mfma_f32_16x16x32_bf16 v[28:31], v[172:175], v[188:191], v[28:31]
	v_mfma_f32_16x16x32_bf16 v[24:27], v[180:183], v[188:191], v[24:27]
	v_mfma_f32_16x16x32_bf16 v[20:23], v[172:175], v[196:199], v[20:23]
	v_mfma_f32_16x16x32_bf16 v[16:19], v[180:183], v[196:199], v[16:19]
	v_mfma_f32_16x16x32_bf16 v[12:15], v[172:175], v[204:207], v[12:15]
	v_mfma_f32_16x16x32_bf16 v[8:11], v[180:183], v[204:207], v[8:11]
	v_mfma_f32_16x16x32_bf16 v[4:7], v[172:175], v[216:219], v[4:7]
	v_mfma_f32_16x16x32_bf16 v[0:3], v[180:183], v[216:219], v[0:3]
	s_setprio 0
	s_barrier
	s_add_i32 s37, s37, 2
	s_add_u32 s60, s60, 0x100
	s_addc_u32 s61, s61, 0
	s_add_u32 s34, s34, 0x100
	s_addc_u32 s35, s35, 0
	s_cmp_gt_u32 s37, 13
	s_cbranch_scc0 .LBB0_482
	s_and_b64 vcc, exec, s[38:39]
	s_cbranch_vccz .LBB0_485
	s_barrier

; #define STAGE(bufoff, gbase) STAGE_(bufoff, gbase, voffA)
; #define STAGEB(bufoff, gbase) STAGE_(bufoff, gbase, voffB)
; #define WAIT_V(n) asm volatile("s_waitcnt vmcnt(" #n ")" ::: "memory")
; #define BAR __builtin_amdgcn_s_barrier()
; #define WAIT_V(n) asm volatile("s_waitcnt vmcnt(" #n ")" ::: "memory")
; #define BAR do { __builtin_amdgcn_sched_barrier(0); __builtin_amdgcn_s_barrier(); asm volatile("" ::: "memory"); __builtin_amdgcn_sched_barrier(0); } while (0)
; template <bool SP2, bool ALIGN_EPI, bool DUAL, class Epi> DI void gemm_phase2(const bf16_t* A, const bf16_t* Bt, const bf16_t* A2, const bf16_t* Bt2, int M, int N, int K, const Epi& E, lds_t* lds) {
;     ...
;   for (int i = 0; i < 2; ++i) { int R, C; stage_rc(tid * 16 + i * 8192, R, C); const int Rb = (R >> 5) * 64 + perm32(R & 31);
;     voffA[i] = (unsigned)(R * K + C) * 2u; voffB[i] = (unsigned)(Rb * K + C) * 2u; }
;   const size_t kstep = (size_t)(BK * 2), hstep = (size_t)HALF * K * 2, tstep = 2 * hstep, bstep = (size_t)32 * K * 2;
;   const unsigned ldsw = (unsigned)wid * 1024u;
;   const int aoff = lds_byte(wr * 64 + fr, fq * 8), boff = lds_byte(wc * 32 + fr, fq * 8);
;     ...
;     STAGEB(SB(0, 0), cB); STAGEB(SB(0, 1), cB + bstep); STAGE(SA(0, 0), cA); STAGE(SA(0, 1), cA + hstep);
;     if (wr == 1) BAR;
;     WAIT_V(2); BAR;
;     STAGEB(SB(1, 0), cB + kstep); STAGE(SA(1, 0), cA + kstep); STAGEB(SB(1, 1), cB + bstep + kstep);
;     WAIT_V(6); BAR;
.LBB0_541:
	s_mov_b64 s[30:31], 0x80
	s_and_b32 s5, s0, 3
	s_add_i32 m0, s3, 0x18000
	v_lshl_add_u64 v[6:7], v[6:7], 0, s[30:31]
	s_lshl_b32 s11, s1, 6
	s_lshl_b32 s6, s1, 13
	s_lshl_b32 s7, s5, 12
	s_waitcnt vmcnt(2)
	s_barrier
	global_load_lds_dwordx4 v[6:7], off
	v_lshl_add_u64 v[4:5], v[4:5], 0, s[30:31]
	s_add_i32 m0, s3, 0x1a000
	s_add_i32 s14, s3, 0x8000
	s_add_i32 s15, s3, 0xa000
	global_load_lds_dwordx4 v[4:5], off
	v_lshl_add_u64 v[0:1], v[0:1], 0, s[30:31]
	s_mov_b32 m0, s14
	s_add_u32 s0, s62, 0x10080
	global_load_lds_dwordx4 v[0:1], off
	v_lshl_add_u64 v[0:1], v[2:3], 0, s[30:31]
	s_mov_b32 m0, s15
	s_addc_u32 s1, s63, 0
	global_load_lds_dwordx4 v[0:1], off
	s_add_i32 m0, s3, 0x1c000
	s_nop 0
	global_load_lds_dwordx4 v130, s[0:1]
	v_lshl_add_u64 v[0:1], s[0:1], 0, v[134:135]
	s_add_i32 m0, s3, 0x1e000
	s_cmpk_lt_u32 s4, 0x100
	global_load_lds_dwordx4 v[0:1], off
	v_bfe_u32 v0, v8, 4, 2
	v_lshlrev_b32_e32 v1, 3, v0
	v_lshlrev_b32_e32 v2, 4, v0
	v_lshl_or_b32 v144, s5, 6, v1
	v_cmp_eq_u32_e64 s[4:5], 0, v0
	v_lshlrev_b32_e32 v0, 14, v9
	v_and_b32_e32 v0, 0xffff8000, v0
	v_lshl_add_u32 v0, v10, 11, v0
	v_and_b32_e32 v1, 1, v9
	v_lshl_or_b32 v0, v1, 6, v0
	v_lshl_add_u32 v136, v11, 1, v0
	v_lshlrev_b32_e32 v0, 14, v12
	v_and_b32_e32 v142, 15, v8
	v_lshlrev_b32_e32 v3, 2, v8
	v_and_b32_e32 v0, 0xffff8000, v0
	v_lshl_or_b32 v2, v142, 6, v2
	v_and_b32_e32 v3, 32, v3
	s_waitcnt vmcnt(6)
	v_lshl_add_u32 v0, v13, 11, v0
	v_and_b32_e32 v1, 1, v12
	v_bitop3_b32 v4, v2, s6, v3 bitop3:0xde
	v_bitop3_b32 v143, v2, s7, v3 bitop3:0xde
	s_cselect_b64 s[38:39], -1, 0
	v_cmp_lt_u32_e64 s[6:7], 7, v142
	v_lshl_or_b32 v0, v1, 6, v0
	s_add_i32 s18, 0, 0x10000
	s_add_i32 s19, 0, 0x14000
	v_and_b32_e32 v145, 7, v8
	v_cndmask_b32_e64 v146, 0, 32, s[6:7]
	v_cndmask_b32_e64 v147, 32, 0, s[6:7]
	v_mov_b32_e32 v137, v131
	v_lshl_add_u32 v138, v14, 1, v0
	v_mov_b32_e32 v139, v131
	v_add_u32_e32 v148, s18, v143
	v_add_u32_e32 v149, s19, v143
	v_add_u32_e32 v150, 0, v4
	v_mov_b32_e32 v151, 0x4000
	s_mov_b32 s42, 0
	s_mov_b32 s20, 0
	s_barrier
	s_branch .LBB0_544

; #define STAGE(bufoff, gbase) STAGE_(bufoff, gbase, voffA)
; #define STAGEB(bufoff, gbase) STAGE_(bufoff, gbase, voffB)
; #define LDA(dst, b, h) do { _Pragma("unroll") for (int m = 0; m < 4; ++m) _Pragma("unroll") for (int k = 0; k < 2; ++k) dst[m][k] = *LDSP(const bf16x8, lds + SA(b, h) + aoff + m * 2048 + k * 1024); } while (0)
; #define LDB(dst, b, h) do { _Pragma("unroll") for (int n = 0; n < 2; ++n) _Pragma("unroll") for (int k = 0; k < 2; ++k) dst[n][k] = *LDSP(const bf16x8, lds + SB(b, h) + boff + n * 2048 + k * 1024); } while (0)
; #define MMA(ai, bj, AT, BT) do { __builtin_amdgcn_s_setprio(1); \
;     _Pragma("unroll") for (int m = 0; m < 4; ++m) _Pragma("unroll") for (int n = 0; n < 2; ++n) _Pragma("unroll") for (int k = 0; k < 2; ++k) \
;       acc[ai][bj][m][n] = __builtin_amdgcn_mfma_f32_16x16x32_bf16(BT[n][k], AT[m][k], acc[ai][bj][m][n], 0, 0, 0); \
;     __builtin_amdgcn_s_setprio(0); } while (0)
; #define WAIT_V(n) asm volatile("s_waitcnt vmcnt(" #n ")" ::: "memory")
; #define WAIT_L(n) asm volatile("s_waitcnt lgkmcnt(" #n ")" ::: "memory")
; #define BAR __builtin_amdgcn_s_barrier()
; #define SCHED __builtin_amdgcn_sched_barrier(0)
; #define WAIT_V(n) asm volatile("s_waitcnt vmcnt(" #n ")" ::: "memory")
; #define BAR do { __builtin_amdgcn_sched_barrier(0); __builtin_amdgcn_s_barrier(); asm volatile("" ::: "memory"); __builtin_amdgcn_sched_barrier(0); } while (0)
; template <bool SP2, bool ALIGN_EPI, bool DUAL, class Epi> DI void gemm_phase2(const bf16_t* A, const bf16_t* Bt, const bf16_t* A2, const bf16_t* Bt2, int M, int N, int K, const Epi& E, lds_t* lds) {
;     ...
;       const char* a1 = cA + (size_t)(t + 1) * kstep;
;       const char* a2 = last ? nA : cA + (size_t)(t + 2) * kstep; const char* b2 = last ? nB : cB + (size_t)(t + 2) * kstep;
;       const char* a3 = a2 + kstep; const char* b3 = b2 + kstep;
;       if constexpr (SP2) {
;         LDB(B0, 0, 0); LDB(B1, 0, 1); SCHED; LDA(At, 0, 0); STAGE(SA(1, 1), a1 + hstep);
;         WAIT_V(8); WAIT_L(0); BAR; MMA(0, 0, At, B0); MMA(0, 1, At, B1); BAR; SCHED;
;         LDA(At, 0, 1); STAGEB(SB(0, 0), b2); STAGEB(SB(0, 1), b2 + bstep); STAGE(SA(0, 0), a2);
;         WAIT_V(8); WAIT_L(0); BAR; MMA(1, 0, At, B0); MMA(1, 1, At, B1); BAR; SCHED;
.LBB0_551:
	ds_read_b128 v[152:155], v148
	ds_read_b128 v[156:159], v148 offset:1024
	ds_read_b128 v[160:163], v148 offset:2048
	ds_read_b128 v[164:167], v148 offset:3072
	ds_read_b128 v[168:171], v149
	ds_read_b128 v[172:175], v149 offset:1024
	ds_read_b128 v[176:179], v149 offset:2048
	ds_read_b128 v[180:183], v149 offset:3072
	s_add_u32 s35, s60, 0xfffc0080
	s_addc_u32 s37, s61, -1
	s_cmp_eq_u32 s34, 12
	s_cselect_b32 s65, s0, s37
	s_cselect_b32 s64, s1, s35
	s_cselect_b32 s63, s21, s33
	s_cselect_b32 s62, s22, s23
	s_add_i32 m0, s3, 0xc000
	ds_read_b128 v[184:187], v150
	ds_read_b128 v[188:191], v150 offset:1024
	ds_read_b128 v[192:195], v150 offset:2048
	ds_read_b128 v[196:199], v150 offset:3072
	ds_read_b128 v[200:203], v150 offset:4096
	ds_read_b128 v[204:207], v150 offset:5120
	ds_read_b128 v[208:211], v150 offset:6144
	ds_read_b128 v[216:219], v150 offset:7168
	global_load_lds_dwordx4 v136, s[60:61]
	s_add_i32 m0, s3, 0xe000
	s_nop 0
	global_load_lds_dwordx4 v138, s[60:61]
	s_waitcnt vmcnt(8)
	s_waitcnt lgkmcnt(0)
	s_barrier
	s_setprio 1
	s_waitcnt lgkmcnt(0)
	v_mfma_f32_16x16x32_bf16 v[124:127], v[152:155], v[184:187], v[124:127]
	v_mfma_f32_16x16x32_bf16 v[120:123], v[160:163], v[184:187], v[120:123]
	v_mfma_f32_16x16x32_bf16 v[108:111], v[152:155], v[192:195], v[108:111]
	v_mfma_f32_16x16x32_bf16 v[104:107], v[160:163], v[192:195], v[104:107]
	v_mfma_f32_16x16x32_bf16 v[92:95], v[152:155], v[200:203], v[92:95]
	v_mfma_f32_16x16x32_bf16 v[88:91], v[160:163], v[200:203], v[88:91]
	v_mfma_f32_16x16x32_bf16 v[76:79], v[152:155], v[208:211], v[76:79]
	v_mfma_f32_16x16x32_bf16 v[72:75], v[160:163], v[208:211], v[72:75]
	v_mfma_f32_16x16x32_bf16 v[124:127], v[156:159], v[188:191], v[124:127]
	v_mfma_f32_16x16x32_bf16 v[120:123], v[164:167], v[188:191], v[120:123]
	v_mfma_f32_16x16x32_bf16 v[108:111], v[156:159], v[196:199], v[108:111]
	v_mfma_f32_16x16x32_bf16 v[104:107], v[164:167], v[196:199], v[104:107]
	v_mfma_f32_16x16x32_bf16 v[92:95], v[156:159], v[204:207], v[92:95]
	v_mfma_f32_16x16x32_bf16 v[88:91], v[164:167], v[204:207], v[88:91]
	v_mfma_f32_16x16x32_bf16 v[76:79], v[156:159], v[216:219], v[76:79]
	v_mfma_f32_16x16x32_bf16 v[72:75], v[164:167], v[216:219], v[72:75]
	s_setprio 0
	s_setprio 1
	v_mfma_f32_16x16x32_bf16 v[116:119], v[168:171], v[184:187], v[116:119]
	v_mfma_f32_16x16x32_bf16 v[112:115], v[176:179], v[184:187], v[112:115]
	v_mfma_f32_16x16x32_bf16 v[100:103], v[168:171], v[192:195], v[100:103]
	v_mfma_f32_16x16x32_bf16 v[96:99], v[176:179], v[192:195], v[96:99]
	v_mfma_f32_16x16x32_bf16 v[84:87], v[168:171], v[200:203], v[84:87]
	v_mfma_f32_16x16x32_bf16 v[80:83], v[176:179], v[200:203], v[80:83]
	v_mfma_f32_16x16x32_bf16 v[68:71], v[168:171], v[208:211], v[68:71]
	v_mfma_f32_16x16x32_bf16 v[64:67], v[176:179], v[208:211], v[64:67]
	v_mfma_f32_16x16x32_bf16 v[116:119], v[172:175], v[188:191], v[116:119]
	v_mfma_f32_16x16x32_bf16 v[112:115], v[180:183], v[188:191], v[112:115]
	v_mfma_f32_16x16x32_bf16 v[100:103], v[172:175], v[196:199], v[100:103]
	v_mfma_f32_16x16x32_bf16 v[96:99], v[180:183], v[196:199], v[96:99]
	v_mfma_f32_16x16x32_bf16 v[84:87], v[172:175], v[204:207], v[84:87]
	v_mfma_f32_16x16x32_bf16 v[80:83], v[180:183], v[204:207], v[80:83]
	v_mfma_f32_16x16x32_bf16 v[68:71], v[172:175], v[216:219], v[68:71]
	v_mfma_f32_16x16x32_bf16 v[64:67], v[180:183], v[216:219], v[64:67]
	s_setprio 0
	s_barrier
	s_add_i32 s35, s18, s2
	v_lshl_add_u64 v[140:141], s[62:63], 0, v[130:131]
	s_mov_b32 m0, s35
	ds_read_b128 v[184:187], v150 offset:16384
	ds_read_b128 v[188:191], v150 offset:17408
	ds_read_b128 v[192:195], v150 offset:18432
	ds_read_b128 v[196:199], v150 offset:19456
	ds_read_b128 v[200:203], v150 offset:20480
	ds_read_b128 v[204:207], v150 offset:21504
	ds_read_b128 v[208:211], v150 offset:22528
	ds_read_b128 v[216:219], v150 offset:23552
	global_load_lds_dwordx4 v[140:141], off
	s_add_i32 m0, s35, 0x2000
	s_add_u32 s66, s62, 0x10000
	v_lshl_add_u64 v[220:221], s[62:63], 0, v[134:135]
	s_addc_u32 s67, s63, 0
	s_add_i32 s35, s19, s2
	global_load_lds_dwordx4 v[220:221], off
	s_mov_b32 m0, s35
	v_lshl_add_u64 v[224:225], s[64:65], 0, v[132:133]
	global_load_lds_dwordx4 v130, s[66:67]
	s_add_i32 m0, s35, 0x2000
	s_nop 0
	global_load_lds_dwordx4 v134, s[66:67]
	v_lshl_add_u64 v[222:223], s[64:65], 0, v[128:129]
	s_mov_b32 m0, s3
	s_nop 0
	global_load_lds_dwordx4 v[222:223], off
	s_mov_b32 m0, s8
	s_nop 0
	global_load_lds_dwordx4 v[224:225], off
	s_waitcnt vmcnt(8)
	s_waitcnt lgkmcnt(0)
	s_barrier
; #define STAGE(bufoff, gbase) STAGE_(bufoff, gbase, voffA)
; #define LDA(dst, b, h) do { _Pragma("unroll") for (int m = 0; m < 4; ++m) _Pragma("unroll") for (int k = 0; k < 2; ++k) dst[m][k] = *LDSP(const bf16x8, lds + SA(b, h) + aoff + m * 2048 + k * 1024); } while (0)
; #define LDB(dst, b, h) do { _Pragma("unroll") for (int n = 0; n < 2; ++n) _Pragma("unroll") for (int k = 0; k < 2; ++k) dst[n][k] = *LDSP(const bf16x8, lds + SB(b, h) + boff + n * 2048 + k * 1024); } while (0)
; #define MMA(ai, bj, AT, BT) do { __builtin_amdgcn_s_setprio(1); \
;     _Pragma("unroll") for (int m = 0; m < 4; ++m) _Pragma("unroll") for (int n = 0; n < 2; ++n) _Pragma("unroll") for (int k = 0; k < 2; ++k) \
;       acc[ai][bj][m][n] = __builtin_amdgcn_mfma_f32_16x16x32_bf16(BT[n][k], AT[m][k], acc[ai][bj][m][n], 0, 0, 0); \
;     __builtin_amdgcn_s_setprio(0); } while (0)
; #define WAIT_V(n) asm volatile("s_waitcnt vmcnt(" #n ")" ::: "memory")
; #define WAIT_L(n) asm volatile("s_waitcnt lgkmcnt(" #n ")" ::: "memory")
; #define BAR __builtin_amdgcn_s_barrier()
; #define SCHED __builtin_amdgcn_sched_barrier(0)
; #define WAIT_V(n) asm volatile("s_waitcnt vmcnt(" #n ")" ::: "memory")
; #define BAR do { __builtin_amdgcn_sched_barrier(0); __builtin_amdgcn_s_barrier(); asm volatile("" ::: "memory"); __builtin_amdgcn_sched_barrier(0); } while (0)
; template <bool SP2, bool ALIGN_EPI, bool DUAL, class Epi> DI void gemm_phase2(const bf16_t* A, const bf16_t* Bt, const bf16_t* A2, const bf16_t* Bt2, int M, int N, int K, const Epi& E, lds_t* lds) {
;     ...
;         WAIT_V(8); WAIT_L(0); BAR; MMA(1, 0, At, B0); MMA(1, 1, At, B1); BAR; SCHED;
;         LDB(B0, 1, 0); LDB(B1, 1, 1); SCHED; LDA(At, 1, 0); STAGE(SA(0, 1), a2 + hstep);
;         WAIT_V(8); WAIT_L(0); BAR; MMA(0, 0, At, B0); MMA(0, 1, At, B1); BAR; SCHED;
	s_setprio 1
	s_waitcnt lgkmcnt(0)
	v_mfma_f32_16x16x32_bf16 v[60:63], v[152:155], v[184:187], v[60:63]
	v_mfma_f32_16x16x32_bf16 v[56:59], v[160:163], v[184:187], v[56:59]
	v_mfma_f32_16x16x32_bf16 v[44:47], v[152:155], v[192:195], v[44:47]
	v_mfma_f32_16x16x32_bf16 v[40:43], v[160:163], v[192:195], v[40:43]
	v_mfma_f32_16x16x32_bf16 v[28:31], v[152:155], v[200:203], v[28:31]
	v_mfma_f32_16x16x32_bf16 v[24:27], v[160:163], v[200:203], v[24:27]
	v_mfma_f32_16x16x32_bf16 v[12:15], v[152:155], v[208:211], v[12:15]
	v_mfma_f32_16x16x32_bf16 v[8:11], v[160:163], v[208:211], v[8:11]
	v_mfma_f32_16x16x32_bf16 v[60:63], v[156:159], v[188:191], v[60:63]
	v_mfma_f32_16x16x32_bf16 v[56:59], v[164:167], v[188:191], v[56:59]
	v_mfma_f32_16x16x32_bf16 v[44:47], v[156:159], v[196:199], v[44:47]
	v_mfma_f32_16x16x32_bf16 v[40:43], v[164:167], v[196:199], v[40:43]
	v_mfma_f32_16x16x32_bf16 v[28:31], v[156:159], v[204:207], v[28:31]
	v_mfma_f32_16x16x32_bf16 v[24:27], v[164:167], v[204:207], v[24:27]
	v_mfma_f32_16x16x32_bf16 v[12:15], v[156:159], v[216:219], v[12:15]
	v_mfma_f32_16x16x32_bf16 v[8:11], v[164:167], v[216:219], v[8:11]
	s_setprio 0
	s_setprio 1
	v_mfma_f32_16x16x32_bf16 v[52:55], v[168:171], v[184:187], v[52:55]
	v_mfma_f32_16x16x32_bf16 v[48:51], v[176:179], v[184:187], v[48:51]
	v_mfma_f32_16x16x32_bf16 v[36:39], v[168:171], v[192:195], v[36:39]
	v_mfma_f32_16x16x32_bf16 v[32:35], v[176:179], v[192:195], v[32:35]
	v_mfma_f32_16x16x32_bf16 v[20:23], v[168:171], v[200:203], v[20:23]
	v_mfma_f32_16x16x32_bf16 v[16:19], v[176:179], v[200:203], v[16:19]
	v_mfma_f32_16x16x32_bf16 v[4:7], v[168:171], v[208:211], v[4:7]
	v_mfma_f32_16x16x32_bf16 v[0:3], v[176:179], v[208:211], v[0:3]
	v_mfma_f32_16x16x32_bf16 v[52:55], v[172:175], v[188:191], v[52:55]
	v_mfma_f32_16x16x32_bf16 v[48:51], v[180:183], v[188:191], v[48:51]
	v_mfma_f32_16x16x32_bf16 v[36:39], v[172:175], v[196:199], v[36:39]
	v_mfma_f32_16x16x32_bf16 v[32:35], v[180:183], v[196:199], v[32:35]
	v_mfma_f32_16x16x32_bf16 v[20:23], v[172:175], v[204:207], v[20:23]
	v_mfma_f32_16x16x32_bf16 v[16:19], v[180:183], v[204:207], v[16:19]
	v_mfma_f32_16x16x32_bf16 v[4:7], v[172:175], v[216:219], v[4:7]
	v_mfma_f32_16x16x32_bf16 v[0:3], v[180:183], v[216:219], v[0:3]
	s_setprio 0
	s_barrier
	s_add_i32 s35, 0, 0x18000
	s_add_i32 s37, 0, 0x1c000
	v_add_u32_e32 v164, s35, v143
	v_add_u32_e32 v180, s37, v143
	ds_read_b128 v[152:155], v164
	ds_read_b128 v[156:159], v164 offset:1024
	ds_read_b128 v[160:163], v164 offset:2048
	ds_read_b128 v[164:167], v164 offset:3072
	ds_read_b128 v[168:171], v180
	ds_read_b128 v[172:175], v180 offset:1024
	ds_read_b128 v[176:179], v180 offset:2048
	ds_read_b128 v[180:183], v180 offset:3072
	s_add_u32 s64, s64, 0x40000
	s_addc_u32 s65, s65, 0
	s_mov_b32 m0, s9
	ds_read_b128 v[184:187], v150 offset:32768
	ds_read_b128 v[188:191], v150 offset:33792
	ds_read_b128 v[192:195], v150 offset:34816
	ds_read_b128 v[196:199], v150 offset:35840
	ds_read_b128 v[200:203], v150 offset:36864
	ds_read_b128 v[204:207], v150 offset:37888
	ds_read_b128 v[208:211], v150 offset:38912
	ds_read_b128 v[216:219], v150 offset:39936
	global_load_lds_dwordx4 v128, s[64:65]
	s_mov_b32 m0, s10
	s_nop 0
	global_load_lds_dwordx4 v132, s[64:65]
	s_waitcnt vmcnt(8)
	s_waitcnt lgkmcnt(0)
	s_barrier
	s_setprio 1
	s_waitcnt lgkmcnt(0)
	v_mfma_f32_16x16x32_bf16 v[124:127], v[152:155], v[184:187], v[124:127]
	v_mfma_f32_16x16x32_bf16 v[120:123], v[160:163], v[184:187], v[120:123]
	v_mfma_f32_16x16x32_bf16 v[108:111], v[152:155], v[192:195], v[108:111]
	v_mfma_f32_16x16x32_bf16 v[104:107], v[160:163], v[192:195], v[104:107]
	v_mfma_f32_16x16x32_bf16 v[92:95], v[152:155], v[200:203], v[92:95]
	v_mfma_f32_16x16x32_bf16 v[88:91], v[160:163], v[200:203], v[88:91]
	v_mfma_f32_16x16x32_bf16 v[76:79], v[152:155], v[208:211], v[76:79]
	v_mfma_f32_16x16x32_bf16 v[72:75], v[160:163], v[208:211], v[72:75]
	v_mfma_f32_16x16x32_bf16 v[124:127], v[156:159], v[188:191], v[124:127]
	v_mfma_f32_16x16x32_bf16 v[120:123], v[164:167], v[188:191], v[120:123]
	v_mfma_f32_16x16x32_bf16 v[108:111], v[156:159], v[196:199], v[108:111]
	v_mfma_f32_16x16x32_bf16 v[104:107], v[164:167], v[196:199], v[104:107]
	v_mfma_f32_16x16x32_bf16 v[92:95], v[156:159], v[204:207], v[92:95]
	v_mfma_f32_16x16x32_bf16 v[88:91], v[164:167], v[204:207], v[88:91]
	v_mfma_f32_16x16x32_bf16 v[76:79], v[156:159], v[216:219], v[76:79]
	v_mfma_f32_16x16x32_bf16 v[72:75], v[164:167], v[216:219], v[72:75]
	s_setprio 0
	s_setprio 1
	v_mfma_f32_16x16x32_bf16 v[116:119], v[168:171], v[184:187], v[116:119]
	v_mfma_f32_16x16x32_bf16 v[112:115], v[176:179], v[184:187], v[112:115]
	v_mfma_f32_16x16x32_bf16 v[100:103], v[168:171], v[192:195], v[100:103]
	v_mfma_f32_16x16x32_bf16 v[96:99], v[176:179], v[192:195], v[96:99]
	v_mfma_f32_16x16x32_bf16 v[84:87], v[168:171], v[200:203], v[84:87]
	v_mfma_f32_16x16x32_bf16 v[80:83], v[176:179], v[200:203], v[80:83]
	v_mfma_f32_16x16x32_bf16 v[68:71], v[168:171], v[208:211], v[68:71]
	v_mfma_f32_16x16x32_bf16 v[64:67], v[176:179], v[208:211], v[64:67]
	v_mfma_f32_16x16x32_bf16 v[116:119], v[172:175], v[188:191], v[116:119]
	v_mfma_f32_16x16x32_bf16 v[112:115], v[180:183], v[188:191], v[112:115]
	v_mfma_f32_16x16x32_bf16 v[100:103], v[172:175], v[196:199], v[100:103]
	v_mfma_f32_16x16x32_bf16 v[96:99], v[180:183], v[196:199], v[96:99]
	v_mfma_f32_16x16x32_bf16 v[84:87], v[172:175], v[204:207], v[84:87]
	v_mfma_f32_16x16x32_bf16 v[80:83], v[180:183], v[204:207], v[80:83]
	v_mfma_f32_16x16x32_bf16 v[68:71], v[172:175], v[216:219], v[68:71]
	v_mfma_f32_16x16x32_bf16 v[64:67], v[180:183], v[216:219], v[64:67]
	s_setprio 0
	s_barrier
; #define STAGE(bufoff, gbase) STAGE_(bufoff, gbase, voffA)
; #define STAGEB(bufoff, gbase) STAGE_(bufoff, gbase, voffB)
; #define LDA(dst, b, h) do { _Pragma("unroll") for (int m = 0; m < 4; ++m) _Pragma("unroll") for (int k = 0; k < 2; ++k) dst[m][k] = *LDSP(const bf16x8, lds + SA(b, h) + aoff + m * 2048 + k * 1024); } while (0)
; #define MMA(ai, bj, AT, BT) do { __builtin_amdgcn_s_setprio(1); \
;     _Pragma("unroll") for (int m = 0; m < 4; ++m) _Pragma("unroll") for (int n = 0; n < 2; ++n) _Pragma("unroll") for (int k = 0; k < 2; ++k) \
;       acc[ai][bj][m][n] = __builtin_amdgcn_mfma_f32_16x16x32_bf16(BT[n][k], AT[m][k], acc[ai][bj][m][n], 0, 0, 0); \
;     __builtin_amdgcn_s_setprio(0); } while (0)
; #define WAIT_V(n) asm volatile("s_waitcnt vmcnt(" #n ")" ::: "memory")
; #define WAIT_L(n) asm volatile("s_waitcnt lgkmcnt(" #n ")" ::: "memory")
; #define BAR __builtin_amdgcn_s_barrier()
; #define SCHED __builtin_amdgcn_sched_barrier(0)
; #define WAIT_V(n) asm volatile("s_waitcnt vmcnt(" #n ")" ::: "memory")
; #define BAR do { __builtin_amdgcn_sched_barrier(0); __builtin_amdgcn_s_barrier(); asm volatile("" ::: "memory"); __builtin_amdgcn_sched_barrier(0); } while (0)
; template <bool SP2, bool ALIGN_EPI, bool DUAL, class Epi> DI void gemm_phase2(const bf16_t* A, const bf16_t* Bt, const bf16_t* A2, const bf16_t* Bt2, int M, int N, int K, const Epi& E, lds_t* lds) {
;     ...
;         LDA(At, 1, 1); STAGEB(SB(1, 0), b3); STAGEB(SB(1, 1), b3 + bstep); STAGE(SA(1, 0), a3);
;         WAIT_V(8); WAIT_L(0); BAR; MMA(1, 0, At, B0); MMA(1, 1, At, B1); BAR; SCHED;
	s_add_i32 s35, s35, s2
	v_lshl_add_u64 v[140:141], v[140:141], 0, s[30:31]
	s_mov_b32 m0, s35
	ds_read_b128 v[184:187], v150 offset:49152
	ds_read_b128 v[188:191], v150 offset:50176
	ds_read_b128 v[192:195], v150 offset:51200
	ds_read_b128 v[196:199], v150 offset:52224
	ds_read_b128 v[200:203], v150 offset:53248
	ds_read_b128 v[204:207], v150 offset:54272
	ds_read_b128 v[208:211], v150 offset:55296
	ds_read_b128 v[216:219], v150 offset:56320
	global_load_lds_dwordx4 v[140:141], off
	s_add_i32 m0, s35, 0x2000
	s_add_u32 s62, s62, 0x10080
	v_lshl_add_u64 v[140:141], v[220:221], 0, s[30:31]
	s_addc_u32 s63, s63, 0
	s_add_i32 s35, s37, s2
	global_load_lds_dwordx4 v[140:141], off
	s_mov_b32 m0, s35
	s_nop 0
	global_load_lds_dwordx4 v130, s[62:63]
	s_add_i32 m0, s35, 0x2000
	s_nop 0
	global_load_lds_dwordx4 v134, s[62:63]
	v_lshl_add_u64 v[140:141], v[222:223], 0, s[30:31]
	s_mov_b32 m0, s14
	s_nop 0
	global_load_lds_dwordx4 v[140:141], off
	v_lshl_add_u64 v[140:141], v[224:225], 0, s[30:31]
	s_mov_b32 m0, s15
	s_nop 0
	global_load_lds_dwordx4 v[140:141], off
	s_waitcnt vmcnt(8)
	s_waitcnt lgkmcnt(0)
	s_barrier
	s_setprio 1
	s_waitcnt lgkmcnt(0)
	v_mfma_f32_16x16x32_bf16 v[60:63], v[152:155], v[184:187], v[60:63]
	v_mfma_f32_16x16x32_bf16 v[56:59], v[160:163], v[184:187], v[56:59]
	v_mfma_f32_16x16x32_bf16 v[44:47], v[152:155], v[192:195], v[44:47]
	v_mfma_f32_16x16x32_bf16 v[40:43], v[160:163], v[192:195], v[40:43]
	v_mfma_f32_16x16x32_bf16 v[28:31], v[152:155], v[200:203], v[28:31]
	v_mfma_f32_16x16x32_bf16 v[24:27], v[160:163], v[200:203], v[24:27]
	v_mfma_f32_16x16x32_bf16 v[12:15], v[152:155], v[208:211], v[12:15]
	v_mfma_f32_16x16x32_bf16 v[8:11], v[160:163], v[208:211], v[8:11]
	v_mfma_f32_16x16x32_bf16 v[60:63], v[156:159], v[188:191], v[60:63]
	v_mfma_f32_16x16x32_bf16 v[56:59], v[164:167], v[188:191], v[56:59]
	v_mfma_f32_16x16x32_bf16 v[44:47], v[156:159], v[196:199], v[44:47]
	v_mfma_f32_16x16x32_bf16 v[40:43], v[164:167], v[196:199], v[40:43]
	v_mfma_f32_16x16x32_bf16 v[28:31], v[156:159], v[204:207], v[28:31]
	v_mfma_f32_16x16x32_bf16 v[24:27], v[164:167], v[204:207], v[24:27]
	v_mfma_f32_16x16x32_bf16 v[12:15], v[156:159], v[216:219], v[12:15]
	v_mfma_f32_16x16x32_bf16 v[8:11], v[164:167], v[216:219], v[8:11]
	s_setprio 0
	s_setprio 1
	v_mfma_f32_16x16x32_bf16 v[52:55], v[168:171], v[184:187], v[52:55]
	v_mfma_f32_16x16x32_bf16 v[48:51], v[176:179], v[184:187], v[48:51]
	v_mfma_f32_16x16x32_bf16 v[36:39], v[168:171], v[192:195], v[36:39]
	v_mfma_f32_16x16x32_bf16 v[32:35], v[176:179], v[192:195], v[32:35]
	v_mfma_f32_16x16x32_bf16 v[20:23], v[168:171], v[200:203], v[20:23]
	v_mfma_f32_16x16x32_bf16 v[16:19], v[176:179], v[200:203], v[16:19]
	v_mfma_f32_16x16x32_bf16 v[4:7], v[168:171], v[208:211], v[4:7]
	v_mfma_f32_16x16x32_bf16 v[0:3], v[176:179], v[208:211], v[0:3]
	v_mfma_f32_16x16x32_bf16 v[52:55], v[172:175], v[188:191], v[52:55]
	v_mfma_f32_16x16x32_bf16 v[48:51], v[180:183], v[188:191], v[48:51]
	v_mfma_f32_16x16x32_bf16 v[36:39], v[172:175], v[196:199], v[36:39]
	v_mfma_f32_16x16x32_bf16 v[32:35], v[180:183], v[196:199], v[32:35]
	v_mfma_f32_16x16x32_bf16 v[20:23], v[172:175], v[204:207], v[20:23]
	v_mfma_f32_16x16x32_bf16 v[16:19], v[180:183], v[204:207], v[16:19]
	v_mfma_f32_16x16x32_bf16 v[4:7], v[172:175], v[216:219], v[4:7]
	v_mfma_f32_16x16x32_bf16 v[0:3], v[180:183], v[216:219], v[0:3]
	s_setprio 0
	s_barrier
	s_add_i32 s34, s34, 2
	s_add_u32 s60, s60, 0x100
	s_addc_u32 s61, s61, 0
	s_add_u32 s23, s23, 0x100
	s_addc_u32 s33, s33, 0
	s_cmp_gt_u32 s34, 13
	s_cbranch_scc0 .LBB0_551
	s_and_b64 vcc, exec, s[38:39]
	s_cbranch_vccz .LBB0_554
	s_barrier

; #define STAGE(bufoff, gbase) STAGE_(bufoff, gbase, voffA)
; #define STAGEB(bufoff, gbase) STAGE_(bufoff, gbase, voffB)
; #define WAIT_V(n) asm volatile("s_waitcnt vmcnt(" #n ")" ::: "memory")
; #define BAR __builtin_amdgcn_s_barrier()
; #define WAIT_V(n) asm volatile("s_waitcnt vmcnt(" #n ")" ::: "memory")
; #define BAR do { __builtin_amdgcn_sched_barrier(0); __builtin_amdgcn_s_barrier(); asm volatile("" ::: "memory"); __builtin_amdgcn_sched_barrier(0); } while (0)
; template <bool SP2, bool ALIGN_EPI, bool DUAL, class Epi> DI void gemm_phase2(const bf16_t* A, const bf16_t* Bt, const bf16_t* A2, const bf16_t* Bt2, int M, int N, int K, const Epi& E, lds_t* lds) {
;     ...
;   for (int i = 0; i < 2; ++i) { int R, C; stage_rc(tid * 16 + i * 8192, R, C); const int Rb = (R >> 5) * 64 + perm32(R & 31);
;     voffA[i] = (unsigned)(R * K + C) * 2u; voffB[i] = (unsigned)(Rb * K + C) * 2u; }
;   const size_t kstep = (size_t)(BK * 2), hstep = (size_t)HALF * K * 2, tstep = 2 * hstep, bstep = (size_t)32 * K * 2;
;   const unsigned ldsw = (unsigned)wid * 1024u;
;   const int aoff = lds_byte(wr * 64 + fr, fq * 8), boff = lds_byte(wc * 32 + fr, fq * 8);
;     ...
;     STAGEB(SB(0, 0), cB); STAGEB(SB(0, 1), cB + bstep); STAGE(SA(0, 0), cA); STAGE(SA(0, 1), cA + hstep);
;     if (wr == 1) BAR;
;     WAIT_V(2); BAR;
;     STAGEB(SB(1, 0), cB + kstep); STAGE(SA(1, 0), cA + kstep); STAGEB(SB(1, 1), cB + bstep + kstep);
;     WAIT_V(6); BAR;
.LBB0_681:
	s_mov_b64 s[28:29], 0x80
	s_and_b32 s5, s0, 3
	s_add_i32 m0, s3, 0x18000
	v_lshl_add_u64 v[6:7], v[6:7], 0, s[28:29]
	s_lshl_b32 s11, s1, 6
	s_lshl_b32 s6, s1, 13
	s_lshl_b32 s7, s5, 12
	s_waitcnt vmcnt(2)
	s_barrier
	global_load_lds_dwordx4 v[6:7], off
	v_lshl_add_u64 v[4:5], v[4:5], 0, s[28:29]
	s_add_i32 m0, s3, 0x1a000
	s_add_i32 s14, s3, 0x8000
	s_add_i32 s15, s3, 0xa000
	global_load_lds_dwordx4 v[4:5], off
	v_lshl_add_u64 v[0:1], v[0:1], 0, s[28:29]
	s_mov_b32 m0, s14
	s_add_u32 s0, s54, 0x10080
	global_load_lds_dwordx4 v[0:1], off
	v_lshl_add_u64 v[0:1], v[2:3], 0, s[28:29]
	s_mov_b32 m0, s15
	s_addc_u32 s1, s55, 0
	global_load_lds_dwordx4 v[0:1], off
	s_add_i32 m0, s3, 0x1c000
	s_nop 0
	global_load_lds_dwordx4 v130, s[0:1]
	v_lshl_add_u64 v[0:1], s[0:1], 0, v[134:135]
	s_add_i32 m0, s3, 0x1e000
	s_cmpk_lt_u32 s4, 0x100
	global_load_lds_dwordx4 v[0:1], off
	v_bfe_u32 v0, v8, 4, 2
	v_lshlrev_b32_e32 v1, 3, v0
	v_lshlrev_b32_e32 v2, 4, v0
	v_lshl_or_b32 v144, s5, 6, v1
	v_cmp_eq_u32_e64 s[4:5], 0, v0
	v_lshlrev_b32_e32 v0, 14, v9
	v_and_b32_e32 v0, 0xffff8000, v0
	v_lshl_add_u32 v0, v10, 11, v0
	v_and_b32_e32 v1, 1, v9
	v_lshl_or_b32 v0, v1, 6, v0
	v_lshl_add_u32 v136, v11, 1, v0
	v_lshlrev_b32_e32 v0, 14, v12
	v_and_b32_e32 v142, 15, v8
	v_lshlrev_b32_e32 v3, 2, v8
	v_and_b32_e32 v0, 0xffff8000, v0
	v_lshl_or_b32 v2, v142, 6, v2
	v_and_b32_e32 v3, 32, v3
	s_waitcnt vmcnt(6)
	v_lshl_add_u32 v0, v13, 11, v0
	v_and_b32_e32 v1, 1, v12
	v_bitop3_b32 v4, v2, s6, v3 bitop3:0xde
	v_bitop3_b32 v143, v2, s7, v3 bitop3:0xde
	s_cselect_b64 s[36:37], -1, 0
	v_cmp_lt_u32_e64 s[6:7], 7, v142
	v_lshl_or_b32 v0, v1, 6, v0
	s_add_i32 s18, 0, 0x10000
	s_add_i32 s19, 0, 0x14000
	v_and_b32_e32 v145, 7, v8
	v_cndmask_b32_e64 v146, 0, 32, s[6:7]
	v_cndmask_b32_e64 v147, 32, 0, s[6:7]
	v_mov_b32_e32 v137, v131
	v_lshl_add_u32 v138, v14, 1, v0
	v_mov_b32_e32 v139, v131
	v_add_u32_e32 v148, s18, v143
	v_add_u32_e32 v149, s19, v143
	v_add_u32_e32 v150, 0, v4
	v_mov_b32_e32 v151, 0x4000
	s_mov_b32 s40, 0
	s_mov_b32 s20, 0
	s_barrier
	s_branch .LBB0_684

; #define STAGE(bufoff, gbase) STAGE_(bufoff, gbase, voffA)
; #define STAGEB(bufoff, gbase) STAGE_(bufoff, gbase, voffB)
; #define LDA(dst, b, h) do { _Pragma("unroll") for (int m = 0; m < 4; ++m) _Pragma("unroll") for (int k = 0; k < 2; ++k) dst[m][k] = *LDSP(const bf16x8, lds + SA(b, h) + aoff + m * 2048 + k * 1024); } while (0)
; #define LDB(dst, b, h) do { _Pragma("unroll") for (int n = 0; n < 2; ++n) _Pragma("unroll") for (int k = 0; k < 2; ++k) dst[n][k] = *LDSP(const bf16x8, lds + SB(b, h) + boff + n * 2048 + k * 1024); } while (0)
; #define MMA(ai, bj, AT, BT) do { __builtin_amdgcn_s_setprio(1); \
;     _Pragma("unroll") for (int m = 0; m < 4; ++m) _Pragma("unroll") for (int n = 0; n < 2; ++n) _Pragma("unroll") for (int k = 0; k < 2; ++k) \
;       acc[ai][bj][m][n] = __builtin_amdgcn_mfma_f32_16x16x32_bf16(BT[n][k], AT[m][k], acc[ai][bj][m][n], 0, 0, 0); \
;     __builtin_amdgcn_s_setprio(0); } while (0)
; #define WAIT_V(n) asm volatile("s_waitcnt vmcnt(" #n ")" ::: "memory")
; #define WAIT_L(n) asm volatile("s_waitcnt lgkmcnt(" #n ")" ::: "memory")
; #define BAR __builtin_amdgcn_s_barrier()
; #define SCHED __builtin_amdgcn_sched_barrier(0)
; #define WAIT_V(n) asm volatile("s_waitcnt vmcnt(" #n ")" ::: "memory")
; #define BAR do { __builtin_amdgcn_sched_barrier(0); __builtin_amdgcn_s_barrier(); asm volatile("" ::: "memory"); __builtin_amdgcn_sched_barrier(0); } while (0)
; template <bool SP2, bool ALIGN_EPI, bool DUAL, class Epi> DI void gemm_phase2(const bf16_t* A, const bf16_t* Bt, const bf16_t* A2, const bf16_t* Bt2, int M, int N, int K, const Epi& E, lds_t* lds) {
;     ...
;       const char* a1 = cA + (size_t)(t + 1) * kstep;
;       const char* a2 = last ? nA : cA + (size_t)(t + 2) * kstep; const char* b2 = last ? nB : cB + (size_t)(t + 2) * kstep;
;       const char* a3 = a2 + kstep; const char* b3 = b2 + kstep;
;       if constexpr (SP2) {
;         LDB(B0, 0, 0); LDB(B1, 0, 1); SCHED; LDA(At, 0, 0); STAGE(SA(1, 1), a1 + hstep);
;         WAIT_V(8); WAIT_L(0); BAR; MMA(0, 0, At, B0); MMA(0, 1, At, B1); BAR; SCHED;
;         LDA(At, 0, 1); STAGEB(SB(0, 0), b2); STAGEB(SB(0, 1), b2 + bstep); STAGE(SA(0, 0), a2);
;         WAIT_V(8); WAIT_L(0); BAR; MMA(1, 0, At, B0); MMA(1, 1, At, B1); BAR; SCHED;
.LBB0_691:
	ds_read_b128 v[152:155], v148
	ds_read_b128 v[156:159], v148 offset:1024
	ds_read_b128 v[160:163], v148 offset:2048
	ds_read_b128 v[164:167], v148 offset:3072
	ds_read_b128 v[168:171], v149
	ds_read_b128 v[172:175], v149 offset:1024
	ds_read_b128 v[176:179], v149 offset:2048
	ds_read_b128 v[180:183], v149 offset:3072
	s_add_u32 s34, s52, 0xfffc0080
	s_addc_u32 s35, s53, -1
	s_cmp_eq_u32 s33, 12
	s_cselect_b32 s57, s0, s35
	s_cselect_b32 s56, s1, s34
	s_cselect_b32 s55, s21, s31
	s_cselect_b32 s54, s22, s23
	s_add_i32 m0, s3, 0xc000
	ds_read_b128 v[184:187], v150
	ds_read_b128 v[188:191], v150 offset:1024
	ds_read_b128 v[192:195], v150 offset:2048
	ds_read_b128 v[196:199], v150 offset:3072
	ds_read_b128 v[200:203], v150 offset:4096
	ds_read_b128 v[204:207], v150 offset:5120
	ds_read_b128 v[208:211], v150 offset:6144
	ds_read_b128 v[216:219], v150 offset:7168
	global_load_lds_dwordx4 v136, s[52:53]
	s_add_i32 m0, s3, 0xe000
	s_nop 0
	global_load_lds_dwordx4 v138, s[52:53]
	s_waitcnt vmcnt(8)
	s_waitcnt lgkmcnt(0)
	s_barrier
	s_setprio 1
	s_waitcnt lgkmcnt(0)
	v_mfma_f32_16x16x32_bf16 v[124:127], v[152:155], v[184:187], v[124:127]
	v_mfma_f32_16x16x32_bf16 v[120:123], v[160:163], v[184:187], v[120:123]
	v_mfma_f32_16x16x32_bf16 v[108:111], v[152:155], v[192:195], v[108:111]
	v_mfma_f32_16x16x32_bf16 v[104:107], v[160:163], v[192:195], v[104:107]
	v_mfma_f32_16x16x32_bf16 v[92:95], v[152:155], v[200:203], v[92:95]
	v_mfma_f32_16x16x32_bf16 v[88:91], v[160:163], v[200:203], v[88:91]
	v_mfma_f32_16x16x32_bf16 v[76:79], v[152:155], v[208:211], v[76:79]
	v_mfma_f32_16x16x32_bf16 v[72:75], v[160:163], v[208:211], v[72:75]
	v_mfma_f32_16x16x32_bf16 v[124:127], v[156:159], v[188:191], v[124:127]
	v_mfma_f32_16x16x32_bf16 v[120:123], v[164:167], v[188:191], v[120:123]
	v_mfma_f32_16x16x32_bf16 v[108:111], v[156:159], v[196:199], v[108:111]
	v_mfma_f32_16x16x32_bf16 v[104:107], v[164:167], v[196:199], v[104:107]
	v_mfma_f32_16x16x32_bf16 v[92:95], v[156:159], v[204:207], v[92:95]
	v_mfma_f32_16x16x32_bf16 v[88:91], v[164:167], v[204:207], v[88:91]
	v_mfma_f32_16x16x32_bf16 v[76:79], v[156:159], v[216:219], v[76:79]
	v_mfma_f32_16x16x32_bf16 v[72:75], v[164:167], v[216:219], v[72:75]
	s_setprio 0
	s_setprio 1
	v_mfma_f32_16x16x32_bf16 v[116:119], v[168:171], v[184:187], v[116:119]
	v_mfma_f32_16x16x32_bf16 v[112:115], v[176:179], v[184:187], v[112:115]
	v_mfma_f32_16x16x32_bf16 v[100:103], v[168:171], v[192:195], v[100:103]
	v_mfma_f32_16x16x32_bf16 v[96:99], v[176:179], v[192:195], v[96:99]
	v_mfma_f32_16x16x32_bf16 v[84:87], v[168:171], v[200:203], v[84:87]
	v_mfma_f32_16x16x32_bf16 v[80:83], v[176:179], v[200:203], v[80:83]
	v_mfma_f32_16x16x32_bf16 v[68:71], v[168:171], v[208:211], v[68:71]
	v_mfma_f32_16x16x32_bf16 v[64:67], v[176:179], v[208:211], v[64:67]
	v_mfma_f32_16x16x32_bf16 v[116:119], v[172:175], v[188:191], v[116:119]
	v_mfma_f32_16x16x32_bf16 v[112:115], v[180:183], v[188:191], v[112:115]
	v_mfma_f32_16x16x32_bf16 v[100:103], v[172:175], v[196:199], v[100:103]
	v_mfma_f32_16x16x32_bf16 v[96:99], v[180:183], v[196:199], v[96:99]
	v_mfma_f32_16x16x32_bf16 v[84:87], v[172:175], v[204:207], v[84:87]
	v_mfma_f32_16x16x32_bf16 v[80:83], v[180:183], v[204:207], v[80:83]
	v_mfma_f32_16x16x32_bf16 v[68:71], v[172:175], v[216:219], v[68:71]
	v_mfma_f32_16x16x32_bf16 v[64:67], v[180:183], v[216:219], v[64:67]
	s_setprio 0
	s_barrier
	s_add_i32 s34, s18, s2
	v_lshl_add_u64 v[140:141], s[54:55], 0, v[130:131]
	s_mov_b32 m0, s34
	ds_read_b128 v[184:187], v150 offset:16384
	ds_read_b128 v[188:191], v150 offset:17408
	ds_read_b128 v[192:195], v150 offset:18432
	ds_read_b128 v[196:199], v150 offset:19456
	ds_read_b128 v[200:203], v150 offset:20480
	ds_read_b128 v[204:207], v150 offset:21504
	ds_read_b128 v[208:211], v150 offset:22528
	ds_read_b128 v[216:219], v150 offset:23552
	global_load_lds_dwordx4 v[140:141], off
	s_add_i32 m0, s34, 0x2000
	s_add_u32 s34, s54, 0x10000
	v_lshl_add_u64 v[220:221], s[54:55], 0, v[134:135]
	s_addc_u32 s35, s55, 0
	s_add_i32 s41, s19, s2
	global_load_lds_dwordx4 v[220:221], off
	s_mov_b32 m0, s41
	v_lshl_add_u64 v[224:225], s[56:57], 0, v[132:133]
	global_load_lds_dwordx4 v130, s[34:35]
	s_add_i32 m0, s41, 0x2000
	s_nop 0
	global_load_lds_dwordx4 v134, s[34:35]
	v_lshl_add_u64 v[222:223], s[56:57], 0, v[128:129]
	s_mov_b32 m0, s3
	s_nop 0
	global_load_lds_dwordx4 v[222:223], off
	s_mov_b32 m0, s8
	s_nop 0
	global_load_lds_dwordx4 v[224:225], off
	s_waitcnt vmcnt(8)
	s_waitcnt lgkmcnt(0)
	s_barrier
; #define STAGE(bufoff, gbase) STAGE_(bufoff, gbase, voffA)
; #define LDA(dst, b, h) do { _Pragma("unroll") for (int m = 0; m < 4; ++m) _Pragma("unroll") for (int k = 0; k < 2; ++k) dst[m][k] = *LDSP(const bf16x8, lds + SA(b, h) + aoff + m * 2048 + k * 1024); } while (0)
; #define LDB(dst, b, h) do { _Pragma("unroll") for (int n = 0; n < 2; ++n) _Pragma("unroll") for (int k = 0; k < 2; ++k) dst[n][k] = *LDSP(const bf16x8, lds + SB(b, h) + boff + n * 2048 + k * 1024); } while (0)
; #define MMA(ai, bj, AT, BT) do { __builtin_amdgcn_s_setprio(1); \
;     _Pragma("unroll") for (int m = 0; m < 4; ++m) _Pragma("unroll") for (int n = 0; n < 2; ++n) _Pragma("unroll") for (int k = 0; k < 2; ++k) \
;       acc[ai][bj][m][n] = __builtin_amdgcn_mfma_f32_16x16x32_bf16(BT[n][k], AT[m][k], acc[ai][bj][m][n], 0, 0, 0); \
;     __builtin_amdgcn_s_setprio(0); } while (0)
; #define WAIT_V(n) asm volatile("s_waitcnt vmcnt(" #n ")" ::: "memory")
; #define WAIT_L(n) asm volatile("s_waitcnt lgkmcnt(" #n ")" ::: "memory")
; #define BAR __builtin_amdgcn_s_barrier()
; #define SCHED __builtin_amdgcn_sched_barrier(0)
; #define WAIT_V(n) asm volatile("s_waitcnt vmcnt(" #n ")" ::: "memory")
; #define BAR do { __builtin_amdgcn_sched_barrier(0); __builtin_amdgcn_s_barrier(); asm volatile("" ::: "memory"); __builtin_amdgcn_sched_barrier(0); } while (0)
; template <bool SP2, bool ALIGN_EPI, bool DUAL, class Epi> DI void gemm_phase2(const bf16_t* A, const bf16_t* Bt, const bf16_t* A2, const bf16_t* Bt2, int M, int N, int K, const Epi& E, lds_t* lds) {
;     ...
;         WAIT_V(8); WAIT_L(0); BAR; MMA(1, 0, At, B0); MMA(1, 1, At, B1); BAR; SCHED;
;         LDB(B0, 1, 0); LDB(B1, 1, 1); SCHED; LDA(At, 1, 0); STAGE(SA(0, 1), a2 + hstep);
;         WAIT_V(8); WAIT_L(0); BAR; MMA(0, 0, At, B0); MMA(0, 1, At, B1); BAR; SCHED;
	s_setprio 1
	s_waitcnt lgkmcnt(0)
	v_mfma_f32_16x16x32_bf16 v[60:63], v[152:155], v[184:187], v[60:63]
	v_mfma_f32_16x16x32_bf16 v[56:59], v[160:163], v[184:187], v[56:59]
	v_mfma_f32_16x16x32_bf16 v[44:47], v[152:155], v[192:195], v[44:47]
	v_mfma_f32_16x16x32_bf16 v[40:43], v[160:163], v[192:195], v[40:43]
	v_mfma_f32_16x16x32_bf16 v[28:31], v[152:155], v[200:203], v[28:31]
	v_mfma_f32_16x16x32_bf16 v[24:27], v[160:163], v[200:203], v[24:27]
	v_mfma_f32_16x16x32_bf16 v[12:15], v[152:155], v[208:211], v[12:15]
	v_mfma_f32_16x16x32_bf16 v[8:11], v[160:163], v[208:211], v[8:11]
	v_mfma_f32_16x16x32_bf16 v[60:63], v[156:159], v[188:191], v[60:63]
	v_mfma_f32_16x16x32_bf16 v[56:59], v[164:167], v[188:191], v[56:59]
	v_mfma_f32_16x16x32_bf16 v[44:47], v[156:159], v[196:199], v[44:47]
	v_mfma_f32_16x16x32_bf16 v[40:43], v[164:167], v[196:199], v[40:43]
	v_mfma_f32_16x16x32_bf16 v[28:31], v[156:159], v[204:207], v[28:31]
	v_mfma_f32_16x16x32_bf16 v[24:27], v[164:167], v[204:207], v[24:27]
	v_mfma_f32_16x16x32_bf16 v[12:15], v[156:159], v[216:219], v[12:15]
	v_mfma_f32_16x16x32_bf16 v[8:11], v[164:167], v[216:219], v[8:11]
	s_setprio 0
	s_setprio 1
	v_mfma_f32_16x16x32_bf16 v[52:55], v[168:171], v[184:187], v[52:55]
	v_mfma_f32_16x16x32_bf16 v[48:51], v[176:179], v[184:187], v[48:51]
	v_mfma_f32_16x16x32_bf16 v[36:39], v[168:171], v[192:195], v[36:39]
	v_mfma_f32_16x16x32_bf16 v[32:35], v[176:179], v[192:195], v[32:35]
	v_mfma_f32_16x16x32_bf16 v[20:23], v[168:171], v[200:203], v[20:23]
	v_mfma_f32_16x16x32_bf16 v[16:19], v[176:179], v[200:203], v[16:19]
	v_mfma_f32_16x16x32_bf16 v[4:7], v[168:171], v[208:211], v[4:7]
	v_mfma_f32_16x16x32_bf16 v[0:3], v[176:179], v[208:211], v[0:3]
	v_mfma_f32_16x16x32_bf16 v[52:55], v[172:175], v[188:191], v[52:55]
	v_mfma_f32_16x16x32_bf16 v[48:51], v[180:183], v[188:191], v[48:51]
	v_mfma_f32_16x16x32_bf16 v[36:39], v[172:175], v[196:199], v[36:39]
	v_mfma_f32_16x16x32_bf16 v[32:35], v[180:183], v[196:199], v[32:35]
	v_mfma_f32_16x16x32_bf16 v[20:23], v[172:175], v[204:207], v[20:23]
	v_mfma_f32_16x16x32_bf16 v[16:19], v[180:183], v[204:207], v[16:19]
	v_mfma_f32_16x16x32_bf16 v[4:7], v[172:175], v[216:219], v[4:7]
	v_mfma_f32_16x16x32_bf16 v[0:3], v[180:183], v[216:219], v[0:3]
	s_setprio 0
	s_barrier
	s_add_i32 s41, 0, 0x18000
	s_add_i32 s49, 0, 0x1c000
	v_add_u32_e32 v164, s41, v143
	v_add_u32_e32 v180, s49, v143
	ds_read_b128 v[152:155], v164
	ds_read_b128 v[156:159], v164 offset:1024
	ds_read_b128 v[160:163], v164 offset:2048
	ds_read_b128 v[164:167], v164 offset:3072
	ds_read_b128 v[168:171], v180
	ds_read_b128 v[172:175], v180 offset:1024
	ds_read_b128 v[176:179], v180 offset:2048
	ds_read_b128 v[180:183], v180 offset:3072
	s_add_u32 s34, s56, 0x40000
	s_addc_u32 s35, s57, 0
	s_mov_b32 m0, s9
	ds_read_b128 v[184:187], v150 offset:32768
	ds_read_b128 v[188:191], v150 offset:33792
	ds_read_b128 v[192:195], v150 offset:34816
	ds_read_b128 v[196:199], v150 offset:35840
	ds_read_b128 v[200:203], v150 offset:36864
	ds_read_b128 v[204:207], v150 offset:37888
	ds_read_b128 v[208:211], v150 offset:38912
	ds_read_b128 v[216:219], v150 offset:39936
	global_load_lds_dwordx4 v128, s[34:35]
	s_mov_b32 m0, s10
	s_nop 0
	global_load_lds_dwordx4 v132, s[34:35]
	s_waitcnt vmcnt(8)
	s_waitcnt lgkmcnt(0)
	s_barrier
	s_setprio 1
	s_waitcnt lgkmcnt(0)
	v_mfma_f32_16x16x32_bf16 v[124:127], v[152:155], v[184:187], v[124:127]
	v_mfma_f32_16x16x32_bf16 v[120:123], v[160:163], v[184:187], v[120:123]
	v_mfma_f32_16x16x32_bf16 v[108:111], v[152:155], v[192:195], v[108:111]
	v_mfma_f32_16x16x32_bf16 v[104:107], v[160:163], v[192:195], v[104:107]
	v_mfma_f32_16x16x32_bf16 v[92:95], v[152:155], v[200:203], v[92:95]
	v_mfma_f32_16x16x32_bf16 v[88:91], v[160:163], v[200:203], v[88:91]
	v_mfma_f32_16x16x32_bf16 v[76:79], v[152:155], v[208:211], v[76:79]
	v_mfma_f32_16x16x32_bf16 v[72:75], v[160:163], v[208:211], v[72:75]
	v_mfma_f32_16x16x32_bf16 v[124:127], v[156:159], v[188:191], v[124:127]
	v_mfma_f32_16x16x32_bf16 v[120:123], v[164:167], v[188:191], v[120:123]
	v_mfma_f32_16x16x32_bf16 v[108:111], v[156:159], v[196:199], v[108:111]
	v_mfma_f32_16x16x32_bf16 v[104:107], v[164:167], v[196:199], v[104:107]
	v_mfma_f32_16x16x32_bf16 v[92:95], v[156:159], v[204:207], v[92:95]
	v_mfma_f32_16x16x32_bf16 v[88:91], v[164:167], v[204:207], v[88:91]
	v_mfma_f32_16x16x32_bf16 v[76:79], v[156:159], v[216:219], v[76:79]
	v_mfma_f32_16x16x32_bf16 v[72:75], v[164:167], v[216:219], v[72:75]
	s_setprio 0
	s_setprio 1
	v_mfma_f32_16x16x32_bf16 v[116:119], v[168:171], v[184:187], v[116:119]
	v_mfma_f32_16x16x32_bf16 v[112:115], v[176:179], v[184:187], v[112:115]
	v_mfma_f32_16x16x32_bf16 v[100:103], v[168:171], v[192:195], v[100:103]
	v_mfma_f32_16x16x32_bf16 v[96:99], v[176:179], v[192:195], v[96:99]
	v_mfma_f32_16x16x32_bf16 v[84:87], v[168:171], v[200:203], v[84:87]
	v_mfma_f32_16x16x32_bf16 v[80:83], v[176:179], v[200:203], v[80:83]
	v_mfma_f32_16x16x32_bf16 v[68:71], v[168:171], v[208:211], v[68:71]
	v_mfma_f32_16x16x32_bf16 v[64:67], v[176:179], v[208:211], v[64:67]
	v_mfma_f32_16x16x32_bf16 v[116:119], v[172:175], v[188:191], v[116:119]
	v_mfma_f32_16x16x32_bf16 v[112:115], v[180:183], v[188:191], v[112:115]
	v_mfma_f32_16x16x32_bf16 v[100:103], v[172:175], v[196:199], v[100:103]
	v_mfma_f32_16x16x32_bf16 v[96:99], v[180:183], v[196:199], v[96:99]
	v_mfma_f32_16x16x32_bf16 v[84:87], v[172:175], v[204:207], v[84:87]
	v_mfma_f32_16x16x32_bf16 v[80:83], v[180:183], v[204:207], v[80:83]
	v_mfma_f32_16x16x32_bf16 v[68:71], v[172:175], v[216:219], v[68:71]
	v_mfma_f32_16x16x32_bf16 v[64:67], v[180:183], v[216:219], v[64:67]
	s_setprio 0
	s_barrier
; #define STAGE(bufoff, gbase) STAGE_(bufoff, gbase, voffA)
; #define STAGEB(bufoff, gbase) STAGE_(bufoff, gbase, voffB)
; #define LDA(dst, b, h) do { _Pragma("unroll") for (int m = 0; m < 4; ++m) _Pragma("unroll") for (int k = 0; k < 2; ++k) dst[m][k] = *LDSP(const bf16x8, lds + SA(b, h) + aoff + m * 2048 + k * 1024); } while (0)
; #define MMA(ai, bj, AT, BT) do { __builtin_amdgcn_s_setprio(1); \
;     _Pragma("unroll") for (int m = 0; m < 4; ++m) _Pragma("unroll") for (int n = 0; n < 2; ++n) _Pragma("unroll") for (int k = 0; k < 2; ++k) \
;       acc[ai][bj][m][n] = __builtin_amdgcn_mfma_f32_16x16x32_bf16(BT[n][k], AT[m][k], acc[ai][bj][m][n], 0, 0, 0); \
;     __builtin_amdgcn_s_setprio(0); } while (0)
; #define WAIT_V(n) asm volatile("s_waitcnt vmcnt(" #n ")" ::: "memory")
; #define WAIT_L(n) asm volatile("s_waitcnt lgkmcnt(" #n ")" ::: "memory")
; #define BAR __builtin_amdgcn_s_barrier()
; #define SCHED __builtin_amdgcn_sched_barrier(0)
; #define WAIT_V(n) asm volatile("s_waitcnt vmcnt(" #n ")" ::: "memory")
; #define BAR do { __builtin_amdgcn_sched_barrier(0); __builtin_amdgcn_s_barrier(); asm volatile("" ::: "memory"); __builtin_amdgcn_sched_barrier(0); } while (0)
; template <bool SP2, bool ALIGN_EPI, bool DUAL, class Epi> DI void gemm_phase2(const bf16_t* A, const bf16_t* Bt, const bf16_t* A2, const bf16_t* Bt2, int M, int N, int K, const Epi& E, lds_t* lds) {
;     ...
;         LDA(At, 1, 1); STAGEB(SB(1, 0), b3); STAGEB(SB(1, 1), b3 + bstep); STAGE(SA(1, 0), a3);
;         WAIT_V(8); WAIT_L(0); BAR; MMA(1, 0, At, B0); MMA(1, 1, At, B1); BAR; SCHED;
	s_add_i32 s34, s41, s2
	v_lshl_add_u64 v[140:141], v[140:141], 0, s[28:29]
	s_mov_b32 m0, s34
	ds_read_b128 v[184:187], v150 offset:49152
	ds_read_b128 v[188:191], v150 offset:50176
	ds_read_b128 v[192:195], v150 offset:51200
	ds_read_b128 v[196:199], v150 offset:52224
	ds_read_b128 v[200:203], v150 offset:53248
	ds_read_b128 v[204:207], v150 offset:54272
	ds_read_b128 v[208:211], v150 offset:55296
	ds_read_b128 v[216:219], v150 offset:56320
	global_load_lds_dwordx4 v[140:141], off
	s_add_i32 m0, s34, 0x2000
	s_add_u32 s34, s54, 0x10080
	v_lshl_add_u64 v[140:141], v[220:221], 0, s[28:29]
	s_addc_u32 s35, s55, 0
	s_add_i32 s41, s49, s2
	global_load_lds_dwordx4 v[140:141], off
	s_mov_b32 m0, s41
	s_nop 0
	global_load_lds_dwordx4 v130, s[34:35]
	s_add_i32 m0, s41, 0x2000
	s_nop 0
	global_load_lds_dwordx4 v134, s[34:35]
	v_lshl_add_u64 v[140:141], v[222:223], 0, s[28:29]
	s_mov_b32 m0, s14
	s_nop 0
	global_load_lds_dwordx4 v[140:141], off
	v_lshl_add_u64 v[140:141], v[224:225], 0, s[28:29]
	s_mov_b32 m0, s15
	s_nop 0
	global_load_lds_dwordx4 v[140:141], off
	s_waitcnt vmcnt(8)
	s_waitcnt lgkmcnt(0)
	s_barrier
	s_setprio 1
	s_waitcnt lgkmcnt(0)
	v_mfma_f32_16x16x32_bf16 v[60:63], v[152:155], v[184:187], v[60:63]
	v_mfma_f32_16x16x32_bf16 v[56:59], v[160:163], v[184:187], v[56:59]
	v_mfma_f32_16x16x32_bf16 v[44:47], v[152:155], v[192:195], v[44:47]
	v_mfma_f32_16x16x32_bf16 v[40:43], v[160:163], v[192:195], v[40:43]
	v_mfma_f32_16x16x32_bf16 v[28:31], v[152:155], v[200:203], v[28:31]
	v_mfma_f32_16x16x32_bf16 v[24:27], v[160:163], v[200:203], v[24:27]
	v_mfma_f32_16x16x32_bf16 v[12:15], v[152:155], v[208:211], v[12:15]
	v_mfma_f32_16x16x32_bf16 v[8:11], v[160:163], v[208:211], v[8:11]
	v_mfma_f32_16x16x32_bf16 v[60:63], v[156:159], v[188:191], v[60:63]
	v_mfma_f32_16x16x32_bf16 v[56:59], v[164:167], v[188:191], v[56:59]
	v_mfma_f32_16x16x32_bf16 v[44:47], v[156:159], v[196:199], v[44:47]
	v_mfma_f32_16x16x32_bf16 v[40:43], v[164:167], v[196:199], v[40:43]
	v_mfma_f32_16x16x32_bf16 v[28:31], v[156:159], v[204:207], v[28:31]
	v_mfma_f32_16x16x32_bf16 v[24:27], v[164:167], v[204:207], v[24:27]
	v_mfma_f32_16x16x32_bf16 v[12:15], v[156:159], v[216:219], v[12:15]
	v_mfma_f32_16x16x32_bf16 v[8:11], v[164:167], v[216:219], v[8:11]
	s_setprio 0
	s_setprio 1
	v_mfma_f32_16x16x32_bf16 v[52:55], v[168:171], v[184:187], v[52:55]
	v_mfma_f32_16x16x32_bf16 v[48:51], v[176:179], v[184:187], v[48:51]
	v_mfma_f32_16x16x32_bf16 v[36:39], v[168:171], v[192:195], v[36:39]
	v_mfma_f32_16x16x32_bf16 v[32:35], v[176:179], v[192:195], v[32:35]
	v_mfma_f32_16x16x32_bf16 v[20:23], v[168:171], v[200:203], v[20:23]
	v_mfma_f32_16x16x32_bf16 v[16:19], v[176:179], v[200:203], v[16:19]
	v_mfma_f32_16x16x32_bf16 v[4:7], v[168:171], v[208:211], v[4:7]
	v_mfma_f32_16x16x32_bf16 v[0:3], v[176:179], v[208:211], v[0:3]
	v_mfma_f32_16x16x32_bf16 v[52:55], v[172:175], v[188:191], v[52:55]
	v_mfma_f32_16x16x32_bf16 v[48:51], v[180:183], v[188:191], v[48:51]
	v_mfma_f32_16x16x32_bf16 v[36:39], v[172:175], v[196:199], v[36:39]
	v_mfma_f32_16x16x32_bf16 v[32:35], v[180:183], v[196:199], v[32:35]
	v_mfma_f32_16x16x32_bf16 v[20:23], v[172:175], v[204:207], v[20:23]
	v_mfma_f32_16x16x32_bf16 v[16:19], v[180:183], v[204:207], v[16:19]
	v_mfma_f32_16x16x32_bf16 v[4:7], v[172:175], v[216:219], v[4:7]
	v_mfma_f32_16x16x32_bf16 v[0:3], v[180:183], v[216:219], v[0:3]
	s_setprio 0
	s_barrier
	s_add_i32 s33, s33, 2
	s_add_u32 s52, s52, 0x100
	s_addc_u32 s53, s53, 0
	s_add_u32 s23, s23, 0x100
	s_addc_u32 s31, s31, 0
	s_cmp_gt_u32 s33, 13
	s_cbranch_scc0 .LBB0_691
	s_and_b64 vcc, exec, s[36:37]
	s_cbranch_vccz .LBB0_694
	s_barrier

; #define STAGE(bufoff, gbase) STAGE_(bufoff, gbase, voffA)
; #define STAGEB(bufoff, gbase) STAGE_(bufoff, gbase, voffB)
; #define WAIT_V(n) asm volatile("s_waitcnt vmcnt(" #n ")" ::: "memory")
; #define BAR __builtin_amdgcn_s_barrier()
; #define WAIT_V(n) asm volatile("s_waitcnt vmcnt(" #n ")" ::: "memory")
; #define BAR do { __builtin_amdgcn_sched_barrier(0); __builtin_amdgcn_s_barrier(); asm volatile("" ::: "memory"); __builtin_amdgcn_sched_barrier(0); } while (0)
; template <bool SP2, bool ALIGN_EPI, bool DUAL, class Epi> DI void gemm_phase2(const bf16_t* A, const bf16_t* Bt, const bf16_t* A2, const bf16_t* Bt2, int M, int N, int K, const Epi& E, lds_t* lds) {
;     ...
;   for (int i = 0; i < 2; ++i) { int R, C; stage_rc(tid * 16 + i * 8192, R, C); const int Rb = (R >> 5) * 64 + perm32(R & 31);
;     voffA[i] = (unsigned)(R * K + C) * 2u; voffB[i] = (unsigned)(Rb * K + C) * 2u; }
;   const size_t kstep = (size_t)(BK * 2), hstep = (size_t)HALF * K * 2, tstep = 2 * hstep, bstep = (size_t)32 * K * 2;
;   const unsigned ldsw = (unsigned)wid * 1024u;
;   const int aoff = lds_byte(wr * 64 + fr, fq * 8), boff = lds_byte(wc * 32 + fr, fq * 8);
;     ...
;     STAGEB(SB(0, 0), cB); STAGEB(SB(0, 1), cB + bstep); STAGE(SA(0, 0), cA); STAGE(SA(0, 1), cA + hstep);
;     if (wr == 1) BAR;
;     WAIT_V(2); BAR;
;     STAGEB(SB(1, 0), cB + kstep); STAGE(SA(1, 0), cA + kstep); STAGEB(SB(1, 1), cB + bstep + kstep);
;     WAIT_V(6); BAR;
.LBB0_814:
	s_mov_b64 s[22:23], 0x80
	s_and_b32 s5, s0, 3
	s_add_i32 m0, s3, 0x18000
	v_lshl_add_u64 v[6:7], v[6:7], 0, s[22:23]
	s_lshl_b32 s11, s1, 6
	s_lshl_b32 s7, s1, 13
	s_lshl_b32 s18, s5, 12
	s_waitcnt vmcnt(2)
	s_barrier
	global_load_lds_dwordx4 v[6:7], off
	v_lshl_add_u64 v[4:5], v[4:5], 0, s[22:23]
	s_add_i32 m0, s3, 0x1a000
	s_add_i32 s14, s3, 0x8000
	s_add_i32 s15, s3, 0xa000
	global_load_lds_dwordx4 v[4:5], off
	v_lshl_add_u64 v[0:1], v[0:1], 0, s[22:23]
	s_mov_b32 m0, s14
	s_add_u32 s0, s48, 0x40080
	global_load_lds_dwordx4 v[0:1], off
	v_lshl_add_u64 v[0:1], v[2:3], 0, s[22:23]
	s_mov_b32 m0, s15
	s_addc_u32 s1, s49, 0
	global_load_lds_dwordx4 v[0:1], off
	s_add_i32 m0, s3, 0x1c000
	s_nop 0
	global_load_lds_dwordx4 v130, s[0:1]
	v_lshl_add_u64 v[0:1], s[0:1], 0, v[134:135]
	s_add_i32 m0, s3, 0x1e000
	s_cmpk_lt_u32 s4, 0x100
	global_load_lds_dwordx4 v[0:1], off
	v_bfe_u32 v0, v8, 4, 2
	v_lshlrev_b32_e32 v1, 3, v0
	v_lshlrev_b32_e32 v2, 4, v0
	v_lshl_or_b32 v144, s5, 6, v1
	v_cmp_eq_u32_e64 s[4:5], 0, v0
	v_lshlrev_b32_e32 v0, 16, v9
	v_and_b32_e32 v0, 0xfffe0000, v0
	v_lshl_add_u32 v0, v10, 13, v0
	v_and_b32_e32 v1, 1, v9
	v_lshl_or_b32 v0, v1, 6, v0
	v_lshl_add_u32 v136, v11, 1, v0
	v_lshlrev_b32_e32 v0, 16, v12
	v_and_b32_e32 v142, 15, v8
	v_lshlrev_b32_e32 v3, 2, v8
	v_and_b32_e32 v0, 0xfffe0000, v0
	v_lshl_or_b32 v2, v142, 6, v2
	v_and_b32_e32 v3, 32, v3
	s_waitcnt vmcnt(6)
	s_cselect_b64 s[28:29], -1, 0
	s_cmp_lg_u64 s[72:73], 0
	v_lshl_add_u32 v0, v13, 13, v0
	v_and_b32_e32 v1, 1, v12
	v_bitop3_b32 v4, v2, s7, v3 bitop3:0xde
	v_bitop3_b32 v143, v2, s18, v3 bitop3:0xde
	s_cselect_b64 s[30:31], -1, 0
	v_lshl_or_b32 v0, v1, 6, v0
	s_add_i32 s18, 0, 0x10000
	s_add_i32 s19, 0, 0x14000
	v_or_b32_e32 v145, 0x80, v142
	v_or_b32_e32 v146, 0x90, v142
	v_or_b32_e32 v147, 0xa0, v142
	v_or_b32_e32 v148, 0xb0, v142
	v_mov_b32_e32 v137, v131
	v_lshl_add_u32 v138, v14, 1, v0
	v_mov_b32_e32 v139, v131
	v_add_u32_e32 v149, s18, v143
	v_add_u32_e32 v150, s19, v143
	v_add_u32_e32 v151, 0, v4
	s_mov_b32 s38, 0
	s_mov_b32 s33, 0
	s_barrier
	s_branch .LBB0_817

; #define STAGE(bufoff, gbase) STAGE_(bufoff, gbase, voffA)
; #define STAGEB(bufoff, gbase) STAGE_(bufoff, gbase, voffB)
; #define LDA(dst, b, h) do { _Pragma("unroll") for (int m = 0; m < 4; ++m) _Pragma("unroll") for (int k = 0; k < 2; ++k) dst[m][k] = *LDSP(const bf16x8, lds + SA(b, h) + aoff + m * 2048 + k * 1024); } while (0)
; #define LDB(dst, b, h) do { _Pragma("unroll") for (int n = 0; n < 2; ++n) _Pragma("unroll") for (int k = 0; k < 2; ++k) dst[n][k] = *LDSP(const bf16x8, lds + SB(b, h) + boff + n * 2048 + k * 1024); } while (0)
; #define MMA(ai, bj, AT, BT) do { __builtin_amdgcn_s_setprio(1); \
;     _Pragma("unroll") for (int m = 0; m < 4; ++m) _Pragma("unroll") for (int n = 0; n < 2; ++n) _Pragma("unroll") for (int k = 0; k < 2; ++k) \
;       acc[ai][bj][m][n] = __builtin_amdgcn_mfma_f32_16x16x32_bf16(BT[n][k], AT[m][k], acc[ai][bj][m][n], 0, 0, 0); \
;     __builtin_amdgcn_s_setprio(0); } while (0)
; #define WAIT_V(n) asm volatile("s_waitcnt vmcnt(" #n ")" ::: "memory")
; #define WAIT_L(n) asm volatile("s_waitcnt lgkmcnt(" #n ")" ::: "memory")
; #define BAR __builtin_amdgcn_s_barrier()
; #define SCHED __builtin_amdgcn_sched_barrier(0)
; #define WAIT_V(n) asm volatile("s_waitcnt vmcnt(" #n ")" ::: "memory")
; #define BAR do { __builtin_amdgcn_sched_barrier(0); __builtin_amdgcn_s_barrier(); asm volatile("" ::: "memory"); __builtin_amdgcn_sched_barrier(0); } while (0)
; template <bool SP2, bool ALIGN_EPI, bool DUAL, class Epi> DI void gemm_phase2(const bf16_t* A, const bf16_t* Bt, const bf16_t* A2, const bf16_t* Bt2, int M, int N, int K, const Epi& E, lds_t* lds) {
;     ...
;       const char* a1 = cA + (size_t)(t + 1) * kstep;
;       const char* a2 = last ? nA : cA + (size_t)(t + 2) * kstep; const char* b2 = last ? nB : cB + (size_t)(t + 2) * kstep;
;       const char* a3 = a2 + kstep; const char* b3 = b2 + kstep;
;       if constexpr (SP2) {
;         LDB(B0, 0, 0); LDB(B1, 0, 1); SCHED; LDA(At, 0, 0); STAGE(SA(1, 1), a1 + hstep);
;         WAIT_V(8); WAIT_L(0); BAR; MMA(0, 0, At, B0); MMA(0, 1, At, B1); BAR; SCHED;
;         LDA(At, 0, 1); STAGEB(SB(0, 0), b2); STAGEB(SB(0, 1), b2 + bstep); STAGE(SA(0, 0), a2);
;         WAIT_V(8); WAIT_L(0); BAR; MMA(1, 0, At, B0); MMA(1, 1, At, B1); BAR; SCHED;
.LBB0_824:
	ds_read_b128 v[152:155], v149
	ds_read_b128 v[156:159], v149 offset:1024
	ds_read_b128 v[160:163], v149 offset:2048
	ds_read_b128 v[164:167], v149 offset:3072
	ds_read_b128 v[168:171], v150
	ds_read_b128 v[172:175], v150 offset:1024
	ds_read_b128 v[176:179], v150 offset:2048
	ds_read_b128 v[180:183], v150 offset:3072
	s_add_u32 s45, s46, 0xfff00080
	s_addc_u32 s48, s47, -1
	s_cmp_eq_u32 s39, 60
	s_cselect_b32 s51, s0, s48
	s_cselect_b32 s50, s1, s45
	s_cselect_b32 s49, s7, s35
	s_cselect_b32 s48, s27, s34
	s_add_i32 m0, s3, 0xc000
	ds_read_b128 v[184:187], v151
	ds_read_b128 v[188:191], v151 offset:1024
	ds_read_b128 v[192:195], v151 offset:2048
	ds_read_b128 v[196:199], v151 offset:3072
	ds_read_b128 v[200:203], v151 offset:4096
	ds_read_b128 v[204:207], v151 offset:5120
	ds_read_b128 v[208:211], v151 offset:6144
	ds_read_b128 v[216:219], v151 offset:7168
	global_load_lds_dwordx4 v136, s[46:47]
	s_add_i32 m0, s3, 0xe000
	s_nop 0
	global_load_lds_dwordx4 v138, s[46:47]
	s_waitcnt vmcnt(8)
	s_waitcnt lgkmcnt(0)
	s_barrier
	s_setprio 1
	s_waitcnt lgkmcnt(0)
	v_mfma_f32_16x16x32_bf16 v[124:127], v[152:155], v[184:187], v[124:127]
	v_mfma_f32_16x16x32_bf16 v[120:123], v[160:163], v[184:187], v[120:123]
	v_mfma_f32_16x16x32_bf16 v[108:111], v[152:155], v[192:195], v[108:111]
	v_mfma_f32_16x16x32_bf16 v[104:107], v[160:163], v[192:195], v[104:107]
	v_mfma_f32_16x16x32_bf16 v[92:95], v[152:155], v[200:203], v[92:95]
	v_mfma_f32_16x16x32_bf16 v[88:91], v[160:163], v[200:203], v[88:91]
	v_mfma_f32_16x16x32_bf16 v[76:79], v[152:155], v[208:211], v[76:79]
	v_mfma_f32_16x16x32_bf16 v[72:75], v[160:163], v[208:211], v[72:75]
	v_mfma_f32_16x16x32_bf16 v[124:127], v[156:159], v[188:191], v[124:127]
	v_mfma_f32_16x16x32_bf16 v[120:123], v[164:167], v[188:191], v[120:123]
	v_mfma_f32_16x16x32_bf16 v[108:111], v[156:159], v[196:199], v[108:111]
	v_mfma_f32_16x16x32_bf16 v[104:107], v[164:167], v[196:199], v[104:107]
	v_mfma_f32_16x16x32_bf16 v[92:95], v[156:159], v[204:207], v[92:95]
	v_mfma_f32_16x16x32_bf16 v[88:91], v[164:167], v[204:207], v[88:91]
	v_mfma_f32_16x16x32_bf16 v[76:79], v[156:159], v[216:219], v[76:79]
	v_mfma_f32_16x16x32_bf16 v[72:75], v[164:167], v[216:219], v[72:75]
	s_setprio 0
	s_setprio 1
	v_mfma_f32_16x16x32_bf16 v[116:119], v[168:171], v[184:187], v[116:119]
	v_mfma_f32_16x16x32_bf16 v[112:115], v[176:179], v[184:187], v[112:115]
	v_mfma_f32_16x16x32_bf16 v[100:103], v[168:171], v[192:195], v[100:103]
	v_mfma_f32_16x16x32_bf16 v[96:99], v[176:179], v[192:195], v[96:99]
	v_mfma_f32_16x16x32_bf16 v[84:87], v[168:171], v[200:203], v[84:87]
	v_mfma_f32_16x16x32_bf16 v[80:83], v[176:179], v[200:203], v[80:83]
	v_mfma_f32_16x16x32_bf16 v[68:71], v[168:171], v[208:211], v[68:71]
	v_mfma_f32_16x16x32_bf16 v[64:67], v[176:179], v[208:211], v[64:67]
	v_mfma_f32_16x16x32_bf16 v[116:119], v[172:175], v[188:191], v[116:119]
	v_mfma_f32_16x16x32_bf16 v[112:115], v[180:183], v[188:191], v[112:115]
	v_mfma_f32_16x16x32_bf16 v[100:103], v[172:175], v[196:199], v[100:103]
	v_mfma_f32_16x16x32_bf16 v[96:99], v[180:183], v[196:199], v[96:99]
	v_mfma_f32_16x16x32_bf16 v[84:87], v[172:175], v[204:207], v[84:87]
	v_mfma_f32_16x16x32_bf16 v[80:83], v[180:183], v[204:207], v[80:83]
	v_mfma_f32_16x16x32_bf16 v[68:71], v[172:175], v[216:219], v[68:71]
	v_mfma_f32_16x16x32_bf16 v[64:67], v[180:183], v[216:219], v[64:67]
	s_setprio 0
	s_barrier
	s_add_i32 s45, s18, s2
	v_lshl_add_u64 v[140:141], s[48:49], 0, v[130:131]
	s_mov_b32 m0, s45
	ds_read_b128 v[184:187], v151 offset:16384
	ds_read_b128 v[188:191], v151 offset:17408
	ds_read_b128 v[192:195], v151 offset:18432
	ds_read_b128 v[196:199], v151 offset:19456
	ds_read_b128 v[200:203], v151 offset:20480
	ds_read_b128 v[204:207], v151 offset:21504
	ds_read_b128 v[208:211], v151 offset:22528
	ds_read_b128 v[216:219], v151 offset:23552
	global_load_lds_dwordx4 v[140:141], off
	s_add_i32 m0, s45, 0x2000
	s_add_u32 s52, s48, 0x40000
	v_lshl_add_u64 v[220:221], s[48:49], 0, v[134:135]
	s_addc_u32 s53, s49, 0
	s_add_i32 s45, s19, s2
	global_load_lds_dwordx4 v[220:221], off
	s_mov_b32 m0, s45
	v_lshl_add_u64 v[224:225], s[50:51], 0, v[132:133]
	global_load_lds_dwordx4 v130, s[52:53]
	s_add_i32 m0, s45, 0x2000
	s_nop 0
	global_load_lds_dwordx4 v134, s[52:53]
	v_lshl_add_u64 v[222:223], s[50:51], 0, v[128:129]
	s_mov_b32 m0, s3
	s_nop 0
	global_load_lds_dwordx4 v[222:223], off
	s_mov_b32 m0, s8
	s_nop 0
	global_load_lds_dwordx4 v[224:225], off
	s_waitcnt vmcnt(8)
	s_waitcnt lgkmcnt(0)
	s_barrier
; #define STAGE(bufoff, gbase) STAGE_(bufoff, gbase, voffA)
; #define LDA(dst, b, h) do { _Pragma("unroll") for (int m = 0; m < 4; ++m) _Pragma("unroll") for (int k = 0; k < 2; ++k) dst[m][k] = *LDSP(const bf16x8, lds + SA(b, h) + aoff + m * 2048 + k * 1024); } while (0)
; #define LDB(dst, b, h) do { _Pragma("unroll") for (int n = 0; n < 2; ++n) _Pragma("unroll") for (int k = 0; k < 2; ++k) dst[n][k] = *LDSP(const bf16x8, lds + SB(b, h) + boff + n * 2048 + k * 1024); } while (0)
; #define MMA(ai, bj, AT, BT) do { __builtin_amdgcn_s_setprio(1); \
;     _Pragma("unroll") for (int m = 0; m < 4; ++m) _Pragma("unroll") for (int n = 0; n < 2; ++n) _Pragma("unroll") for (int k = 0; k < 2; ++k) \
;       acc[ai][bj][m][n] = __builtin_amdgcn_mfma_f32_16x16x32_bf16(BT[n][k], AT[m][k], acc[ai][bj][m][n], 0, 0, 0); \
;     __builtin_amdgcn_s_setprio(0); } while (0)
; #define WAIT_V(n) asm volatile("s_waitcnt vmcnt(" #n ")" ::: "memory")
; #define WAIT_L(n) asm volatile("s_waitcnt lgkmcnt(" #n ")" ::: "memory")
; #define BAR __builtin_amdgcn_s_barrier()
; #define SCHED __builtin_amdgcn_sched_barrier(0)
; #define WAIT_V(n) asm volatile("s_waitcnt vmcnt(" #n ")" ::: "memory")
; #define BAR do { __builtin_amdgcn_sched_barrier(0); __builtin_amdgcn_s_barrier(); asm volatile("" ::: "memory"); __builtin_amdgcn_sched_barrier(0); } while (0)
; template <bool SP2, bool ALIGN_EPI, bool DUAL, class Epi> DI void gemm_phase2(const bf16_t* A, const bf16_t* Bt, const bf16_t* A2, const bf16_t* Bt2, int M, int N, int K, const Epi& E, lds_t* lds) {
;     ...
;         WAIT_V(8); WAIT_L(0); BAR; MMA(1, 0, At, B0); MMA(1, 1, At, B1); BAR; SCHED;
;         LDB(B0, 1, 0); LDB(B1, 1, 1); SCHED; LDA(At, 1, 0); STAGE(SA(0, 1), a2 + hstep);
;         WAIT_V(8); WAIT_L(0); BAR; MMA(0, 0, At, B0); MMA(0, 1, At, B1); BAR; SCHED;
	s_setprio 1
	s_waitcnt lgkmcnt(0)
	v_mfma_f32_16x16x32_bf16 v[60:63], v[152:155], v[184:187], v[60:63]
	v_mfma_f32_16x16x32_bf16 v[56:59], v[160:163], v[184:187], v[56:59]
	v_mfma_f32_16x16x32_bf16 v[44:47], v[152:155], v[192:195], v[44:47]
	v_mfma_f32_16x16x32_bf16 v[40:43], v[160:163], v[192:195], v[40:43]
	v_mfma_f32_16x16x32_bf16 v[28:31], v[152:155], v[200:203], v[28:31]
	v_mfma_f32_16x16x32_bf16 v[24:27], v[160:163], v[200:203], v[24:27]
	v_mfma_f32_16x16x32_bf16 v[12:15], v[152:155], v[208:211], v[12:15]
	v_mfma_f32_16x16x32_bf16 v[8:11], v[160:163], v[208:211], v[8:11]
	v_mfma_f32_16x16x32_bf16 v[60:63], v[156:159], v[188:191], v[60:63]
	v_mfma_f32_16x16x32_bf16 v[56:59], v[164:167], v[188:191], v[56:59]
	v_mfma_f32_16x16x32_bf16 v[44:47], v[156:159], v[196:199], v[44:47]
	v_mfma_f32_16x16x32_bf16 v[40:43], v[164:167], v[196:199], v[40:43]
	v_mfma_f32_16x16x32_bf16 v[28:31], v[156:159], v[204:207], v[28:31]
	v_mfma_f32_16x16x32_bf16 v[24:27], v[164:167], v[204:207], v[24:27]
	v_mfma_f32_16x16x32_bf16 v[12:15], v[156:159], v[216:219], v[12:15]
	v_mfma_f32_16x16x32_bf16 v[8:11], v[164:167], v[216:219], v[8:11]
	s_setprio 0
	s_setprio 1
	v_mfma_f32_16x16x32_bf16 v[52:55], v[168:171], v[184:187], v[52:55]
	v_mfma_f32_16x16x32_bf16 v[48:51], v[176:179], v[184:187], v[48:51]
	v_mfma_f32_16x16x32_bf16 v[36:39], v[168:171], v[192:195], v[36:39]
	v_mfma_f32_16x16x32_bf16 v[32:35], v[176:179], v[192:195], v[32:35]
	v_mfma_f32_16x16x32_bf16 v[20:23], v[168:171], v[200:203], v[20:23]
	v_mfma_f32_16x16x32_bf16 v[16:19], v[176:179], v[200:203], v[16:19]
	v_mfma_f32_16x16x32_bf16 v[4:7], v[168:171], v[208:211], v[4:7]
	v_mfma_f32_16x16x32_bf16 v[0:3], v[176:179], v[208:211], v[0:3]
	v_mfma_f32_16x16x32_bf16 v[52:55], v[172:175], v[188:191], v[52:55]
	v_mfma_f32_16x16x32_bf16 v[48:51], v[180:183], v[188:191], v[48:51]
	v_mfma_f32_16x16x32_bf16 v[36:39], v[172:175], v[196:199], v[36:39]
	v_mfma_f32_16x16x32_bf16 v[32:35], v[180:183], v[196:199], v[32:35]
	v_mfma_f32_16x16x32_bf16 v[20:23], v[172:175], v[204:207], v[20:23]
	v_mfma_f32_16x16x32_bf16 v[16:19], v[180:183], v[204:207], v[16:19]
	v_mfma_f32_16x16x32_bf16 v[4:7], v[172:175], v[216:219], v[4:7]
	v_mfma_f32_16x16x32_bf16 v[0:3], v[180:183], v[216:219], v[0:3]
	s_setprio 0
	s_barrier
	s_add_i32 s45, 0, 0x18000
	s_add_i32 s52, 0, 0x1c000
	v_add_u32_e32 v164, s45, v143
	v_add_u32_e32 v180, s52, v143
	ds_read_b128 v[152:155], v164
	ds_read_b128 v[156:159], v164 offset:1024
	ds_read_b128 v[160:163], v164 offset:2048
	ds_read_b128 v[164:167], v164 offset:3072
	ds_read_b128 v[168:171], v180
	ds_read_b128 v[172:175], v180 offset:1024
	ds_read_b128 v[176:179], v180 offset:2048
	ds_read_b128 v[180:183], v180 offset:3072
	s_add_u32 s50, s50, 0x100000
	s_addc_u32 s51, s51, 0
	s_mov_b32 m0, s9
	ds_read_b128 v[184:187], v151 offset:32768
	ds_read_b128 v[188:191], v151 offset:33792
	ds_read_b128 v[192:195], v151 offset:34816
	ds_read_b128 v[196:199], v151 offset:35840
	ds_read_b128 v[200:203], v151 offset:36864
	ds_read_b128 v[204:207], v151 offset:37888
	ds_read_b128 v[208:211], v151 offset:38912
	ds_read_b128 v[216:219], v151 offset:39936
	global_load_lds_dwordx4 v128, s[50:51]
	s_mov_b32 m0, s10
	s_nop 0
	global_load_lds_dwordx4 v132, s[50:51]
	s_waitcnt vmcnt(8)
	s_waitcnt lgkmcnt(0)
	s_barrier
	s_setprio 1
	s_waitcnt lgkmcnt(0)
	v_mfma_f32_16x16x32_bf16 v[124:127], v[152:155], v[184:187], v[124:127]
	v_mfma_f32_16x16x32_bf16 v[120:123], v[160:163], v[184:187], v[120:123]
	v_mfma_f32_16x16x32_bf16 v[108:111], v[152:155], v[192:195], v[108:111]
	v_mfma_f32_16x16x32_bf16 v[104:107], v[160:163], v[192:195], v[104:107]
	v_mfma_f32_16x16x32_bf16 v[92:95], v[152:155], v[200:203], v[92:95]
	v_mfma_f32_16x16x32_bf16 v[88:91], v[160:163], v[200:203], v[88:91]
	v_mfma_f32_16x16x32_bf16 v[76:79], v[152:155], v[208:211], v[76:79]
	v_mfma_f32_16x16x32_bf16 v[72:75], v[160:163], v[208:211], v[72:75]
	v_mfma_f32_16x16x32_bf16 v[124:127], v[156:159], v[188:191], v[124:127]
	v_mfma_f32_16x16x32_bf16 v[120:123], v[164:167], v[188:191], v[120:123]
	v_mfma_f32_16x16x32_bf16 v[108:111], v[156:159], v[196:199], v[108:111]
	v_mfma_f32_16x16x32_bf16 v[104:107], v[164:167], v[196:199], v[104:107]
	v_mfma_f32_16x16x32_bf16 v[92:95], v[156:159], v[204:207], v[92:95]
	v_mfma_f32_16x16x32_bf16 v[88:91], v[164:167], v[204:207], v[88:91]
	v_mfma_f32_16x16x32_bf16 v[76:79], v[156:159], v[216:219], v[76:79]
	v_mfma_f32_16x16x32_bf16 v[72:75], v[164:167], v[216:219], v[72:75]
	s_setprio 0
	s_setprio 1
	v_mfma_f32_16x16x32_bf16 v[116:119], v[168:171], v[184:187], v[116:119]
	v_mfma_f32_16x16x32_bf16 v[112:115], v[176:179], v[184:187], v[112:115]
	v_mfma_f32_16x16x32_bf16 v[100:103], v[168:171], v[192:195], v[100:103]
	v_mfma_f32_16x16x32_bf16 v[96:99], v[176:179], v[192:195], v[96:99]
	v_mfma_f32_16x16x32_bf16 v[84:87], v[168:171], v[200:203], v[84:87]
	v_mfma_f32_16x16x32_bf16 v[80:83], v[176:179], v[200:203], v[80:83]
	v_mfma_f32_16x16x32_bf16 v[68:71], v[168:171], v[208:211], v[68:71]
	v_mfma_f32_16x16x32_bf16 v[64:67], v[176:179], v[208:211], v[64:67]
	v_mfma_f32_16x16x32_bf16 v[116:119], v[172:175], v[188:191], v[116:119]
	v_mfma_f32_16x16x32_bf16 v[112:115], v[180:183], v[188:191], v[112:115]
	v_mfma_f32_16x16x32_bf16 v[100:103], v[172:175], v[196:199], v[100:103]
	v_mfma_f32_16x16x32_bf16 v[96:99], v[180:183], v[196:199], v[96:99]
	v_mfma_f32_16x16x32_bf16 v[84:87], v[172:175], v[204:207], v[84:87]
	v_mfma_f32_16x16x32_bf16 v[80:83], v[180:183], v[204:207], v[80:83]
	v_mfma_f32_16x16x32_bf16 v[68:71], v[172:175], v[216:219], v[68:71]
	v_mfma_f32_16x16x32_bf16 v[64:67], v[180:183], v[216:219], v[64:67]
	s_setprio 0
	s_barrier
; #define STAGE(bufoff, gbase) STAGE_(bufoff, gbase, voffA)
; #define STAGEB(bufoff, gbase) STAGE_(bufoff, gbase, voffB)
; #define LDA(dst, b, h) do { _Pragma("unroll") for (int m = 0; m < 4; ++m) _Pragma("unroll") for (int k = 0; k < 2; ++k) dst[m][k] = *LDSP(const bf16x8, lds + SA(b, h) + aoff + m * 2048 + k * 1024); } while (0)
; #define MMA(ai, bj, AT, BT) do { __builtin_amdgcn_s_setprio(1); \
;     _Pragma("unroll") for (int m = 0; m < 4; ++m) _Pragma("unroll") for (int n = 0; n < 2; ++n) _Pragma("unroll") for (int k = 0; k < 2; ++k) \
;       acc[ai][bj][m][n] = __builtin_amdgcn_mfma_f32_16x16x32_bf16(BT[n][k], AT[m][k], acc[ai][bj][m][n], 0, 0, 0); \
;     __builtin_amdgcn_s_setprio(0); } while (0)
; #define WAIT_V(n) asm volatile("s_waitcnt vmcnt(" #n ")" ::: "memory")
; #define WAIT_L(n) asm volatile("s_waitcnt lgkmcnt(" #n ")" ::: "memory")
; #define BAR __builtin_amdgcn_s_barrier()
; #define SCHED __builtin_amdgcn_sched_barrier(0)
; #define WAIT_V(n) asm volatile("s_waitcnt vmcnt(" #n ")" ::: "memory")
; #define BAR do { __builtin_amdgcn_sched_barrier(0); __builtin_amdgcn_s_barrier(); asm volatile("" ::: "memory"); __builtin_amdgcn_sched_barrier(0); } while (0)
; template <bool SP2, bool ALIGN_EPI, bool DUAL, class Epi> DI void gemm_phase2(const bf16_t* A, const bf16_t* Bt, const bf16_t* A2, const bf16_t* Bt2, int M, int N, int K, const Epi& E, lds_t* lds) {
;     ...
;         LDA(At, 1, 1); STAGEB(SB(1, 0), b3); STAGEB(SB(1, 1), b3 + bstep); STAGE(SA(1, 0), a3);
;         WAIT_V(8); WAIT_L(0); BAR; MMA(1, 0, At, B0); MMA(1, 1, At, B1); BAR; SCHED;
	s_add_i32 s45, s45, s2
	v_lshl_add_u64 v[140:141], v[140:141], 0, s[22:23]
	s_mov_b32 m0, s45
	ds_read_b128 v[184:187], v151 offset:49152
	ds_read_b128 v[188:191], v151 offset:50176
	ds_read_b128 v[192:195], v151 offset:51200
	ds_read_b128 v[196:199], v151 offset:52224
	ds_read_b128 v[200:203], v151 offset:53248
	ds_read_b128 v[204:207], v151 offset:54272
	ds_read_b128 v[208:211], v151 offset:55296
	ds_read_b128 v[216:219], v151 offset:56320
	global_load_lds_dwordx4 v[140:141], off
	s_add_i32 m0, s45, 0x2000
	s_add_u32 s48, s48, 0x40080
	v_lshl_add_u64 v[140:141], v[220:221], 0, s[22:23]
	s_addc_u32 s49, s49, 0
	s_add_i32 s45, s52, s2
	global_load_lds_dwordx4 v[140:141], off
	s_mov_b32 m0, s45
	s_nop 0
	global_load_lds_dwordx4 v130, s[48:49]
	s_add_i32 m0, s45, 0x2000
	s_nop 0
	global_load_lds_dwordx4 v134, s[48:49]
	v_lshl_add_u64 v[140:141], v[222:223], 0, s[22:23]
	s_mov_b32 m0, s14
	s_nop 0
	global_load_lds_dwordx4 v[140:141], off
	v_lshl_add_u64 v[140:141], v[224:225], 0, s[22:23]
	s_mov_b32 m0, s15
	s_nop 0
	global_load_lds_dwordx4 v[140:141], off
	s_waitcnt vmcnt(8)
	s_waitcnt lgkmcnt(0)
	s_barrier
	s_setprio 1
	s_waitcnt lgkmcnt(0)
	v_mfma_f32_16x16x32_bf16 v[60:63], v[152:155], v[184:187], v[60:63]
	v_mfma_f32_16x16x32_bf16 v[56:59], v[160:163], v[184:187], v[56:59]
	v_mfma_f32_16x16x32_bf16 v[44:47], v[152:155], v[192:195], v[44:47]
	v_mfma_f32_16x16x32_bf16 v[40:43], v[160:163], v[192:195], v[40:43]
	v_mfma_f32_16x16x32_bf16 v[28:31], v[152:155], v[200:203], v[28:31]
	v_mfma_f32_16x16x32_bf16 v[24:27], v[160:163], v[200:203], v[24:27]
	v_mfma_f32_16x16x32_bf16 v[12:15], v[152:155], v[208:211], v[12:15]
	v_mfma_f32_16x16x32_bf16 v[8:11], v[160:163], v[208:211], v[8:11]
	v_mfma_f32_16x16x32_bf16 v[60:63], v[156:159], v[188:191], v[60:63]
	v_mfma_f32_16x16x32_bf16 v[56:59], v[164:167], v[188:191], v[56:59]
	v_mfma_f32_16x16x32_bf16 v[44:47], v[156:159], v[196:199], v[44:47]
	v_mfma_f32_16x16x32_bf16 v[40:43], v[164:167], v[196:199], v[40:43]
	v_mfma_f32_16x16x32_bf16 v[28:31], v[156:159], v[204:207], v[28:31]
	v_mfma_f32_16x16x32_bf16 v[24:27], v[164:167], v[204:207], v[24:27]
	v_mfma_f32_16x16x32_bf16 v[12:15], v[156:159], v[216:219], v[12:15]
	v_mfma_f32_16x16x32_bf16 v[8:11], v[164:167], v[216:219], v[8:11]
	s_setprio 0
	s_setprio 1
	v_mfma_f32_16x16x32_bf16 v[52:55], v[168:171], v[184:187], v[52:55]
	v_mfma_f32_16x16x32_bf16 v[48:51], v[176:179], v[184:187], v[48:51]
	v_mfma_f32_16x16x32_bf16 v[36:39], v[168:171], v[192:195], v[36:39]
	v_mfma_f32_16x16x32_bf16 v[32:35], v[176:179], v[192:195], v[32:35]
	v_mfma_f32_16x16x32_bf16 v[20:23], v[168:171], v[200:203], v[20:23]
	v_mfma_f32_16x16x32_bf16 v[16:19], v[176:179], v[200:203], v[16:19]
	v_mfma_f32_16x16x32_bf16 v[4:7], v[168:171], v[208:211], v[4:7]
	v_mfma_f32_16x16x32_bf16 v[0:3], v[176:179], v[208:211], v[0:3]
	v_mfma_f32_16x16x32_bf16 v[52:55], v[172:175], v[188:191], v[52:55]
	v_mfma_f32_16x16x32_bf16 v[48:51], v[180:183], v[188:191], v[48:51]
	v_mfma_f32_16x16x32_bf16 v[36:39], v[172:175], v[196:199], v[36:39]
	v_mfma_f32_16x16x32_bf16 v[32:35], v[180:183], v[196:199], v[32:35]
	v_mfma_f32_16x16x32_bf16 v[20:23], v[172:175], v[204:207], v[20:23]
	v_mfma_f32_16x16x32_bf16 v[16:19], v[180:183], v[204:207], v[16:19]
	v_mfma_f32_16x16x32_bf16 v[4:7], v[172:175], v[216:219], v[4:7]
	v_mfma_f32_16x16x32_bf16 v[0:3], v[180:183], v[216:219], v[0:3]
	s_setprio 0
	s_barrier
	s_add_i32 s39, s39, 2
	s_add_u32 s46, s46, 0x100
	s_addc_u32 s47, s47, 0
	s_add_u32 s34, s34, 0x100
	s_addc_u32 s35, s35, 0
	s_cmp_gt_u32 s39, 61
	s_cbranch_scc0 .LBB0_824
	s_and_b64 vcc, exec, s[28:29]
	s_cbranch_vccz .LBB0_827
	s_barrier

; #define STAGE(bufoff, gbase) STAGE_(bufoff, gbase, voffA)
; #define STAGEB(bufoff, gbase) STAGE_(bufoff, gbase, voffB)
; #define WAIT_V(n) asm volatile("s_waitcnt vmcnt(" #n ")" ::: "memory")
; #define BAR __builtin_amdgcn_s_barrier()
; #define WAIT_V(n) asm volatile("s_waitcnt vmcnt(" #n ")" ::: "memory")
; #define BAR do { __builtin_amdgcn_sched_barrier(0); __builtin_amdgcn_s_barrier(); asm volatile("" ::: "memory"); __builtin_amdgcn_sched_barrier(0); } while (0)
; template <bool SP2, bool ALIGN_EPI, bool DUAL, class Epi> DI void gemm_phase2(const bf16_t* A, const bf16_t* Bt, const bf16_t* A2, const bf16_t* Bt2, int M, int N, int K, const Epi& E, lds_t* lds) {
;     ...
;   for (int i = 0; i < 2; ++i) { int R, C; stage_rc(tid * 16 + i * 8192, R, C); const int Rb = (R >> 5) * 64 + perm32(R & 31);
;     voffA[i] = (unsigned)(R * K + C) * 2u; voffB[i] = (unsigned)(Rb * K + C) * 2u; }
;   const size_t kstep = (size_t)(BK * 2), hstep = (size_t)HALF * K * 2, tstep = 2 * hstep, bstep = (size_t)32 * K * 2;
;   const unsigned ldsw = (unsigned)wid * 1024u;
;   const int aoff = lds_byte(wr * 64 + fr, fq * 8), boff = lds_byte(wc * 32 + fr, fq * 8);
;     ...
;     STAGEB(SB(0, 0), cB); STAGEB(SB(0, 1), cB + bstep); STAGE(SA(0, 0), cA); STAGE(SA(0, 1), cA + hstep);
;     if (wr == 1) BAR;
;     WAIT_V(2); BAR;
;     STAGEB(SB(1, 0), cB + kstep); STAGE(SA(1, 0), cA + kstep); STAGEB(SB(1, 1), cB + bstep + kstep);
;     WAIT_V(6); BAR;
.LBB0_890:
	s_add_u32 s34, s74, 0x383800
	s_mov_b64 s[8:9], 0x80
	s_addc_u32 s35, s75, 0
	s_and_b32 s0, s0, 3
	s_add_i32 m0, s11, 0x18000
	v_lshl_add_u64 v[6:7], v[6:7], 0, s[8:9]
	s_lshl_b32 s3, s1, 13
	s_lshl_b32 s14, s0, 12
	s_waitcnt vmcnt(2)
	s_barrier
	global_load_lds_dwordx4 v[6:7], off
	v_lshl_add_u64 v[4:5], v[4:5], 0, s[8:9]
	s_add_i32 m0, s11, 0x1a000
	s_add_i32 s39, s11, 0x8000
	s_add_i32 s48, s11, 0xa000
	global_load_lds_dwordx4 v[4:5], off
	v_lshl_add_u64 v[0:1], v[0:1], 0, s[8:9]
	s_mov_b32 m0, s39
	s_add_u32 s4, s44, 0x40080
	global_load_lds_dwordx4 v[0:1], off
	v_lshl_add_u64 v[0:1], v[2:3], 0, s[8:9]
	s_mov_b32 m0, s48
	s_addc_u32 s5, s45, 0
	global_load_lds_dwordx4 v[0:1], off
	s_add_i32 m0, s11, 0x1c000
	s_nop 0
	global_load_lds_dwordx4 v130, s[4:5]
	v_lshl_add_u64 v[0:1], s[4:5], 0, v[134:135]
	s_add_i32 m0, s11, 0x1e000
	v_lshlrev_b32_e32 v3, 2, v8
	global_load_lds_dwordx4 v[0:1], off
	v_bfe_u32 v1, v8, 4, 2
	v_and_b32_e32 v0, 15, v8
	v_lshlrev_b32_e32 v2, 4, v1
	v_lshl_or_b32 v156, s1, 6, v0
	v_lshl_or_b32 v0, v0, 6, v2
	v_and_b32_e32 v3, 32, v3
	v_bitop3_b32 v4, v0, s3, v3 bitop3:0xde
	v_bitop3_b32 v157, v0, s14, v3 bitop3:0xde
	v_lshlrev_b32_e32 v0, 5, v1
	v_lshl_or_b32 v158, s0, 8, v0
	v_lshlrev_b32_e32 v0, 16, v9
	v_and_b32_e32 v0, 0xfffe0000, v0
	v_cmp_eq_u32_e64 s[4:5], 0, v1
	v_lshl_add_u32 v0, v10, 13, v0
	v_and_b32_e32 v1, 1, v9
	v_lshl_or_b32 v0, v1, 6, v0
	v_lshl_add_u32 v136, v11, 1, v0
	v_lshlrev_b32_e32 v0, 16, v12
	v_and_b32_e32 v0, 0xfffe0000, v0
	s_waitcnt vmcnt(6)
	s_cmpk_lt_u32 s2, 0x100
	v_lshl_add_u32 v0, v13, 13, v0
	v_and_b32_e32 v1, 1, v12
	s_cselect_b64 s[22:23], -1, 0
	v_lshl_or_b32 v0, v1, 6, v0
	s_add_i32 s49, 0, 0x10000
	s_add_i32 s50, 0, 0x14000
	v_lshl_or_b32 v159, s0, 7, v2
	v_mov_b32_e32 v137, v131
	v_lshl_add_u32 v138, v14, 1, v0
	v_mov_b32_e32 v139, v131
	v_add_u32_e32 v160, s49, v157
	v_add_u32_e32 v161, s50, v157
	v_add_u32_e32 v162, 0, v4
	v_mov_b32_e32 v163, 0x358637bd
	s_mov_b32 s51, 0x800000
	s_mov_b32 s26, 0
	s_mov_b32 s52, 0
	s_barrier
	s_branch .LBB0_893

; #define STAGE(bufoff, gbase) STAGE_(bufoff, gbase, voffA)
; #define STAGEB(bufoff, gbase) STAGE_(bufoff, gbase, voffB)
; #define LDA(dst, b, h) do { _Pragma("unroll") for (int m = 0; m < 4; ++m) _Pragma("unroll") for (int k = 0; k < 2; ++k) dst[m][k] = *LDSP(const bf16x8, lds + SA(b, h) + aoff + m * 2048 + k * 1024); } while (0)
; #define LDB(dst, b, h) do { _Pragma("unroll") for (int n = 0; n < 2; ++n) _Pragma("unroll") for (int k = 0; k < 2; ++k) dst[n][k] = *LDSP(const bf16x8, lds + SB(b, h) + boff + n * 2048 + k * 1024); } while (0)
; #define MMA(ai, bj, AT, BT) do { __builtin_amdgcn_s_setprio(1); \
;     _Pragma("unroll") for (int m = 0; m < 4; ++m) _Pragma("unroll") for (int n = 0; n < 2; ++n) _Pragma("unroll") for (int k = 0; k < 2; ++k) \
;       acc[ai][bj][m][n] = __builtin_amdgcn_mfma_f32_16x16x32_bf16(BT[n][k], AT[m][k], acc[ai][bj][m][n], 0, 0, 0); \
;     __builtin_amdgcn_s_setprio(0); } while (0)
; #define WAIT_V(n) asm volatile("s_waitcnt vmcnt(" #n ")" ::: "memory")
; #define WAIT_L(n) asm volatile("s_waitcnt lgkmcnt(" #n ")" ::: "memory")
; #define BAR __builtin_amdgcn_s_barrier()
; #define SCHED __builtin_amdgcn_sched_barrier(0)
; #define WAIT_V(n) asm volatile("s_waitcnt vmcnt(" #n ")" ::: "memory")
; #define BAR do { __builtin_amdgcn_sched_barrier(0); __builtin_amdgcn_s_barrier(); asm volatile("" ::: "memory"); __builtin_amdgcn_sched_barrier(0); } while (0)
; template <bool SP2, bool ALIGN_EPI, bool DUAL, class Epi> DI void gemm_phase2(const bf16_t* A, const bf16_t* Bt, const bf16_t* A2, const bf16_t* Bt2, int M, int N, int K, const Epi& E, lds_t* lds) {
;     ...
;       const char* a1 = cA + (size_t)(t + 1) * kstep;
;       const char* a2 = last ? nA : cA + (size_t)(t + 2) * kstep; const char* b2 = last ? nB : cB + (size_t)(t + 2) * kstep;
;       const char* a3 = a2 + kstep; const char* b3 = b2 + kstep;
;       if constexpr (SP2) {
;         LDB(B0, 0, 0); LDB(B1, 0, 1); SCHED; LDA(At, 0, 0); STAGE(SA(1, 1), a1 + hstep);
;         WAIT_V(8); WAIT_L(0); BAR; MMA(0, 0, At, B0); MMA(0, 1, At, B1); BAR; SCHED;
;         LDA(At, 0, 1); STAGEB(SB(0, 0), b2); STAGEB(SB(0, 1), b2 + bstep); STAGE(SA(0, 0), a2);
;         WAIT_V(8); WAIT_L(0); BAR; MMA(1, 0, At, B0); MMA(1, 1, At, B1); BAR; SCHED;
.LBB0_900:
	ds_read_b128 v[140:143], v160
	ds_read_b128 v[144:147], v160 offset:1024
	ds_read_b128 v[148:151], v160 offset:2048
	ds_read_b128 v[152:155], v160 offset:3072
	ds_read_b128 v[164:167], v161
	ds_read_b128 v[168:171], v161 offset:1024
	ds_read_b128 v[172:175], v161 offset:2048
	ds_read_b128 v[176:179], v161 offset:3072
	s_add_u32 s27, s42, 0xfff00080
	s_addc_u32 s41, s43, -1
	s_cmp_eq_u32 s21, 60
	s_cselect_b32 s47, s0, s41
	s_cselect_b32 s46, s1, s27
	s_cselect_b32 s45, s2, s15
	s_cselect_b32 s44, s3, s14
	s_add_i32 m0, s11, 0xc000
	ds_read_b128 v[180:183], v162
	ds_read_b128 v[184:187], v162 offset:1024
	ds_read_b128 v[188:191], v162 offset:2048
	ds_read_b128 v[192:195], v162 offset:3072
	ds_read_b128 v[196:199], v162 offset:4096
	ds_read_b128 v[200:203], v162 offset:5120
	ds_read_b128 v[204:207], v162 offset:6144
	ds_read_b128 v[208:211], v162 offset:7168
	global_load_lds_dwordx4 v136, s[42:43]
	s_add_i32 m0, s11, 0xe000
	s_nop 0
	global_load_lds_dwordx4 v138, s[42:43]
	s_waitcnt vmcnt(8)
	s_waitcnt lgkmcnt(0)
	s_barrier
	s_setprio 1
	s_waitcnt lgkmcnt(0)
	v_mfma_f32_16x16x32_bf16 v[124:127], v[140:143], v[180:183], v[124:127]
	v_mfma_f32_16x16x32_bf16 v[120:123], v[148:151], v[180:183], v[120:123]
	v_mfma_f32_16x16x32_bf16 v[108:111], v[140:143], v[188:191], v[108:111]
	v_mfma_f32_16x16x32_bf16 v[104:107], v[148:151], v[188:191], v[104:107]
	v_mfma_f32_16x16x32_bf16 v[92:95], v[140:143], v[196:199], v[92:95]
	v_mfma_f32_16x16x32_bf16 v[88:91], v[148:151], v[196:199], v[88:91]
	v_mfma_f32_16x16x32_bf16 v[76:79], v[140:143], v[204:207], v[76:79]
	v_mfma_f32_16x16x32_bf16 v[72:75], v[148:151], v[204:207], v[72:75]
	v_mfma_f32_16x16x32_bf16 v[124:127], v[144:147], v[184:187], v[124:127]
	v_mfma_f32_16x16x32_bf16 v[120:123], v[152:155], v[184:187], v[120:123]
	v_mfma_f32_16x16x32_bf16 v[108:111], v[144:147], v[192:195], v[108:111]
	v_mfma_f32_16x16x32_bf16 v[104:107], v[152:155], v[192:195], v[104:107]
	v_mfma_f32_16x16x32_bf16 v[92:95], v[144:147], v[200:203], v[92:95]
	v_mfma_f32_16x16x32_bf16 v[88:91], v[152:155], v[200:203], v[88:91]
	v_mfma_f32_16x16x32_bf16 v[76:79], v[144:147], v[208:211], v[76:79]
	v_mfma_f32_16x16x32_bf16 v[72:75], v[152:155], v[208:211], v[72:75]
	s_setprio 0
	s_setprio 1
	v_mfma_f32_16x16x32_bf16 v[116:119], v[164:167], v[180:183], v[116:119]
	v_mfma_f32_16x16x32_bf16 v[112:115], v[172:175], v[180:183], v[112:115]
	v_mfma_f32_16x16x32_bf16 v[100:103], v[164:167], v[188:191], v[100:103]
	v_mfma_f32_16x16x32_bf16 v[96:99], v[172:175], v[188:191], v[96:99]
	v_mfma_f32_16x16x32_bf16 v[84:87], v[164:167], v[196:199], v[84:87]
	v_mfma_f32_16x16x32_bf16 v[80:83], v[172:175], v[196:199], v[80:83]
	v_mfma_f32_16x16x32_bf16 v[68:71], v[164:167], v[204:207], v[68:71]
	v_mfma_f32_16x16x32_bf16 v[64:67], v[172:175], v[204:207], v[64:67]
	v_mfma_f32_16x16x32_bf16 v[116:119], v[168:171], v[184:187], v[116:119]
	v_mfma_f32_16x16x32_bf16 v[112:115], v[176:179], v[184:187], v[112:115]
	v_mfma_f32_16x16x32_bf16 v[100:103], v[168:171], v[192:195], v[100:103]
	v_mfma_f32_16x16x32_bf16 v[96:99], v[176:179], v[192:195], v[96:99]
	v_mfma_f32_16x16x32_bf16 v[84:87], v[168:171], v[200:203], v[84:87]
	v_mfma_f32_16x16x32_bf16 v[80:83], v[176:179], v[200:203], v[80:83]
	v_mfma_f32_16x16x32_bf16 v[68:71], v[168:171], v[208:211], v[68:71]
	v_mfma_f32_16x16x32_bf16 v[64:67], v[176:179], v[208:211], v[64:67]
	s_setprio 0
	s_barrier
	s_add_i32 s27, s49, s10
	v_lshl_add_u64 v[216:217], s[44:45], 0, v[130:131]
	s_mov_b32 m0, s27
	ds_read_b128 v[180:183], v162 offset:16384
	ds_read_b128 v[184:187], v162 offset:17408
	ds_read_b128 v[188:191], v162 offset:18432
	ds_read_b128 v[192:195], v162 offset:19456
	ds_read_b128 v[196:199], v162 offset:20480
	ds_read_b128 v[200:203], v162 offset:21504
	ds_read_b128 v[204:207], v162 offset:22528
	ds_read_b128 v[208:211], v162 offset:23552
	global_load_lds_dwordx4 v[216:217], off
	s_add_i32 m0, s27, 0x2000
	s_add_u32 s54, s44, 0x40000
	v_lshl_add_u64 v[218:219], s[44:45], 0, v[134:135]
	s_addc_u32 s55, s45, 0
	s_add_i32 s27, s50, s10
	global_load_lds_dwordx4 v[218:219], off
	s_mov_b32 m0, s27
	v_lshl_add_u64 v[222:223], s[46:47], 0, v[132:133]
	global_load_lds_dwordx4 v130, s[54:55]
	s_add_i32 m0, s27, 0x2000
	s_nop 0
	global_load_lds_dwordx4 v134, s[54:55]
	v_lshl_add_u64 v[220:221], s[46:47], 0, v[128:129]
	s_mov_b32 m0, s11
	s_nop 0
	global_load_lds_dwordx4 v[220:221], off
	s_mov_b32 m0, s18
	s_nop 0
	global_load_lds_dwordx4 v[222:223], off
	s_waitcnt vmcnt(8)
	s_waitcnt lgkmcnt(0)
	s_barrier
; #define STAGE(bufoff, gbase) STAGE_(bufoff, gbase, voffA)
; #define LDA(dst, b, h) do { _Pragma("unroll") for (int m = 0; m < 4; ++m) _Pragma("unroll") for (int k = 0; k < 2; ++k) dst[m][k] = *LDSP(const bf16x8, lds + SA(b, h) + aoff + m * 2048 + k * 1024); } while (0)
; #define LDB(dst, b, h) do { _Pragma("unroll") for (int n = 0; n < 2; ++n) _Pragma("unroll") for (int k = 0; k < 2; ++k) dst[n][k] = *LDSP(const bf16x8, lds + SB(b, h) + boff + n * 2048 + k * 1024); } while (0)
; #define MMA(ai, bj, AT, BT) do { __builtin_amdgcn_s_setprio(1); \
;     _Pragma("unroll") for (int m = 0; m < 4; ++m) _Pragma("unroll") for (int n = 0; n < 2; ++n) _Pragma("unroll") for (int k = 0; k < 2; ++k) \
;       acc[ai][bj][m][n] = __builtin_amdgcn_mfma_f32_16x16x32_bf16(BT[n][k], AT[m][k], acc[ai][bj][m][n], 0, 0, 0); \
;     __builtin_amdgcn_s_setprio(0); } while (0)
; #define WAIT_V(n) asm volatile("s_waitcnt vmcnt(" #n ")" ::: "memory")
; #define WAIT_L(n) asm volatile("s_waitcnt lgkmcnt(" #n ")" ::: "memory")
; #define BAR __builtin_amdgcn_s_barrier()
; #define SCHED __builtin_amdgcn_sched_barrier(0)
; #define WAIT_V(n) asm volatile("s_waitcnt vmcnt(" #n ")" ::: "memory")
; #define BAR do { __builtin_amdgcn_sched_barrier(0); __builtin_amdgcn_s_barrier(); asm volatile("" ::: "memory"); __builtin_amdgcn_sched_barrier(0); } while (0)
; template <bool SP2, bool ALIGN_EPI, bool DUAL, class Epi> DI void gemm_phase2(const bf16_t* A, const bf16_t* Bt, const bf16_t* A2, const bf16_t* Bt2, int M, int N, int K, const Epi& E, lds_t* lds) {
;     ...
;         WAIT_V(8); WAIT_L(0); BAR; MMA(1, 0, At, B0); MMA(1, 1, At, B1); BAR; SCHED;
;         LDB(B0, 1, 0); LDB(B1, 1, 1); SCHED; LDA(At, 1, 0); STAGE(SA(0, 1), a2 + hstep);
;         WAIT_V(8); WAIT_L(0); BAR; MMA(0, 0, At, B0); MMA(0, 1, At, B1); BAR; SCHED;
	s_setprio 1
	s_waitcnt lgkmcnt(0)
	v_mfma_f32_16x16x32_bf16 v[60:63], v[140:143], v[180:183], v[60:63]
	v_mfma_f32_16x16x32_bf16 v[56:59], v[148:151], v[180:183], v[56:59]
	v_mfma_f32_16x16x32_bf16 v[44:47], v[140:143], v[188:191], v[44:47]
	v_mfma_f32_16x16x32_bf16 v[40:43], v[148:151], v[188:191], v[40:43]
	v_mfma_f32_16x16x32_bf16 v[28:31], v[140:143], v[196:199], v[28:31]
	v_mfma_f32_16x16x32_bf16 v[24:27], v[148:151], v[196:199], v[24:27]
	v_mfma_f32_16x16x32_bf16 v[12:15], v[140:143], v[204:207], v[12:15]
	v_mfma_f32_16x16x32_bf16 v[8:11], v[148:151], v[204:207], v[8:11]
	v_mfma_f32_16x16x32_bf16 v[60:63], v[144:147], v[184:187], v[60:63]
	v_mfma_f32_16x16x32_bf16 v[56:59], v[152:155], v[184:187], v[56:59]
	v_mfma_f32_16x16x32_bf16 v[44:47], v[144:147], v[192:195], v[44:47]
	v_mfma_f32_16x16x32_bf16 v[40:43], v[152:155], v[192:195], v[40:43]
	v_mfma_f32_16x16x32_bf16 v[28:31], v[144:147], v[200:203], v[28:31]
	v_mfma_f32_16x16x32_bf16 v[24:27], v[152:155], v[200:203], v[24:27]
	v_mfma_f32_16x16x32_bf16 v[12:15], v[144:147], v[208:211], v[12:15]
	v_mfma_f32_16x16x32_bf16 v[8:11], v[152:155], v[208:211], v[8:11]
	s_setprio 0
	s_setprio 1
	v_mfma_f32_16x16x32_bf16 v[52:55], v[164:167], v[180:183], v[52:55]
	v_mfma_f32_16x16x32_bf16 v[48:51], v[172:175], v[180:183], v[48:51]
	v_mfma_f32_16x16x32_bf16 v[36:39], v[164:167], v[188:191], v[36:39]
	v_mfma_f32_16x16x32_bf16 v[32:35], v[172:175], v[188:191], v[32:35]
	v_mfma_f32_16x16x32_bf16 v[20:23], v[164:167], v[196:199], v[20:23]
	v_mfma_f32_16x16x32_bf16 v[16:19], v[172:175], v[196:199], v[16:19]
	v_mfma_f32_16x16x32_bf16 v[4:7], v[164:167], v[204:207], v[4:7]
	v_mfma_f32_16x16x32_bf16 v[0:3], v[172:175], v[204:207], v[0:3]
	v_mfma_f32_16x16x32_bf16 v[52:55], v[168:171], v[184:187], v[52:55]
	v_mfma_f32_16x16x32_bf16 v[48:51], v[176:179], v[184:187], v[48:51]
	v_mfma_f32_16x16x32_bf16 v[36:39], v[168:171], v[192:195], v[36:39]
	v_mfma_f32_16x16x32_bf16 v[32:35], v[176:179], v[192:195], v[32:35]
	v_mfma_f32_16x16x32_bf16 v[20:23], v[168:171], v[200:203], v[20:23]
	v_mfma_f32_16x16x32_bf16 v[16:19], v[176:179], v[200:203], v[16:19]
	v_mfma_f32_16x16x32_bf16 v[4:7], v[168:171], v[208:211], v[4:7]
	v_mfma_f32_16x16x32_bf16 v[0:3], v[176:179], v[208:211], v[0:3]
	s_setprio 0
	s_barrier
	s_add_i32 s27, 0, 0x18000
	s_add_i32 s41, 0, 0x1c000
	v_add_u32_e32 v152, s27, v157
	v_add_u32_e32 v176, s41, v157
	ds_read_b128 v[140:143], v152
	ds_read_b128 v[144:147], v152 offset:1024
	ds_read_b128 v[148:151], v152 offset:2048
	ds_read_b128 v[152:155], v152 offset:3072
	ds_read_b128 v[164:167], v176
	ds_read_b128 v[168:171], v176 offset:1024
	ds_read_b128 v[172:175], v176 offset:2048
	ds_read_b128 v[176:179], v176 offset:3072
	s_add_u32 s46, s46, 0x100000
	s_addc_u32 s47, s47, 0
	s_mov_b32 m0, s19
	ds_read_b128 v[180:183], v162 offset:32768
	ds_read_b128 v[184:187], v162 offset:33792
	ds_read_b128 v[188:191], v162 offset:34816
	ds_read_b128 v[192:195], v162 offset:35840
	ds_read_b128 v[196:199], v162 offset:36864
	ds_read_b128 v[200:203], v162 offset:37888
	ds_read_b128 v[204:207], v162 offset:38912
	ds_read_b128 v[208:211], v162 offset:39936
	global_load_lds_dwordx4 v128, s[46:47]
	s_mov_b32 m0, s33
	s_nop 0
	global_load_lds_dwordx4 v132, s[46:47]
	s_waitcnt vmcnt(8)
	s_waitcnt lgkmcnt(0)
	s_barrier
	s_setprio 1
	s_waitcnt lgkmcnt(0)
	v_mfma_f32_16x16x32_bf16 v[124:127], v[140:143], v[180:183], v[124:127]
	v_mfma_f32_16x16x32_bf16 v[120:123], v[148:151], v[180:183], v[120:123]
	v_mfma_f32_16x16x32_bf16 v[108:111], v[140:143], v[188:191], v[108:111]
	v_mfma_f32_16x16x32_bf16 v[104:107], v[148:151], v[188:191], v[104:107]
	v_mfma_f32_16x16x32_bf16 v[92:95], v[140:143], v[196:199], v[92:95]
	v_mfma_f32_16x16x32_bf16 v[88:91], v[148:151], v[196:199], v[88:91]
	v_mfma_f32_16x16x32_bf16 v[76:79], v[140:143], v[204:207], v[76:79]
	v_mfma_f32_16x16x32_bf16 v[72:75], v[148:151], v[204:207], v[72:75]
	v_mfma_f32_16x16x32_bf16 v[124:127], v[144:147], v[184:187], v[124:127]
	v_mfma_f32_16x16x32_bf16 v[120:123], v[152:155], v[184:187], v[120:123]
	v_mfma_f32_16x16x32_bf16 v[108:111], v[144:147], v[192:195], v[108:111]
	v_mfma_f32_16x16x32_bf16 v[104:107], v[152:155], v[192:195], v[104:107]
	v_mfma_f32_16x16x32_bf16 v[92:95], v[144:147], v[200:203], v[92:95]
	v_mfma_f32_16x16x32_bf16 v[88:91], v[152:155], v[200:203], v[88:91]
	v_mfma_f32_16x16x32_bf16 v[76:79], v[144:147], v[208:211], v[76:79]
	v_mfma_f32_16x16x32_bf16 v[72:75], v[152:155], v[208:211], v[72:75]
	s_setprio 0
	s_setprio 1
	v_mfma_f32_16x16x32_bf16 v[116:119], v[164:167], v[180:183], v[116:119]
	v_mfma_f32_16x16x32_bf16 v[112:115], v[172:175], v[180:183], v[112:115]
	v_mfma_f32_16x16x32_bf16 v[100:103], v[164:167], v[188:191], v[100:103]
	v_mfma_f32_16x16x32_bf16 v[96:99], v[172:175], v[188:191], v[96:99]
	v_mfma_f32_16x16x32_bf16 v[84:87], v[164:167], v[196:199], v[84:87]
	v_mfma_f32_16x16x32_bf16 v[80:83], v[172:175], v[196:199], v[80:83]
	v_mfma_f32_16x16x32_bf16 v[68:71], v[164:167], v[204:207], v[68:71]
	v_mfma_f32_16x16x32_bf16 v[64:67], v[172:175], v[204:207], v[64:67]
	v_mfma_f32_16x16x32_bf16 v[116:119], v[168:171], v[184:187], v[116:119]
	v_mfma_f32_16x16x32_bf16 v[112:115], v[176:179], v[184:187], v[112:115]
	v_mfma_f32_16x16x32_bf16 v[100:103], v[168:171], v[192:195], v[100:103]
	v_mfma_f32_16x16x32_bf16 v[96:99], v[176:179], v[192:195], v[96:99]
	v_mfma_f32_16x16x32_bf16 v[84:87], v[168:171], v[200:203], v[84:87]
	v_mfma_f32_16x16x32_bf16 v[80:83], v[176:179], v[200:203], v[80:83]
	v_mfma_f32_16x16x32_bf16 v[68:71], v[168:171], v[208:211], v[68:71]
	v_mfma_f32_16x16x32_bf16 v[64:67], v[176:179], v[208:211], v[64:67]
	s_setprio 0
	s_barrier
; #define STAGE(bufoff, gbase) STAGE_(bufoff, gbase, voffA)
; #define STAGEB(bufoff, gbase) STAGE_(bufoff, gbase, voffB)
; #define LDA(dst, b, h) do { _Pragma("unroll") for (int m = 0; m < 4; ++m) _Pragma("unroll") for (int k = 0; k < 2; ++k) dst[m][k] = *LDSP(const bf16x8, lds + SA(b, h) + aoff + m * 2048 + k * 1024); } while (0)
; #define MMA(ai, bj, AT, BT) do { __builtin_amdgcn_s_setprio(1); \
;     _Pragma("unroll") for (int m = 0; m < 4; ++m) _Pragma("unroll") for (int n = 0; n < 2; ++n) _Pragma("unroll") for (int k = 0; k < 2; ++k) \
;       acc[ai][bj][m][n] = __builtin_amdgcn_mfma_f32_16x16x32_bf16(BT[n][k], AT[m][k], acc[ai][bj][m][n], 0, 0, 0); \
;     __builtin_amdgcn_s_setprio(0); } while (0)
; #define WAIT_V(n) asm volatile("s_waitcnt vmcnt(" #n ")" ::: "memory")
; #define WAIT_L(n) asm volatile("s_waitcnt lgkmcnt(" #n ")" ::: "memory")
; #define BAR __builtin_amdgcn_s_barrier()
; #define SCHED __builtin_amdgcn_sched_barrier(0)
; #define WAIT_V(n) asm volatile("s_waitcnt vmcnt(" #n ")" ::: "memory")
; #define BAR do { __builtin_amdgcn_sched_barrier(0); __builtin_amdgcn_s_barrier(); asm volatile("" ::: "memory"); __builtin_amdgcn_sched_barrier(0); } while (0)
; template <bool SP2, bool ALIGN_EPI, bool DUAL, class Epi> DI void gemm_phase2(const bf16_t* A, const bf16_t* Bt, const bf16_t* A2, const bf16_t* Bt2, int M, int N, int K, const Epi& E, lds_t* lds) {
;     ...
;         LDA(At, 1, 1); STAGEB(SB(1, 0), b3); STAGEB(SB(1, 1), b3 + bstep); STAGE(SA(1, 0), a3);
;         WAIT_V(8); WAIT_L(0); BAR; MMA(1, 0, At, B0); MMA(1, 1, At, B1); BAR; SCHED;
	s_add_i32 s27, s27, s10
	v_lshl_add_u64 v[216:217], v[216:217], 0, s[8:9]
	s_mov_b32 m0, s27
	ds_read_b128 v[180:183], v162 offset:49152
	ds_read_b128 v[184:187], v162 offset:50176
	ds_read_b128 v[188:191], v162 offset:51200
	ds_read_b128 v[192:195], v162 offset:52224
	ds_read_b128 v[196:199], v162 offset:53248
	ds_read_b128 v[200:203], v162 offset:54272
	ds_read_b128 v[204:207], v162 offset:55296
	ds_read_b128 v[208:211], v162 offset:56320
	global_load_lds_dwordx4 v[216:217], off
	s_add_i32 m0, s27, 0x2000
	s_add_u32 s44, s44, 0x40080
	v_lshl_add_u64 v[216:217], v[218:219], 0, s[8:9]
	s_addc_u32 s45, s45, 0
	s_add_i32 s27, s41, s10
	global_load_lds_dwordx4 v[216:217], off
	s_mov_b32 m0, s27
	s_nop 0
	global_load_lds_dwordx4 v130, s[44:45]
	s_add_i32 m0, s27, 0x2000
	s_nop 0
	global_load_lds_dwordx4 v134, s[44:45]
	v_lshl_add_u64 v[216:217], v[220:221], 0, s[8:9]
	s_mov_b32 m0, s39
	s_nop 0
	global_load_lds_dwordx4 v[216:217], off
	v_lshl_add_u64 v[216:217], v[222:223], 0, s[8:9]
	s_mov_b32 m0, s48
	s_nop 0
	global_load_lds_dwordx4 v[216:217], off
	s_waitcnt vmcnt(8)
	s_waitcnt lgkmcnt(0)
	s_barrier
	s_setprio 1
	s_waitcnt lgkmcnt(0)
	v_mfma_f32_16x16x32_bf16 v[60:63], v[140:143], v[180:183], v[60:63]
	v_mfma_f32_16x16x32_bf16 v[56:59], v[148:151], v[180:183], v[56:59]
	v_mfma_f32_16x16x32_bf16 v[44:47], v[140:143], v[188:191], v[44:47]
	v_mfma_f32_16x16x32_bf16 v[40:43], v[148:151], v[188:191], v[40:43]
	v_mfma_f32_16x16x32_bf16 v[28:31], v[140:143], v[196:199], v[28:31]
	v_mfma_f32_16x16x32_bf16 v[24:27], v[148:151], v[196:199], v[24:27]
	v_mfma_f32_16x16x32_bf16 v[12:15], v[140:143], v[204:207], v[12:15]
	v_mfma_f32_16x16x32_bf16 v[8:11], v[148:151], v[204:207], v[8:11]
	v_mfma_f32_16x16x32_bf16 v[60:63], v[144:147], v[184:187], v[60:63]
	v_mfma_f32_16x16x32_bf16 v[56:59], v[152:155], v[184:187], v[56:59]
	v_mfma_f32_16x16x32_bf16 v[44:47], v[144:147], v[192:195], v[44:47]
	v_mfma_f32_16x16x32_bf16 v[40:43], v[152:155], v[192:195], v[40:43]
	v_mfma_f32_16x16x32_bf16 v[28:31], v[144:147], v[200:203], v[28:31]
	v_mfma_f32_16x16x32_bf16 v[24:27], v[152:155], v[200:203], v[24:27]
	v_mfma_f32_16x16x32_bf16 v[12:15], v[144:147], v[208:211], v[12:15]
	v_mfma_f32_16x16x32_bf16 v[8:11], v[152:155], v[208:211], v[8:11]
	s_setprio 0
	s_setprio 1
	v_mfma_f32_16x16x32_bf16 v[52:55], v[164:167], v[180:183], v[52:55]
	v_mfma_f32_16x16x32_bf16 v[48:51], v[172:175], v[180:183], v[48:51]
	v_mfma_f32_16x16x32_bf16 v[36:39], v[164:167], v[188:191], v[36:39]
	v_mfma_f32_16x16x32_bf16 v[32:35], v[172:175], v[188:191], v[32:35]
	v_mfma_f32_16x16x32_bf16 v[20:23], v[164:167], v[196:199], v[20:23]
	v_mfma_f32_16x16x32_bf16 v[16:19], v[172:175], v[196:199], v[16:19]
	v_mfma_f32_16x16x32_bf16 v[4:7], v[164:167], v[204:207], v[4:7]
	v_mfma_f32_16x16x32_bf16 v[0:3], v[172:175], v[204:207], v[0:3]
	v_mfma_f32_16x16x32_bf16 v[52:55], v[168:171], v[184:187], v[52:55]
	v_mfma_f32_16x16x32_bf16 v[48:51], v[176:179], v[184:187], v[48:51]
	v_mfma_f32_16x16x32_bf16 v[36:39], v[168:171], v[192:195], v[36:39]
	v_mfma_f32_16x16x32_bf16 v[32:35], v[176:179], v[192:195], v[32:35]
	v_mfma_f32_16x16x32_bf16 v[20:23], v[168:171], v[200:203], v[20:23]
	v_mfma_f32_16x16x32_bf16 v[16:19], v[176:179], v[200:203], v[16:19]
	v_mfma_f32_16x16x32_bf16 v[4:7], v[168:171], v[208:211], v[4:7]
	v_mfma_f32_16x16x32_bf16 v[0:3], v[176:179], v[208:211], v[0:3]
	s_setprio 0
	s_barrier
	s_add_i32 s21, s21, 2
	s_add_u32 s42, s42, 0x100
	s_addc_u32 s43, s43, 0
	s_add_u32 s14, s14, 0x100
	s_addc_u32 s15, s15, 0
	s_cmp_gt_u32 s21, 61
	s_cbranch_scc0 .LBB0_900
	s_and_b64 vcc, exec, s[22:23]
	s_cbranch_vccz .LBB0_903
	s_barrier
